# K-loop re-cut from 8 to 4 barrier-delimited phases per two K-tiles (32 MFMAs per interval), load-side order unchanged, every load segment drains vmcnt(8)+lgkmcnt(0) before its barrier; plus halves in
# speedup vs baseline: 1.0432x; 1.0235x over previous
; #define PG8_STAGE(bufoff, gbase, voff) do { _Pragma("unroll") for (int _i = 0; _i < 2; ++_i) \
;         __builtin_amdgcn_global_load_lds((const unsigned*)((const char*)(gbase) + (voff)[_i]), (PG8_LAS unsigned*)(lds + (bufoff) + ldsw + _i * 8192), 16, 0, 0); } while (0)
; #define PG8_LDA(dst, b, h) do { _Pragma("unroll") for (int m = 0; m < 4; ++m) _Pragma("unroll") for (int k = 0; k < 2; ++k) dst[m][k] = *(const PG8_LAS bf16x8*)(lds + PG8_SA(b, h) + aoff + m * 2048 + k * 1024); } while (0)
; #define PG8_LDB(dst, b, h) do { _Pragma("unroll") for (int n = 0; n < 2; ++n) _Pragma("unroll") for (int k = 0; k < 2; ++k) dst[n][k] = *(const PG8_LAS bf16x8*)(lds + PG8_SB(b, h) + boff + n * 2048 + k * 1024); } while (0)
; #define PG8_MMA(ai, bj, At, Bt) do { __builtin_amdgcn_s_setprio(1); _Pragma("unroll") for (int m = 0; m < 4; ++m) _Pragma("unroll") for (int n = 0; n < 2; ++n) _Pragma("unroll") for (int k = 0; k < 2; ++k) \
;         acc[ai][bj][m][n] = __builtin_amdgcn_mfma_f32_16x16x32_bf16(Bt[n][k], At[m][k], acc[ai][bj][m][n], 0, 0, 0); __builtin_amdgcn_s_setprio(0); } while (0)
; #define PG8_WAIT_L(n) asm volatile("s_waitcnt lgkmcnt(" #n ")" ::: "memory")
; #define PG8_BAR __builtin_amdgcn_s_barrier()
; #define PG8_SCHED __builtin_amdgcn_sched_barrier(0)
; template <class Epi, class Sched>
; __device__ __forceinline__ void gemm_phase(PG8_LAS unsigned char* lds, const Gemm g, const Sched& S, const Epi& E) {
;     ...
;             const bool last = (t == nt - 2);
;             const char* a1 = cA + (size_t)(t + 1) * kstep;
;             const char* a2 = last ? nA : cA + (size_t)(t + 2) * kstep; const char* b2 = last ? nB : cB + (size_t)(t + 2) * kstepB;
;             const char* a3 = a2 + kstep; const char* b3 = b2 + kstepB;
;             if (last && has_next) S.a_ready(nxt);
;             PG8_LDB(B0, 0, 0); PG8_SCHED; PG8_LDA(At, 0, 0); PG8_STAGE(PG8_SA(1, 1), a1 + hstep, voffA);
;             PG8_WAIT_L(8); PG8_BAR; PG8_WAIT_L(0); PG8_MMA(0, 0, At, B0); PG8_BAR; PG8_SCHED;
;             PG8_LDB(B1, 0, 1); PG8_STAGE(PG8_SB(0, 0), b2, voffB);
;             PG8_BAR; PG8_WAIT_L(0); PG8_MMA(0, 1, At, B1); PG8_BAR;
;             PG8_LDA(At, 0, 1); PG8_STAGE(PG8_SA(0, 0), a2, voffA);
;             PG8_BAR; PG8_WAIT_L(0); PG8_MMA(1, 0, At, B0); PG8_BAR; PG8_SCHED;
;             PG8_STAGE(PG8_SB(0, 1), b2 + hstepB, voffB);
.Lhalf_skip_y_0:
.LBB0_79:
	ds_read_b128 v[152:155], v149
	ds_read_b128 v[156:159], v149 offset:1024
	ds_read_b128 v[160:163], v149 offset:2048
	ds_read_b128 v[164:167], v149 offset:3072
	s_add_u32 s24, s22, 0xfff80080
	s_addc_u32 s25, s23, -1
	s_cmp_eq_u32 s61, 28
	s_cselect_b32 s27, s13, s25
	s_cselect_b32 s26, s57, s24
	s_cselect_b32 s25, s15, s60
	s_cselect_b32 s24, s58, s59
	v_lshl_add_u64 v[144:145], s[22:23], 0, v[136:137]
	s_add_i32 m0, s21, 0xc000
	ds_read_b128 v[168:171], v150
	ds_read_b128 v[172:175], v150 offset:1024
	ds_read_b128 v[176:179], v150 offset:2048
	ds_read_b128 v[180:183], v150 offset:3072
	ds_read_b128 v[184:187], v150 offset:4096
	ds_read_b128 v[188:191], v150 offset:5120
	ds_read_b128 v[192:195], v150 offset:6144
	ds_read_b128 v[196:199], v150 offset:7168
	global_load_lds_dwordx4 v[144:145], off
	v_lshl_add_u64 v[144:145], s[22:23], 0, v[138:139]
	s_add_i32 m0, s21, 0xe000
	s_nop 0
	global_load_lds_dwordx4 v[144:145], off
	s_add_i32 s62, s53, s38
	v_lshl_add_u64 v[144:145], s[24:25], 0, v[128:129]
	s_mov_b32 m0, s62
	ds_read_b128 v[200:203], v151
	ds_read_b128 v[204:207], v151 offset:1024
	ds_read_b128 v[208:211], v151 offset:2048
	ds_read_b128 v[212:215], v151 offset:3072
	s_waitcnt vmcnt(8)
	s_waitcnt lgkmcnt(0)
	s_barrier
	s_setprio 1
	v_mfma_f32_16x16x32_bf16 v[124:127], v[152:155], v[168:171], v[124:127]
	v_mfma_f32_16x16x32_bf16 v[120:123], v[160:163], v[168:171], v[120:123]
	v_mfma_f32_16x16x32_bf16 v[108:111], v[152:155], v[176:179], v[108:111]
	v_mfma_f32_16x16x32_bf16 v[104:107], v[160:163], v[176:179], v[104:107]
	v_mfma_f32_16x16x32_bf16 v[92:95], v[152:155], v[184:187], v[92:95]
	v_mfma_f32_16x16x32_bf16 v[88:91], v[160:163], v[184:187], v[88:91]
	v_mfma_f32_16x16x32_bf16 v[76:79], v[152:155], v[192:195], v[76:79]
	v_mfma_f32_16x16x32_bf16 v[72:75], v[160:163], v[192:195], v[72:75]
	v_mfma_f32_16x16x32_bf16 v[124:127], v[156:159], v[172:175], v[124:127]
	v_mfma_f32_16x16x32_bf16 v[120:123], v[164:167], v[172:175], v[120:123]
	v_mfma_f32_16x16x32_bf16 v[108:111], v[156:159], v[180:183], v[108:111]
	v_mfma_f32_16x16x32_bf16 v[104:107], v[164:167], v[180:183], v[104:107]
	v_mfma_f32_16x16x32_bf16 v[92:95], v[156:159], v[188:191], v[92:95]
	v_mfma_f32_16x16x32_bf16 v[88:91], v[164:167], v[188:191], v[88:91]
	v_mfma_f32_16x16x32_bf16 v[76:79], v[156:159], v[196:199], v[76:79]
	v_mfma_f32_16x16x32_bf16 v[72:75], v[164:167], v[196:199], v[72:75]
	v_mfma_f32_16x16x32_bf16 v[116:119], v[200:203], v[168:171], v[116:119]
	v_mfma_f32_16x16x32_bf16 v[112:115], v[208:211], v[168:171], v[112:115]
	v_mfma_f32_16x16x32_bf16 v[100:103], v[200:203], v[176:179], v[100:103]
	v_mfma_f32_16x16x32_bf16 v[96:99], v[208:211], v[176:179], v[96:99]
	v_mfma_f32_16x16x32_bf16 v[84:87], v[200:203], v[184:187], v[84:87]
	v_mfma_f32_16x16x32_bf16 v[80:83], v[208:211], v[184:187], v[80:83]
	v_mfma_f32_16x16x32_bf16 v[68:71], v[200:203], v[192:195], v[68:71]
	v_mfma_f32_16x16x32_bf16 v[64:67], v[208:211], v[192:195], v[64:67]
	v_mfma_f32_16x16x32_bf16 v[116:119], v[204:207], v[172:175], v[116:119]
	v_mfma_f32_16x16x32_bf16 v[112:115], v[212:215], v[172:175], v[112:115]
	v_mfma_f32_16x16x32_bf16 v[100:103], v[204:207], v[180:183], v[100:103]
	v_mfma_f32_16x16x32_bf16 v[96:99], v[212:215], v[180:183], v[96:99]
	v_mfma_f32_16x16x32_bf16 v[84:87], v[204:207], v[188:191], v[84:87]
	v_mfma_f32_16x16x32_bf16 v[80:83], v[212:215], v[188:191], v[80:83]
	v_mfma_f32_16x16x32_bf16 v[68:71], v[204:207], v[196:199], v[68:71]
	v_mfma_f32_16x16x32_bf16 v[64:67], v[212:215], v[196:199], v[64:67]
	s_setprio 0
	s_barrier
	global_load_lds_dwordx4 v[144:145], off
	v_lshl_add_u64 v[144:145], s[24:25], 0, v[130:131]
	s_add_i32 m0, s62, 0x2000
	s_nop 0
	global_load_lds_dwordx4 v[144:145], off
	s_mov_b32 m0, s21
	v_lshl_add_u64 v[144:145], s[26:27], 0, v[134:135]
	ds_read_b128 v[168:171], v150 offset:16384
	ds_read_b128 v[172:175], v150 offset:17408
	ds_read_b128 v[176:179], v150 offset:18432
	ds_read_b128 v[180:183], v150 offset:19456
	ds_read_b128 v[184:187], v150 offset:20480
	ds_read_b128 v[188:191], v150 offset:21504
	ds_read_b128 v[192:195], v150 offset:22528
	ds_read_b128 v[196:199], v150 offset:23552
	global_load_lds_dwordx4 v[144:145], off
	v_lshl_add_u64 v[216:217], s[26:27], 0, v[132:133]
	s_mov_b32 m0, s46
	s_nop 0
	global_load_lds_dwordx4 v[216:217], off
	s_add_u32 s62, s24, 0x4000
	s_addc_u32 s63, s25, 0
	s_add_i32 s64, s54, s38
	v_lshl_add_u64 v[250:251], s[62:63], 0, v[128:129]
	s_mov_b32 m0, s64
	s_nop 0
	global_load_lds_dwordx4 v[250:251], off
	v_lshl_add_u64 v[250:251], s[62:63], 0, v[130:131]
	s_add_i32 m0, s64, 0x2000
	s_nop 0
	global_load_lds_dwordx4 v[250:251], off
	s_waitcnt vmcnt(8)
	s_waitcnt lgkmcnt(0)
	s_barrier
; #define PG8_STAGE(bufoff, gbase, voff) do { _Pragma("unroll") for (int _i = 0; _i < 2; ++_i) \
;         __builtin_amdgcn_global_load_lds((const unsigned*)((const char*)(gbase) + (voff)[_i]), (PG8_LAS unsigned*)(lds + (bufoff) + ldsw + _i * 8192), 16, 0, 0); } while (0)
; #define PG8_LDA(dst, b, h) do { _Pragma("unroll") for (int m = 0; m < 4; ++m) _Pragma("unroll") for (int k = 0; k < 2; ++k) dst[m][k] = *(const PG8_LAS bf16x8*)(lds + PG8_SA(b, h) + aoff + m * 2048 + k * 1024); } while (0)
; #define PG8_LDB(dst, b, h) do { _Pragma("unroll") for (int n = 0; n < 2; ++n) _Pragma("unroll") for (int k = 0; k < 2; ++k) dst[n][k] = *(const PG8_LAS bf16x8*)(lds + PG8_SB(b, h) + boff + n * 2048 + k * 1024); } while (0)
; #define PG8_MMA(ai, bj, At, Bt) do { __builtin_amdgcn_s_setprio(1); _Pragma("unroll") for (int m = 0; m < 4; ++m) _Pragma("unroll") for (int n = 0; n < 2; ++n) _Pragma("unroll") for (int k = 0; k < 2; ++k) \
;         acc[ai][bj][m][n] = __builtin_amdgcn_mfma_f32_16x16x32_bf16(Bt[n][k], At[m][k], acc[ai][bj][m][n], 0, 0, 0); __builtin_amdgcn_s_setprio(0); } while (0)
; #define PG8_WAIT_V(n) asm volatile("s_waitcnt vmcnt(" #n ")" ::: "memory")
; #define PG8_WAIT_L(n) asm volatile("s_waitcnt lgkmcnt(" #n ")" ::: "memory")
; #define PG8_BAR __builtin_amdgcn_s_barrier()
; #define PG8_SCHED __builtin_amdgcn_sched_barrier(0)
; template <class Epi, class Sched>
; __device__ __forceinline__ void gemm_phase(PG8_LAS unsigned char* lds, const Gemm g, const Sched& S, const Epi& E) {
;     ...
;             PG8_BAR; PG8_WAIT_L(0); PG8_MMA(1, 0, At, B0); PG8_BAR; PG8_SCHED;
;             PG8_STAGE(PG8_SB(0, 1), b2 + hstepB, voffB);
;             PG8_WAIT_V(6); PG8_BAR; PG8_MMA(1, 1, At, B1); PG8_BAR;
;             PG8_LDB(B0, 1, 0); PG8_SCHED; PG8_LDA(At, 1, 0); PG8_STAGE(PG8_SA(0, 1), a2 + hstep, voffA);
;             PG8_WAIT_L(8); PG8_BAR; PG8_WAIT_L(0); PG8_MMA(0, 0, At, B0); PG8_BAR; PG8_SCHED;
;             PG8_LDB(B1, 1, 1); PG8_STAGE(PG8_SB(1, 0), b3, voffB);
;             PG8_BAR; PG8_WAIT_L(0); PG8_MMA(0, 1, At, B1); PG8_BAR;
	s_setprio 1
	v_mfma_f32_16x16x32_bf16 v[60:63], v[152:155], v[168:171], v[60:63]
	v_mfma_f32_16x16x32_bf16 v[56:59], v[160:163], v[168:171], v[56:59]
	v_mfma_f32_16x16x32_bf16 v[44:47], v[152:155], v[176:179], v[44:47]
	v_mfma_f32_16x16x32_bf16 v[40:43], v[160:163], v[176:179], v[40:43]
	v_mfma_f32_16x16x32_bf16 v[28:31], v[152:155], v[184:187], v[28:31]
	v_mfma_f32_16x16x32_bf16 v[24:27], v[160:163], v[184:187], v[24:27]
	v_mfma_f32_16x16x32_bf16 v[12:15], v[152:155], v[192:195], v[12:15]
	v_mfma_f32_16x16x32_bf16 v[8:11], v[160:163], v[192:195], v[8:11]
	v_mfma_f32_16x16x32_bf16 v[60:63], v[156:159], v[172:175], v[60:63]
	v_mfma_f32_16x16x32_bf16 v[56:59], v[164:167], v[172:175], v[56:59]
	v_mfma_f32_16x16x32_bf16 v[44:47], v[156:159], v[180:183], v[44:47]
	v_mfma_f32_16x16x32_bf16 v[40:43], v[164:167], v[180:183], v[40:43]
	v_mfma_f32_16x16x32_bf16 v[28:31], v[156:159], v[188:191], v[28:31]
	v_mfma_f32_16x16x32_bf16 v[24:27], v[164:167], v[188:191], v[24:27]
	v_mfma_f32_16x16x32_bf16 v[12:15], v[156:159], v[196:199], v[12:15]
	v_mfma_f32_16x16x32_bf16 v[8:11], v[164:167], v[196:199], v[8:11]
	v_mfma_f32_16x16x32_bf16 v[52:55], v[200:203], v[168:171], v[52:55]
	v_mfma_f32_16x16x32_bf16 v[48:51], v[208:211], v[168:171], v[48:51]
	v_mfma_f32_16x16x32_bf16 v[36:39], v[200:203], v[176:179], v[36:39]
	v_mfma_f32_16x16x32_bf16 v[32:35], v[208:211], v[176:179], v[32:35]
	v_mfma_f32_16x16x32_bf16 v[20:23], v[200:203], v[184:187], v[20:23]
	v_mfma_f32_16x16x32_bf16 v[16:19], v[208:211], v[184:187], v[16:19]
	v_mfma_f32_16x16x32_bf16 v[4:7], v[200:203], v[192:195], v[4:7]
	v_mfma_f32_16x16x32_bf16 v[0:3], v[208:211], v[192:195], v[0:3]
	v_mfma_f32_16x16x32_bf16 v[52:55], v[204:207], v[172:175], v[52:55]
	v_mfma_f32_16x16x32_bf16 v[48:51], v[212:215], v[172:175], v[48:51]
	v_mfma_f32_16x16x32_bf16 v[36:39], v[204:207], v[180:183], v[36:39]
	v_mfma_f32_16x16x32_bf16 v[32:35], v[212:215], v[180:183], v[32:35]
	v_mfma_f32_16x16x32_bf16 v[20:23], v[204:207], v[188:191], v[20:23]
	v_mfma_f32_16x16x32_bf16 v[16:19], v[212:215], v[188:191], v[16:19]
	v_mfma_f32_16x16x32_bf16 v[4:7], v[204:207], v[196:199], v[4:7]
	v_mfma_f32_16x16x32_bf16 v[0:3], v[212:215], v[196:199], v[0:3]
	s_setprio 0
	s_barrier
	s_add_i32 s62, 0, 0x18000
	v_add_u32_e32 v164, s62, v147
	ds_read_b128 v[152:155], v164
	ds_read_b128 v[156:159], v164 offset:1024
	ds_read_b128 v[160:163], v164 offset:2048
	ds_read_b128 v[164:167], v164 offset:3072
	s_add_u32 s26, s26, 0x80000
	s_addc_u32 s27, s27, 0
	s_mov_b32 m0, s47
	v_lshl_add_u64 v[200:201], s[26:27], 0, v[134:135]
	ds_read_b128 v[168:171], v150 offset:32768
	ds_read_b128 v[172:175], v150 offset:33792
	ds_read_b128 v[176:179], v150 offset:34816
	ds_read_b128 v[180:183], v150 offset:35840
	ds_read_b128 v[184:187], v150 offset:36864
	ds_read_b128 v[188:191], v150 offset:37888
	ds_read_b128 v[192:195], v150 offset:38912
	ds_read_b128 v[196:199], v150 offset:39936
	global_load_lds_dwordx4 v[200:201], off
	v_lshl_add_u64 v[200:201], s[26:27], 0, v[132:133]
	s_mov_b32 m0, s48
	s_nop 0
	global_load_lds_dwordx4 v[200:201], off
	s_add_i32 s63, 0, 0x1c000
	s_add_u32 s26, s24, 0x8000
	s_addc_u32 s27, s25, 0
	s_add_i32 s62, s62, s38
	v_add_u32_e32 v212, s63, v147
	v_lshl_add_u64 v[218:219], s[26:27], 0, v[128:129]
	s_mov_b32 m0, s62
	ds_read_b128 v[200:203], v212
	ds_read_b128 v[204:207], v212 offset:1024
	ds_read_b128 v[208:211], v212 offset:2048
	ds_read_b128 v[212:215], v212 offset:3072
	s_waitcnt vmcnt(8)
	s_waitcnt lgkmcnt(0)
	s_barrier
	s_setprio 1
	v_mfma_f32_16x16x32_bf16 v[124:127], v[152:155], v[168:171], v[124:127]
	v_mfma_f32_16x16x32_bf16 v[120:123], v[160:163], v[168:171], v[120:123]
	v_mfma_f32_16x16x32_bf16 v[108:111], v[152:155], v[176:179], v[108:111]
	v_mfma_f32_16x16x32_bf16 v[104:107], v[160:163], v[176:179], v[104:107]
	v_mfma_f32_16x16x32_bf16 v[92:95], v[152:155], v[184:187], v[92:95]
	v_mfma_f32_16x16x32_bf16 v[88:91], v[160:163], v[184:187], v[88:91]
	v_mfma_f32_16x16x32_bf16 v[76:79], v[152:155], v[192:195], v[76:79]
	v_mfma_f32_16x16x32_bf16 v[72:75], v[160:163], v[192:195], v[72:75]
	v_mfma_f32_16x16x32_bf16 v[124:127], v[156:159], v[172:175], v[124:127]
	v_mfma_f32_16x16x32_bf16 v[120:123], v[164:167], v[172:175], v[120:123]
	v_mfma_f32_16x16x32_bf16 v[108:111], v[156:159], v[180:183], v[108:111]
	v_mfma_f32_16x16x32_bf16 v[104:107], v[164:167], v[180:183], v[104:107]
	v_mfma_f32_16x16x32_bf16 v[92:95], v[156:159], v[188:191], v[92:95]
	v_mfma_f32_16x16x32_bf16 v[88:91], v[164:167], v[188:191], v[88:91]
	v_mfma_f32_16x16x32_bf16 v[76:79], v[156:159], v[196:199], v[76:79]
	v_mfma_f32_16x16x32_bf16 v[72:75], v[164:167], v[196:199], v[72:75]
	v_mfma_f32_16x16x32_bf16 v[116:119], v[200:203], v[168:171], v[116:119]
	v_mfma_f32_16x16x32_bf16 v[112:115], v[208:211], v[168:171], v[112:115]
	v_mfma_f32_16x16x32_bf16 v[100:103], v[200:203], v[176:179], v[100:103]
	v_mfma_f32_16x16x32_bf16 v[96:99], v[208:211], v[176:179], v[96:99]
	v_mfma_f32_16x16x32_bf16 v[84:87], v[200:203], v[184:187], v[84:87]
	v_mfma_f32_16x16x32_bf16 v[80:83], v[208:211], v[184:187], v[80:83]
	v_mfma_f32_16x16x32_bf16 v[68:71], v[200:203], v[192:195], v[68:71]
	v_mfma_f32_16x16x32_bf16 v[64:67], v[208:211], v[192:195], v[64:67]
	v_mfma_f32_16x16x32_bf16 v[116:119], v[204:207], v[172:175], v[116:119]
	v_mfma_f32_16x16x32_bf16 v[112:115], v[212:215], v[172:175], v[112:115]
	v_mfma_f32_16x16x32_bf16 v[100:103], v[204:207], v[180:183], v[100:103]
	v_mfma_f32_16x16x32_bf16 v[96:99], v[212:215], v[180:183], v[96:99]
	v_mfma_f32_16x16x32_bf16 v[84:87], v[204:207], v[188:191], v[84:87]
	v_mfma_f32_16x16x32_bf16 v[80:83], v[212:215], v[188:191], v[80:83]
	v_mfma_f32_16x16x32_bf16 v[68:71], v[204:207], v[196:199], v[68:71]
	v_mfma_f32_16x16x32_bf16 v[64:67], v[212:215], v[196:199], v[64:67]
	s_setprio 0
	s_barrier
; #define PG8_STAGE(bufoff, gbase, voff) do { _Pragma("unroll") for (int _i = 0; _i < 2; ++_i) \
;         __builtin_amdgcn_global_load_lds((const unsigned*)((const char*)(gbase) + (voff)[_i]), (PG8_LAS unsigned*)(lds + (bufoff) + ldsw + _i * 8192), 16, 0, 0); } while (0)
; #define PG8_LDA(dst, b, h) do { _Pragma("unroll") for (int m = 0; m < 4; ++m) _Pragma("unroll") for (int k = 0; k < 2; ++k) dst[m][k] = *(const PG8_LAS bf16x8*)(lds + PG8_SA(b, h) + aoff + m * 2048 + k * 1024); } while (0)
; #define PG8_LDB(dst, b, h) do { _Pragma("unroll") for (int n = 0; n < 2; ++n) _Pragma("unroll") for (int k = 0; k < 2; ++k) dst[n][k] = *(const PG8_LAS bf16x8*)(lds + PG8_SB(b, h) + boff + n * 2048 + k * 1024); } while (0)
; #define PG8_MMA(ai, bj, At, Bt) do { __builtin_amdgcn_s_setprio(1); _Pragma("unroll") for (int m = 0; m < 4; ++m) _Pragma("unroll") for (int n = 0; n < 2; ++n) _Pragma("unroll") for (int k = 0; k < 2; ++k) \
;         acc[ai][bj][m][n] = __builtin_amdgcn_mfma_f32_16x16x32_bf16(Bt[n][k], At[m][k], acc[ai][bj][m][n], 0, 0, 0); __builtin_amdgcn_s_setprio(0); } while (0)
; #define PG8_WAIT_V(n) asm volatile("s_waitcnt vmcnt(" #n ")" ::: "memory")
; #define PG8_WAIT_L(n) asm volatile("s_waitcnt lgkmcnt(" #n ")" ::: "memory")
; #define PG8_BAR __builtin_amdgcn_s_barrier()
; #define PG8_SCHED __builtin_amdgcn_sched_barrier(0)
; template <class Epi, class Sched>
; __device__ __forceinline__ void gemm_phase(PG8_LAS unsigned char* lds, const Gemm g, const Sched& S, const Epi& E) {
;     ...
;             PG8_LDB(B1, 1, 1); PG8_STAGE(PG8_SB(1, 0), b3, voffB);
;             PG8_BAR; PG8_WAIT_L(0); PG8_MMA(0, 1, At, B1); PG8_BAR;
;             PG8_LDA(At, 1, 1); PG8_STAGE(PG8_SA(1, 0), a3, voffA);
;             PG8_BAR; PG8_WAIT_L(0); PG8_MMA(1, 0, At, B0); PG8_BAR; PG8_SCHED;
;             PG8_STAGE(PG8_SB(1, 1), b3 + hstepB, voffB);
;             PG8_WAIT_V(6); PG8_BAR; PG8_MMA(1, 1, At, B1); PG8_BAR;
;         }
	global_load_lds_dwordx4 v[218:219], off
	v_lshl_add_u64 v[218:219], s[26:27], 0, v[130:131]
	s_add_i32 m0, s62, 0x2000
	s_nop 0
	global_load_lds_dwordx4 v[218:219], off
	s_mov_b32 m0, s50
	v_lshl_add_u64 v[144:145], v[144:145], 0, s[10:11]
	ds_read_b128 v[168:171], v150 offset:49152
	ds_read_b128 v[172:175], v150 offset:50176
	ds_read_b128 v[176:179], v150 offset:51200
	ds_read_b128 v[180:183], v150 offset:52224
	ds_read_b128 v[184:187], v150 offset:53248
	ds_read_b128 v[188:191], v150 offset:54272
	ds_read_b128 v[192:195], v150 offset:55296
	ds_read_b128 v[196:199], v150 offset:56320
	global_load_lds_dwordx4 v[144:145], off
	v_lshl_add_u64 v[144:145], v[216:217], 0, s[10:11]
	s_mov_b32 m0, s51
	s_nop 0
	global_load_lds_dwordx4 v[144:145], off
	s_add_u32 s24, s24, 0xc000
	s_addc_u32 s25, s25, 0
	s_add_i32 s26, s63, s38
	v_lshl_add_u64 v[144:145], s[24:25], 0, v[128:129]
	s_mov_b32 m0, s26
	s_nop 0
	global_load_lds_dwordx4 v[144:145], off
	v_lshl_add_u64 v[144:145], s[24:25], 0, v[130:131]
	s_add_i32 m0, s26, 0x2000
	s_nop 0
	global_load_lds_dwordx4 v[144:145], off
	s_waitcnt vmcnt(8)
	s_waitcnt lgkmcnt(0)
	s_barrier
	s_setprio 1
	v_mfma_f32_16x16x32_bf16 v[60:63], v[152:155], v[168:171], v[60:63]
	v_mfma_f32_16x16x32_bf16 v[56:59], v[160:163], v[168:171], v[56:59]
	v_mfma_f32_16x16x32_bf16 v[44:47], v[152:155], v[176:179], v[44:47]
	v_mfma_f32_16x16x32_bf16 v[40:43], v[160:163], v[176:179], v[40:43]
	v_mfma_f32_16x16x32_bf16 v[28:31], v[152:155], v[184:187], v[28:31]
	v_mfma_f32_16x16x32_bf16 v[24:27], v[160:163], v[184:187], v[24:27]
	v_mfma_f32_16x16x32_bf16 v[12:15], v[152:155], v[192:195], v[12:15]
	v_mfma_f32_16x16x32_bf16 v[8:11], v[160:163], v[192:195], v[8:11]
	v_mfma_f32_16x16x32_bf16 v[60:63], v[156:159], v[172:175], v[60:63]
	v_mfma_f32_16x16x32_bf16 v[56:59], v[164:167], v[172:175], v[56:59]
	v_mfma_f32_16x16x32_bf16 v[44:47], v[156:159], v[180:183], v[44:47]
	v_mfma_f32_16x16x32_bf16 v[40:43], v[164:167], v[180:183], v[40:43]
	v_mfma_f32_16x16x32_bf16 v[28:31], v[156:159], v[188:191], v[28:31]
	v_mfma_f32_16x16x32_bf16 v[24:27], v[164:167], v[188:191], v[24:27]
	v_mfma_f32_16x16x32_bf16 v[12:15], v[156:159], v[196:199], v[12:15]
	v_mfma_f32_16x16x32_bf16 v[8:11], v[164:167], v[196:199], v[8:11]
	v_mfma_f32_16x16x32_bf16 v[52:55], v[200:203], v[168:171], v[52:55]
	v_mfma_f32_16x16x32_bf16 v[48:51], v[208:211], v[168:171], v[48:51]
	v_mfma_f32_16x16x32_bf16 v[36:39], v[200:203], v[176:179], v[36:39]
	v_mfma_f32_16x16x32_bf16 v[32:35], v[208:211], v[176:179], v[32:35]
	v_mfma_f32_16x16x32_bf16 v[20:23], v[200:203], v[184:187], v[20:23]
	v_mfma_f32_16x16x32_bf16 v[16:19], v[208:211], v[184:187], v[16:19]
	v_mfma_f32_16x16x32_bf16 v[4:7], v[200:203], v[192:195], v[4:7]
	v_mfma_f32_16x16x32_bf16 v[0:3], v[208:211], v[192:195], v[0:3]
	v_mfma_f32_16x16x32_bf16 v[52:55], v[204:207], v[172:175], v[52:55]
	v_mfma_f32_16x16x32_bf16 v[48:51], v[212:215], v[172:175], v[48:51]
	v_mfma_f32_16x16x32_bf16 v[36:39], v[204:207], v[180:183], v[36:39]
	v_mfma_f32_16x16x32_bf16 v[32:35], v[212:215], v[180:183], v[32:35]
	v_mfma_f32_16x16x32_bf16 v[20:23], v[204:207], v[188:191], v[20:23]
	v_mfma_f32_16x16x32_bf16 v[16:19], v[212:215], v[188:191], v[16:19]
	v_mfma_f32_16x16x32_bf16 v[4:7], v[204:207], v[196:199], v[4:7]
	v_mfma_f32_16x16x32_bf16 v[0:3], v[212:215], v[196:199], v[0:3]
	s_setprio 0
	s_add_i32 s61, s61, 2
	s_add_u32 s59, s59, 0x10000
	s_addc_u32 s60, s60, 0
	s_add_u32 s22, s22, 0x100
	s_addc_u32 s23, s23, 0
	s_cmp_gt_u32 s61, 29
	s_barrier
	s_cbranch_scc0 .LBB0_79
	s_cmp_eq_u32 s78, 0
	s_cbranch_scc0 .Lhalf_skip_x_0
	s_barrier

; #define PG8_STAGE(bufoff, gbase, voff) do { _Pragma("unroll") for (int _i = 0; _i < 2; ++_i) \
;         __builtin_amdgcn_global_load_lds((const unsigned*)((const char*)(gbase) + (voff)[_i]), (PG8_LAS unsigned*)(lds + (bufoff) + ldsw + _i * 8192), 16, 0, 0); } while (0)
; #define PG8_LDA(dst, b, h) do { _Pragma("unroll") for (int m = 0; m < 4; ++m) _Pragma("unroll") for (int k = 0; k < 2; ++k) dst[m][k] = *(const PG8_LAS bf16x8*)(lds + PG8_SA(b, h) + aoff + m * 2048 + k * 1024); } while (0)
; #define PG8_LDB(dst, b, h) do { _Pragma("unroll") for (int n = 0; n < 2; ++n) _Pragma("unroll") for (int k = 0; k < 2; ++k) dst[n][k] = *(const PG8_LAS bf16x8*)(lds + PG8_SB(b, h) + boff + n * 2048 + k * 1024); } while (0)
; #define PG8_MMA(ai, bj, At, Bt) do { __builtin_amdgcn_s_setprio(1); _Pragma("unroll") for (int m = 0; m < 4; ++m) _Pragma("unroll") for (int n = 0; n < 2; ++n) _Pragma("unroll") for (int k = 0; k < 2; ++k) \
;         acc[ai][bj][m][n] = __builtin_amdgcn_mfma_f32_16x16x32_bf16(Bt[n][k], At[m][k], acc[ai][bj][m][n], 0, 0, 0); __builtin_amdgcn_s_setprio(0); } while (0)
; #define PG8_WAIT_L(n) asm volatile("s_waitcnt lgkmcnt(" #n ")" ::: "memory")
; #define PG8_BAR __builtin_amdgcn_s_barrier()
; #define PG8_SCHED __builtin_amdgcn_sched_barrier(0)
; template <class Epi, class Sched>
; __device__ __forceinline__ void gemm_phase(PG8_LAS unsigned char* lds, const Gemm g, const Sched& S, const Epi& E) {
;     ...
;             const bool last = (t == nt - 2);
;             const char* a1 = cA + (size_t)(t + 1) * kstep;
;             const char* a2 = last ? nA : cA + (size_t)(t + 2) * kstep; const char* b2 = last ? nB : cB + (size_t)(t + 2) * kstepB;
;             const char* a3 = a2 + kstep; const char* b3 = b2 + kstepB;
;             if (last && has_next) S.a_ready(nxt);
;             PG8_LDB(B0, 0, 0); PG8_SCHED; PG8_LDA(At, 0, 0); PG8_STAGE(PG8_SA(1, 1), a1 + hstep, voffA);
;             PG8_WAIT_L(8); PG8_BAR; PG8_WAIT_L(0); PG8_MMA(0, 0, At, B0); PG8_BAR; PG8_SCHED;
;             PG8_LDB(B1, 0, 1); PG8_STAGE(PG8_SB(0, 0), b2, voffB);
;             PG8_BAR; PG8_WAIT_L(0); PG8_MMA(0, 1, At, B1); PG8_BAR;
;             PG8_LDA(At, 0, 1); PG8_STAGE(PG8_SA(0, 0), a2, voffA);
;             PG8_BAR; PG8_WAIT_L(0); PG8_MMA(1, 0, At, B0); PG8_BAR; PG8_SCHED;
;             PG8_STAGE(PG8_SB(0, 1), b2 + hstepB, voffB);
.Lhalf_skip_y_1:
.LBB0_155:
	ds_read_b128 v[144:147], v153
	ds_read_b128 v[156:159], v153 offset:1024
	ds_read_b128 v[160:163], v153 offset:2048
	ds_read_b128 v[164:167], v153 offset:3072
	s_add_u32 s26, s24, 0x100
	s_addc_u32 s27, s25, 0
	s_cmpk_eq_i32 s67, 0x52
	s_cselect_b32 s31, s7, s27
	s_cselect_b32 s30, s6, s26
	s_cselect_b32 s29, s9, s66
	s_cselect_b32 s28, s8, s65
	v_lshl_add_u64 v[148:149], s[24:25], 0, v[136:137]
	s_add_i32 m0, s51, 0xc000
	ds_read_b128 v[168:171], v154
	ds_read_b128 v[172:175], v154 offset:1024
	ds_read_b128 v[176:179], v154 offset:2048
	ds_read_b128 v[180:183], v154 offset:3072
	ds_read_b128 v[184:187], v154 offset:4096
	ds_read_b128 v[188:191], v154 offset:5120
	ds_read_b128 v[192:195], v154 offset:6144
	ds_read_b128 v[196:199], v154 offset:7168
	global_load_lds_dwordx4 v[148:149], off
	v_lshl_add_u64 v[148:149], s[24:25], 0, v[138:139]
	s_add_i32 m0, s51, 0xe000
	s_nop 0
	global_load_lds_dwordx4 v[148:149], off
	s_add_i32 s24, s59, s50
	v_lshl_add_u64 v[148:149], s[28:29], 0, v[128:129]
	s_mov_b32 m0, s24
	ds_read_b128 v[200:203], v155
	ds_read_b128 v[204:207], v155 offset:1024
	ds_read_b128 v[208:211], v155 offset:2048
	ds_read_b128 v[212:215], v155 offset:3072
	s_waitcnt vmcnt(8)
	s_waitcnt lgkmcnt(0)
	s_barrier
	s_setprio 1
	v_mfma_f32_16x16x32_bf16 v[124:127], v[144:147], v[168:171], v[124:127]
	v_mfma_f32_16x16x32_bf16 v[120:123], v[160:163], v[168:171], v[120:123]
	v_mfma_f32_16x16x32_bf16 v[108:111], v[144:147], v[176:179], v[108:111]
	v_mfma_f32_16x16x32_bf16 v[104:107], v[160:163], v[176:179], v[104:107]
	v_mfma_f32_16x16x32_bf16 v[92:95], v[144:147], v[184:187], v[92:95]
	v_mfma_f32_16x16x32_bf16 v[88:91], v[160:163], v[184:187], v[88:91]
	v_mfma_f32_16x16x32_bf16 v[76:79], v[144:147], v[192:195], v[76:79]
	v_mfma_f32_16x16x32_bf16 v[72:75], v[160:163], v[192:195], v[72:75]
	v_mfma_f32_16x16x32_bf16 v[124:127], v[156:159], v[172:175], v[124:127]
	v_mfma_f32_16x16x32_bf16 v[120:123], v[164:167], v[172:175], v[120:123]
	v_mfma_f32_16x16x32_bf16 v[108:111], v[156:159], v[180:183], v[108:111]
	v_mfma_f32_16x16x32_bf16 v[104:107], v[164:167], v[180:183], v[104:107]
	v_mfma_f32_16x16x32_bf16 v[92:95], v[156:159], v[188:191], v[92:95]
	v_mfma_f32_16x16x32_bf16 v[88:91], v[164:167], v[188:191], v[88:91]
	v_mfma_f32_16x16x32_bf16 v[76:79], v[156:159], v[196:199], v[76:79]
	v_mfma_f32_16x16x32_bf16 v[72:75], v[164:167], v[196:199], v[72:75]
	v_mfma_f32_16x16x32_bf16 v[116:119], v[200:203], v[168:171], v[116:119]
	v_mfma_f32_16x16x32_bf16 v[112:115], v[208:211], v[168:171], v[112:115]
	v_mfma_f32_16x16x32_bf16 v[100:103], v[200:203], v[176:179], v[100:103]
	v_mfma_f32_16x16x32_bf16 v[96:99], v[208:211], v[176:179], v[96:99]
	v_mfma_f32_16x16x32_bf16 v[84:87], v[200:203], v[184:187], v[84:87]
	v_mfma_f32_16x16x32_bf16 v[80:83], v[208:211], v[184:187], v[80:83]
	v_mfma_f32_16x16x32_bf16 v[68:71], v[200:203], v[192:195], v[68:71]
	v_mfma_f32_16x16x32_bf16 v[64:67], v[208:211], v[192:195], v[64:67]
	v_mfma_f32_16x16x32_bf16 v[116:119], v[204:207], v[172:175], v[116:119]
	v_mfma_f32_16x16x32_bf16 v[112:115], v[212:215], v[172:175], v[112:115]
	v_mfma_f32_16x16x32_bf16 v[100:103], v[204:207], v[180:183], v[100:103]
	v_mfma_f32_16x16x32_bf16 v[96:99], v[212:215], v[180:183], v[96:99]
	v_mfma_f32_16x16x32_bf16 v[84:87], v[204:207], v[188:191], v[84:87]
	v_mfma_f32_16x16x32_bf16 v[80:83], v[212:215], v[188:191], v[80:83]
	v_mfma_f32_16x16x32_bf16 v[68:71], v[204:207], v[196:199], v[68:71]
	v_mfma_f32_16x16x32_bf16 v[64:67], v[212:215], v[196:199], v[64:67]
	s_setprio 0
	s_barrier
	global_load_lds_dwordx4 v[148:149], off
	v_lshl_add_u64 v[148:149], s[28:29], 0, v[132:133]
	s_add_i32 m0, s24, 0x2000
	s_nop 0
	global_load_lds_dwordx4 v[148:149], off
	s_mov_b32 m0, s51
	v_lshl_add_u64 v[148:149], s[30:31], 0, v[130:131]
	ds_read_b128 v[168:171], v154 offset:16384
	ds_read_b128 v[172:175], v154 offset:17408
	ds_read_b128 v[176:179], v154 offset:18432
	ds_read_b128 v[180:183], v154 offset:19456
	ds_read_b128 v[184:187], v154 offset:20480
	ds_read_b128 v[188:191], v154 offset:21504
	ds_read_b128 v[192:195], v154 offset:22528
	ds_read_b128 v[196:199], v154 offset:23552
	global_load_lds_dwordx4 v[148:149], off
	v_lshl_add_u64 v[216:217], s[30:31], 0, v[134:135]
	s_mov_b32 m0, s52
	s_nop 0
	global_load_lds_dwordx4 v[216:217], off
	s_add_u32 s24, s28, 0x4000
	s_addc_u32 s25, s29, 0
	s_add_i32 s68, s60, s50
	v_lshl_add_u64 v[250:251], s[24:25], 0, v[128:129]
	s_mov_b32 m0, s68
	s_nop 0
	global_load_lds_dwordx4 v[250:251], off
	v_lshl_add_u64 v[250:251], s[24:25], 0, v[132:133]
	s_add_i32 m0, s68, 0x2000
	s_nop 0
	global_load_lds_dwordx4 v[250:251], off
	s_waitcnt vmcnt(8)
	s_waitcnt lgkmcnt(0)
	s_barrier
; #define PG8_STAGE(bufoff, gbase, voff) do { _Pragma("unroll") for (int _i = 0; _i < 2; ++_i) \
;         __builtin_amdgcn_global_load_lds((const unsigned*)((const char*)(gbase) + (voff)[_i]), (PG8_LAS unsigned*)(lds + (bufoff) + ldsw + _i * 8192), 16, 0, 0); } while (0)
; #define PG8_LDA(dst, b, h) do { _Pragma("unroll") for (int m = 0; m < 4; ++m) _Pragma("unroll") for (int k = 0; k < 2; ++k) dst[m][k] = *(const PG8_LAS bf16x8*)(lds + PG8_SA(b, h) + aoff + m * 2048 + k * 1024); } while (0)
; #define PG8_LDB(dst, b, h) do { _Pragma("unroll") for (int n = 0; n < 2; ++n) _Pragma("unroll") for (int k = 0; k < 2; ++k) dst[n][k] = *(const PG8_LAS bf16x8*)(lds + PG8_SB(b, h) + boff + n * 2048 + k * 1024); } while (0)
; #define PG8_MMA(ai, bj, At, Bt) do { __builtin_amdgcn_s_setprio(1); _Pragma("unroll") for (int m = 0; m < 4; ++m) _Pragma("unroll") for (int n = 0; n < 2; ++n) _Pragma("unroll") for (int k = 0; k < 2; ++k) \
;         acc[ai][bj][m][n] = __builtin_amdgcn_mfma_f32_16x16x32_bf16(Bt[n][k], At[m][k], acc[ai][bj][m][n], 0, 0, 0); __builtin_amdgcn_s_setprio(0); } while (0)
; #define PG8_WAIT_V(n) asm volatile("s_waitcnt vmcnt(" #n ")" ::: "memory")
; #define PG8_WAIT_L(n) asm volatile("s_waitcnt lgkmcnt(" #n ")" ::: "memory")
; #define PG8_BAR __builtin_amdgcn_s_barrier()
; #define PG8_SCHED __builtin_amdgcn_sched_barrier(0)
; template <class Epi, class Sched>
; __device__ __forceinline__ void gemm_phase(PG8_LAS unsigned char* lds, const Gemm g, const Sched& S, const Epi& E) {
;     ...
;             PG8_BAR; PG8_WAIT_L(0); PG8_MMA(1, 0, At, B0); PG8_BAR; PG8_SCHED;
;             PG8_STAGE(PG8_SB(0, 1), b2 + hstepB, voffB);
;             PG8_WAIT_V(6); PG8_BAR; PG8_MMA(1, 1, At, B1); PG8_BAR;
;             PG8_LDB(B0, 1, 0); PG8_SCHED; PG8_LDA(At, 1, 0); PG8_STAGE(PG8_SA(0, 1), a2 + hstep, voffA);
;             PG8_WAIT_L(8); PG8_BAR; PG8_WAIT_L(0); PG8_MMA(0, 0, At, B0); PG8_BAR; PG8_SCHED;
;             PG8_LDB(B1, 1, 1); PG8_STAGE(PG8_SB(1, 0), b3, voffB);
;             PG8_BAR; PG8_WAIT_L(0); PG8_MMA(0, 1, At, B1); PG8_BAR;
	s_setprio 1
	v_mfma_f32_16x16x32_bf16 v[60:63], v[144:147], v[168:171], v[60:63]
	v_mfma_f32_16x16x32_bf16 v[56:59], v[160:163], v[168:171], v[56:59]
	v_mfma_f32_16x16x32_bf16 v[44:47], v[144:147], v[176:179], v[44:47]
	v_mfma_f32_16x16x32_bf16 v[40:43], v[160:163], v[176:179], v[40:43]
	v_mfma_f32_16x16x32_bf16 v[28:31], v[144:147], v[184:187], v[28:31]
	v_mfma_f32_16x16x32_bf16 v[24:27], v[160:163], v[184:187], v[24:27]
	v_mfma_f32_16x16x32_bf16 v[12:15], v[144:147], v[192:195], v[12:15]
	v_mfma_f32_16x16x32_bf16 v[8:11], v[160:163], v[192:195], v[8:11]
	v_mfma_f32_16x16x32_bf16 v[60:63], v[156:159], v[172:175], v[60:63]
	v_mfma_f32_16x16x32_bf16 v[56:59], v[164:167], v[172:175], v[56:59]
	v_mfma_f32_16x16x32_bf16 v[44:47], v[156:159], v[180:183], v[44:47]
	v_mfma_f32_16x16x32_bf16 v[40:43], v[164:167], v[180:183], v[40:43]
	v_mfma_f32_16x16x32_bf16 v[28:31], v[156:159], v[188:191], v[28:31]
	v_mfma_f32_16x16x32_bf16 v[24:27], v[164:167], v[188:191], v[24:27]
	v_mfma_f32_16x16x32_bf16 v[12:15], v[156:159], v[196:199], v[12:15]
	v_mfma_f32_16x16x32_bf16 v[8:11], v[164:167], v[196:199], v[8:11]
	v_mfma_f32_16x16x32_bf16 v[52:55], v[200:203], v[168:171], v[52:55]
	v_mfma_f32_16x16x32_bf16 v[48:51], v[208:211], v[168:171], v[48:51]
	v_mfma_f32_16x16x32_bf16 v[36:39], v[200:203], v[176:179], v[36:39]
	v_mfma_f32_16x16x32_bf16 v[32:35], v[208:211], v[176:179], v[32:35]
	v_mfma_f32_16x16x32_bf16 v[20:23], v[200:203], v[184:187], v[20:23]
	v_mfma_f32_16x16x32_bf16 v[16:19], v[208:211], v[184:187], v[16:19]
	v_mfma_f32_16x16x32_bf16 v[4:7], v[200:203], v[192:195], v[4:7]
	v_mfma_f32_16x16x32_bf16 v[0:3], v[208:211], v[192:195], v[0:3]
	v_mfma_f32_16x16x32_bf16 v[52:55], v[204:207], v[172:175], v[52:55]
	v_mfma_f32_16x16x32_bf16 v[48:51], v[212:215], v[172:175], v[48:51]
	v_mfma_f32_16x16x32_bf16 v[36:39], v[204:207], v[180:183], v[36:39]
	v_mfma_f32_16x16x32_bf16 v[32:35], v[212:215], v[180:183], v[32:35]
	v_mfma_f32_16x16x32_bf16 v[20:23], v[204:207], v[188:191], v[20:23]
	v_mfma_f32_16x16x32_bf16 v[16:19], v[212:215], v[188:191], v[16:19]
	v_mfma_f32_16x16x32_bf16 v[4:7], v[204:207], v[196:199], v[4:7]
	v_mfma_f32_16x16x32_bf16 v[0:3], v[212:215], v[196:199], v[0:3]
	s_setprio 0
	s_barrier
	s_add_i32 s68, 0, 0x18000
	v_add_u32_e32 v164, s68, v151
	ds_read_b128 v[144:147], v164
	ds_read_b128 v[156:159], v164 offset:1024
	ds_read_b128 v[160:163], v164 offset:2048
	ds_read_b128 v[164:167], v164 offset:3072
	s_add_u32 s24, s30, 0x158000
	s_addc_u32 s25, s31, 0
	s_mov_b32 m0, s53
	v_lshl_add_u64 v[200:201], s[24:25], 0, v[130:131]
	ds_read_b128 v[168:171], v154 offset:32768
	ds_read_b128 v[172:175], v154 offset:33792
	ds_read_b128 v[176:179], v154 offset:34816
	ds_read_b128 v[180:183], v154 offset:35840
	ds_read_b128 v[184:187], v154 offset:36864
	ds_read_b128 v[188:191], v154 offset:37888
	ds_read_b128 v[192:195], v154 offset:38912
	ds_read_b128 v[196:199], v154 offset:39936
	global_load_lds_dwordx4 v[200:201], off
	v_lshl_add_u64 v[200:201], s[24:25], 0, v[134:135]
	s_mov_b32 m0, s54
	s_nop 0
	global_load_lds_dwordx4 v[200:201], off
	s_add_i32 s30, 0, 0x1c000
	s_add_u32 s24, s28, 0x8000
	s_addc_u32 s25, s29, 0
	s_add_i32 s31, s68, s50
	v_add_u32_e32 v212, s30, v151
	v_lshl_add_u64 v[218:219], s[24:25], 0, v[128:129]
	s_mov_b32 m0, s31
	ds_read_b128 v[200:203], v212
	ds_read_b128 v[204:207], v212 offset:1024
	ds_read_b128 v[208:211], v212 offset:2048
	ds_read_b128 v[212:215], v212 offset:3072
	s_waitcnt vmcnt(8)
	s_waitcnt lgkmcnt(0)
	s_barrier
	s_setprio 1
	v_mfma_f32_16x16x32_bf16 v[124:127], v[144:147], v[168:171], v[124:127]
	v_mfma_f32_16x16x32_bf16 v[120:123], v[160:163], v[168:171], v[120:123]
	v_mfma_f32_16x16x32_bf16 v[108:111], v[144:147], v[176:179], v[108:111]
	v_mfma_f32_16x16x32_bf16 v[104:107], v[160:163], v[176:179], v[104:107]
	v_mfma_f32_16x16x32_bf16 v[92:95], v[144:147], v[184:187], v[92:95]
	v_mfma_f32_16x16x32_bf16 v[88:91], v[160:163], v[184:187], v[88:91]
	v_mfma_f32_16x16x32_bf16 v[76:79], v[144:147], v[192:195], v[76:79]
	v_mfma_f32_16x16x32_bf16 v[72:75], v[160:163], v[192:195], v[72:75]
	v_mfma_f32_16x16x32_bf16 v[124:127], v[156:159], v[172:175], v[124:127]
	v_mfma_f32_16x16x32_bf16 v[120:123], v[164:167], v[172:175], v[120:123]
	v_mfma_f32_16x16x32_bf16 v[108:111], v[156:159], v[180:183], v[108:111]
	v_mfma_f32_16x16x32_bf16 v[104:107], v[164:167], v[180:183], v[104:107]
	v_mfma_f32_16x16x32_bf16 v[92:95], v[156:159], v[188:191], v[92:95]
	v_mfma_f32_16x16x32_bf16 v[88:91], v[164:167], v[188:191], v[88:91]
	v_mfma_f32_16x16x32_bf16 v[76:79], v[156:159], v[196:199], v[76:79]
	v_mfma_f32_16x16x32_bf16 v[72:75], v[164:167], v[196:199], v[72:75]
	v_mfma_f32_16x16x32_bf16 v[116:119], v[200:203], v[168:171], v[116:119]
	v_mfma_f32_16x16x32_bf16 v[112:115], v[208:211], v[168:171], v[112:115]
	v_mfma_f32_16x16x32_bf16 v[100:103], v[200:203], v[176:179], v[100:103]
	v_mfma_f32_16x16x32_bf16 v[96:99], v[208:211], v[176:179], v[96:99]
	v_mfma_f32_16x16x32_bf16 v[84:87], v[200:203], v[184:187], v[84:87]
	v_mfma_f32_16x16x32_bf16 v[80:83], v[208:211], v[184:187], v[80:83]
	v_mfma_f32_16x16x32_bf16 v[68:71], v[200:203], v[192:195], v[68:71]
	v_mfma_f32_16x16x32_bf16 v[64:67], v[208:211], v[192:195], v[64:67]
	v_mfma_f32_16x16x32_bf16 v[116:119], v[204:207], v[172:175], v[116:119]
	v_mfma_f32_16x16x32_bf16 v[112:115], v[212:215], v[172:175], v[112:115]
	v_mfma_f32_16x16x32_bf16 v[100:103], v[204:207], v[180:183], v[100:103]
	v_mfma_f32_16x16x32_bf16 v[96:99], v[212:215], v[180:183], v[96:99]
	v_mfma_f32_16x16x32_bf16 v[84:87], v[204:207], v[188:191], v[84:87]
	v_mfma_f32_16x16x32_bf16 v[80:83], v[212:215], v[188:191], v[80:83]
	v_mfma_f32_16x16x32_bf16 v[68:71], v[204:207], v[196:199], v[68:71]
	v_mfma_f32_16x16x32_bf16 v[64:67], v[212:215], v[196:199], v[64:67]
	s_setprio 0
	s_barrier
; #define PG8_STAGE(bufoff, gbase, voff) do { _Pragma("unroll") for (int _i = 0; _i < 2; ++_i) \
;         __builtin_amdgcn_global_load_lds((const unsigned*)((const char*)(gbase) + (voff)[_i]), (PG8_LAS unsigned*)(lds + (bufoff) + ldsw + _i * 8192), 16, 0, 0); } while (0)
; #define PG8_LDA(dst, b, h) do { _Pragma("unroll") for (int m = 0; m < 4; ++m) _Pragma("unroll") for (int k = 0; k < 2; ++k) dst[m][k] = *(const PG8_LAS bf16x8*)(lds + PG8_SA(b, h) + aoff + m * 2048 + k * 1024); } while (0)
; #define PG8_LDB(dst, b, h) do { _Pragma("unroll") for (int n = 0; n < 2; ++n) _Pragma("unroll") for (int k = 0; k < 2; ++k) dst[n][k] = *(const PG8_LAS bf16x8*)(lds + PG8_SB(b, h) + boff + n * 2048 + k * 1024); } while (0)
; #define PG8_MMA(ai, bj, At, Bt) do { __builtin_amdgcn_s_setprio(1); _Pragma("unroll") for (int m = 0; m < 4; ++m) _Pragma("unroll") for (int n = 0; n < 2; ++n) _Pragma("unroll") for (int k = 0; k < 2; ++k) \
;         acc[ai][bj][m][n] = __builtin_amdgcn_mfma_f32_16x16x32_bf16(Bt[n][k], At[m][k], acc[ai][bj][m][n], 0, 0, 0); __builtin_amdgcn_s_setprio(0); } while (0)
; #define PG8_WAIT_V(n) asm volatile("s_waitcnt vmcnt(" #n ")" ::: "memory")
; #define PG8_WAIT_L(n) asm volatile("s_waitcnt lgkmcnt(" #n ")" ::: "memory")
; #define PG8_BAR __builtin_amdgcn_s_barrier()
; #define PG8_SCHED __builtin_amdgcn_sched_barrier(0)
; template <class Epi, class Sched>
; __device__ __forceinline__ void gemm_phase(PG8_LAS unsigned char* lds, const Gemm g, const Sched& S, const Epi& E) {
;     ...
;             PG8_LDB(B1, 1, 1); PG8_STAGE(PG8_SB(1, 0), b3, voffB);
;             PG8_BAR; PG8_WAIT_L(0); PG8_MMA(0, 1, At, B1); PG8_BAR;
;             PG8_LDA(At, 1, 1); PG8_STAGE(PG8_SA(1, 0), a3, voffA);
;             PG8_BAR; PG8_WAIT_L(0); PG8_MMA(1, 0, At, B0); PG8_BAR; PG8_SCHED;
;             PG8_STAGE(PG8_SB(1, 1), b3 + hstepB, voffB);
;             PG8_WAIT_V(6); PG8_BAR; PG8_MMA(1, 1, At, B1); PG8_BAR;
;         }
	global_load_lds_dwordx4 v[218:219], off
	v_lshl_add_u64 v[218:219], s[24:25], 0, v[132:133]
	s_add_i32 m0, s31, 0x2000
	s_nop 0
	global_load_lds_dwordx4 v[218:219], off
	s_mov_b32 m0, s56
	v_lshl_add_u64 v[148:149], v[148:149], 0, s[14:15]
	ds_read_b128 v[168:171], v154 offset:49152
	ds_read_b128 v[172:175], v154 offset:50176
	ds_read_b128 v[176:179], v154 offset:51200
	ds_read_b128 v[180:183], v154 offset:52224
	ds_read_b128 v[184:187], v154 offset:53248
	ds_read_b128 v[188:191], v154 offset:54272
	ds_read_b128 v[192:195], v154 offset:55296
	ds_read_b128 v[196:199], v154 offset:56320
	global_load_lds_dwordx4 v[148:149], off
	v_lshl_add_u64 v[148:149], v[216:217], 0, s[14:15]
	s_mov_b32 m0, s57
	s_nop 0
	global_load_lds_dwordx4 v[148:149], off
	s_add_u32 s24, s28, 0xc000
	s_addc_u32 s25, s29, 0
	s_add_i32 s28, s30, s50
	v_lshl_add_u64 v[252:253], s[24:25], 0, v[128:129]
	s_mov_b32 m0, s28
	s_nop 0
	global_load_lds_dwordx4 v[252:253], off
	v_lshl_add_u64 v[252:253], s[24:25], 0, v[132:133]
	s_add_i32 m0, s28, 0x2000
	s_nop 0
	global_load_lds_dwordx4 v[252:253], off
	s_waitcnt vmcnt(8)
	s_waitcnt lgkmcnt(0)
	s_barrier
	s_setprio 1
	v_mfma_f32_16x16x32_bf16 v[60:63], v[144:147], v[168:171], v[60:63]
	v_mfma_f32_16x16x32_bf16 v[56:59], v[160:163], v[168:171], v[56:59]
	v_mfma_f32_16x16x32_bf16 v[44:47], v[144:147], v[176:179], v[44:47]
	v_mfma_f32_16x16x32_bf16 v[40:43], v[160:163], v[176:179], v[40:43]
	v_mfma_f32_16x16x32_bf16 v[28:31], v[144:147], v[184:187], v[28:31]
	v_mfma_f32_16x16x32_bf16 v[24:27], v[160:163], v[184:187], v[24:27]
	v_mfma_f32_16x16x32_bf16 v[12:15], v[144:147], v[192:195], v[12:15]
	v_mfma_f32_16x16x32_bf16 v[8:11], v[160:163], v[192:195], v[8:11]
	v_mfma_f32_16x16x32_bf16 v[60:63], v[156:159], v[172:175], v[60:63]
	v_mfma_f32_16x16x32_bf16 v[56:59], v[164:167], v[172:175], v[56:59]
	v_mfma_f32_16x16x32_bf16 v[44:47], v[156:159], v[180:183], v[44:47]
	v_mfma_f32_16x16x32_bf16 v[40:43], v[164:167], v[180:183], v[40:43]
	v_mfma_f32_16x16x32_bf16 v[28:31], v[156:159], v[188:191], v[28:31]
	v_mfma_f32_16x16x32_bf16 v[24:27], v[164:167], v[188:191], v[24:27]
	v_mfma_f32_16x16x32_bf16 v[12:15], v[156:159], v[196:199], v[12:15]
	v_mfma_f32_16x16x32_bf16 v[8:11], v[164:167], v[196:199], v[8:11]
	v_mfma_f32_16x16x32_bf16 v[52:55], v[200:203], v[168:171], v[52:55]
	v_mfma_f32_16x16x32_bf16 v[48:51], v[208:211], v[168:171], v[48:51]
	v_mfma_f32_16x16x32_bf16 v[36:39], v[200:203], v[176:179], v[36:39]
	v_mfma_f32_16x16x32_bf16 v[32:35], v[208:211], v[176:179], v[32:35]
	v_mfma_f32_16x16x32_bf16 v[20:23], v[200:203], v[184:187], v[20:23]
	v_mfma_f32_16x16x32_bf16 v[16:19], v[208:211], v[184:187], v[16:19]
	v_mfma_f32_16x16x32_bf16 v[4:7], v[200:203], v[192:195], v[4:7]
	v_mfma_f32_16x16x32_bf16 v[0:3], v[208:211], v[192:195], v[0:3]
	v_mfma_f32_16x16x32_bf16 v[52:55], v[204:207], v[172:175], v[52:55]
	v_mfma_f32_16x16x32_bf16 v[48:51], v[212:215], v[172:175], v[48:51]
	v_mfma_f32_16x16x32_bf16 v[36:39], v[204:207], v[180:183], v[36:39]
	v_mfma_f32_16x16x32_bf16 v[32:35], v[212:215], v[180:183], v[32:35]
	v_mfma_f32_16x16x32_bf16 v[20:23], v[204:207], v[188:191], v[20:23]
	v_mfma_f32_16x16x32_bf16 v[16:19], v[212:215], v[188:191], v[16:19]
	v_mfma_f32_16x16x32_bf16 v[4:7], v[204:207], v[196:199], v[4:7]
	v_mfma_f32_16x16x32_bf16 v[0:3], v[212:215], v[196:199], v[0:3]
	s_setprio 0
	s_add_i32 s67, s67, 2
	s_add_u32 s65, s65, 0x10000
	s_addc_u32 s66, s66, 0
	s_cmpk_gt_u32 s67, 0x53
	s_mov_b64 s[24:25], s[26:27]
	s_barrier
	s_cbranch_scc0 .LBB0_155
	s_cmp_eq_u32 s78, 0
	s_cbranch_scc0 .Lhalf_skip_x_1
	s_barrier

; #define PG8_STAGE(bufoff, gbase, voff) do { _Pragma("unroll") for (int _i = 0; _i < 2; ++_i) \
;         __builtin_amdgcn_global_load_lds((const unsigned*)((const char*)(gbase) + (voff)[_i]), (PG8_LAS unsigned*)(lds + (bufoff) + ldsw + _i * 8192), 16, 0, 0); } while (0)
; #define PG8_LDA(dst, b, h) do { _Pragma("unroll") for (int m = 0; m < 4; ++m) _Pragma("unroll") for (int k = 0; k < 2; ++k) dst[m][k] = *(const PG8_LAS bf16x8*)(lds + PG8_SA(b, h) + aoff + m * 2048 + k * 1024); } while (0)
; #define PG8_LDB(dst, b, h) do { _Pragma("unroll") for (int n = 0; n < 2; ++n) _Pragma("unroll") for (int k = 0; k < 2; ++k) dst[n][k] = *(const PG8_LAS bf16x8*)(lds + PG8_SB(b, h) + boff + n * 2048 + k * 1024); } while (0)
; #define PG8_MMA(ai, bj, At, Bt) do { __builtin_amdgcn_s_setprio(1); _Pragma("unroll") for (int m = 0; m < 4; ++m) _Pragma("unroll") for (int n = 0; n < 2; ++n) _Pragma("unroll") for (int k = 0; k < 2; ++k) \
;         acc[ai][bj][m][n] = __builtin_amdgcn_mfma_f32_16x16x32_bf16(Bt[n][k], At[m][k], acc[ai][bj][m][n], 0, 0, 0); __builtin_amdgcn_s_setprio(0); } while (0)
; #define PG8_WAIT_L(n) asm volatile("s_waitcnt lgkmcnt(" #n ")" ::: "memory")
; #define PG8_BAR __builtin_amdgcn_s_barrier()
; #define PG8_SCHED __builtin_amdgcn_sched_barrier(0)
; template <class Epi, class Sched>
; __device__ __forceinline__ void gemm_phase(PG8_LAS unsigned char* lds, const Gemm g, const Sched& S, const Epi& E) {
;     ...
;             const bool last = (t == nt - 2);
;             const char* a1 = cA + (size_t)(t + 1) * kstep;
;             const char* a2 = last ? nA : cA + (size_t)(t + 2) * kstep; const char* b2 = last ? nB : cB + (size_t)(t + 2) * kstepB;
;             const char* a3 = a2 + kstep; const char* b3 = b2 + kstepB;
;             if (last && has_next) S.a_ready(nxt);
;             PG8_LDB(B0, 0, 0); PG8_SCHED; PG8_LDA(At, 0, 0); PG8_STAGE(PG8_SA(1, 1), a1 + hstep, voffA);
;             PG8_WAIT_L(8); PG8_BAR; PG8_WAIT_L(0); PG8_MMA(0, 0, At, B0); PG8_BAR; PG8_SCHED;
;             PG8_LDB(B1, 0, 1); PG8_STAGE(PG8_SB(0, 0), b2, voffB);
;             PG8_BAR; PG8_WAIT_L(0); PG8_MMA(0, 1, At, B1); PG8_BAR;
;             PG8_LDA(At, 0, 1); PG8_STAGE(PG8_SA(0, 0), a2, voffA);
;             PG8_BAR; PG8_WAIT_L(0); PG8_MMA(1, 0, At, B0); PG8_BAR; PG8_SCHED;
;             PG8_STAGE(PG8_SB(0, 1), b2 + hstepB, voffB);
.Lhalf_skip_y_2:
.LBB0_280:
	ds_read_b128 v[150:153], v147
	ds_read_b128 v[154:157], v147 offset:1024
	ds_read_b128 v[158:161], v147 offset:2048
	ds_read_b128 v[162:165], v147 offset:3072
	s_add_u32 s48, s6, 0xfff80080
	s_addc_u32 s49, s7, -1
	s_cmp_eq_u32 s69, 28
	s_cselect_b32 s51, s9, s49
	s_cselect_b32 s50, s29, s48
	s_cselect_b32 s49, s31, s68
	s_cselect_b32 s48, s47, s67
	v_lshl_add_u64 v[198:199], s[6:7], 0, v[136:137]
	s_add_i32 m0, s54, 0xc000
	ds_read_b128 v[166:169], v148
	ds_read_b128 v[170:173], v148 offset:1024
	ds_read_b128 v[174:177], v148 offset:2048
	ds_read_b128 v[178:181], v148 offset:3072
	ds_read_b128 v[182:185], v148 offset:4096
	ds_read_b128 v[186:189], v148 offset:5120
	ds_read_b128 v[190:193], v148 offset:6144
	ds_read_b128 v[194:197], v148 offset:7168
	global_load_lds_dwordx4 v[198:199], off
	v_lshl_add_u64 v[198:199], s[6:7], 0, v[138:139]
	s_add_i32 m0, s54, 0xe000
	s_nop 0
	global_load_lds_dwordx4 v[198:199], off
	s_add_i32 s70, s63, s53
	v_lshl_add_u64 v[214:215], s[48:49], 0, v[128:129]
	s_mov_b32 m0, s70
	ds_read_b128 v[198:201], v149
	ds_read_b128 v[202:205], v149 offset:1024
	ds_read_b128 v[206:209], v149 offset:2048
	ds_read_b128 v[210:213], v149 offset:3072
	s_waitcnt vmcnt(8)
	s_waitcnt lgkmcnt(0)
	s_barrier
	s_setprio 1
	v_mfma_f32_16x16x32_bf16 v[124:127], v[150:153], v[166:169], v[124:127]
	v_mfma_f32_16x16x32_bf16 v[120:123], v[158:161], v[166:169], v[120:123]
	v_mfma_f32_16x16x32_bf16 v[108:111], v[150:153], v[174:177], v[108:111]
	v_mfma_f32_16x16x32_bf16 v[104:107], v[158:161], v[174:177], v[104:107]
	v_mfma_f32_16x16x32_bf16 v[92:95], v[150:153], v[182:185], v[92:95]
	v_mfma_f32_16x16x32_bf16 v[88:91], v[158:161], v[182:185], v[88:91]
	v_mfma_f32_16x16x32_bf16 v[76:79], v[150:153], v[190:193], v[76:79]
	v_mfma_f32_16x16x32_bf16 v[72:75], v[158:161], v[190:193], v[72:75]
	v_mfma_f32_16x16x32_bf16 v[124:127], v[154:157], v[170:173], v[124:127]
	v_mfma_f32_16x16x32_bf16 v[120:123], v[162:165], v[170:173], v[120:123]
	v_mfma_f32_16x16x32_bf16 v[108:111], v[154:157], v[178:181], v[108:111]
	v_mfma_f32_16x16x32_bf16 v[104:107], v[162:165], v[178:181], v[104:107]
	v_mfma_f32_16x16x32_bf16 v[92:95], v[154:157], v[186:189], v[92:95]
	v_mfma_f32_16x16x32_bf16 v[88:91], v[162:165], v[186:189], v[88:91]
	v_mfma_f32_16x16x32_bf16 v[76:79], v[154:157], v[194:197], v[76:79]
	v_mfma_f32_16x16x32_bf16 v[72:75], v[162:165], v[194:197], v[72:75]
	v_mfma_f32_16x16x32_bf16 v[116:119], v[198:201], v[166:169], v[116:119]
	v_mfma_f32_16x16x32_bf16 v[112:115], v[206:209], v[166:169], v[112:115]
	v_mfma_f32_16x16x32_bf16 v[100:103], v[198:201], v[174:177], v[100:103]
	v_mfma_f32_16x16x32_bf16 v[96:99], v[206:209], v[174:177], v[96:99]
	v_mfma_f32_16x16x32_bf16 v[84:87], v[198:201], v[182:185], v[84:87]
	v_mfma_f32_16x16x32_bf16 v[80:83], v[206:209], v[182:185], v[80:83]
	v_mfma_f32_16x16x32_bf16 v[68:71], v[198:201], v[190:193], v[68:71]
	v_mfma_f32_16x16x32_bf16 v[64:67], v[206:209], v[190:193], v[64:67]
	v_mfma_f32_16x16x32_bf16 v[116:119], v[202:205], v[170:173], v[116:119]
	v_mfma_f32_16x16x32_bf16 v[112:115], v[210:213], v[170:173], v[112:115]
	v_mfma_f32_16x16x32_bf16 v[100:103], v[202:205], v[178:181], v[100:103]
	v_mfma_f32_16x16x32_bf16 v[96:99], v[210:213], v[178:181], v[96:99]
	v_mfma_f32_16x16x32_bf16 v[84:87], v[202:205], v[186:189], v[84:87]
	v_mfma_f32_16x16x32_bf16 v[80:83], v[210:213], v[186:189], v[80:83]
	v_mfma_f32_16x16x32_bf16 v[68:71], v[202:205], v[194:197], v[68:71]
	v_mfma_f32_16x16x32_bf16 v[64:67], v[210:213], v[194:197], v[64:67]
	s_setprio 0
	s_barrier
	global_load_lds_dwordx4 v[214:215], off
	v_lshl_add_u64 v[214:215], s[48:49], 0, v[132:133]
	s_add_i32 m0, s70, 0x2000
	s_nop 0
	global_load_lds_dwordx4 v[214:215], off
	s_mov_b32 m0, s54
	v_lshl_add_u64 v[214:215], s[50:51], 0, v[130:131]
	ds_read_b128 v[166:169], v148 offset:16384
	ds_read_b128 v[170:173], v148 offset:17408
	ds_read_b128 v[174:177], v148 offset:18432
	ds_read_b128 v[178:181], v148 offset:19456
	ds_read_b128 v[182:185], v148 offset:20480
	ds_read_b128 v[186:189], v148 offset:21504
	ds_read_b128 v[190:193], v148 offset:22528
	ds_read_b128 v[194:197], v148 offset:23552
	global_load_lds_dwordx4 v[214:215], off
	v_lshl_add_u64 v[216:217], s[50:51], 0, v[134:135]
	s_mov_b32 m0, s55
	s_nop 0
	global_load_lds_dwordx4 v[216:217], off
	s_add_u32 s70, s48, 0x4000
	s_addc_u32 s71, s49, 0
	s_add_i32 s72, s64, s53
	v_lshl_add_u64 v[250:251], s[70:71], 0, v[128:129]
	s_mov_b32 m0, s72
	s_nop 0
	global_load_lds_dwordx4 v[250:251], off
	v_lshl_add_u64 v[250:251], s[70:71], 0, v[132:133]
	s_add_i32 m0, s72, 0x2000
	s_nop 0
	global_load_lds_dwordx4 v[250:251], off
	s_waitcnt vmcnt(8)
	s_waitcnt lgkmcnt(0)
	s_barrier
; #define PG8_STAGE(bufoff, gbase, voff) do { _Pragma("unroll") for (int _i = 0; _i < 2; ++_i) \
;         __builtin_amdgcn_global_load_lds((const unsigned*)((const char*)(gbase) + (voff)[_i]), (PG8_LAS unsigned*)(lds + (bufoff) + ldsw + _i * 8192), 16, 0, 0); } while (0)
; #define PG8_LDA(dst, b, h) do { _Pragma("unroll") for (int m = 0; m < 4; ++m) _Pragma("unroll") for (int k = 0; k < 2; ++k) dst[m][k] = *(const PG8_LAS bf16x8*)(lds + PG8_SA(b, h) + aoff + m * 2048 + k * 1024); } while (0)
; #define PG8_LDB(dst, b, h) do { _Pragma("unroll") for (int n = 0; n < 2; ++n) _Pragma("unroll") for (int k = 0; k < 2; ++k) dst[n][k] = *(const PG8_LAS bf16x8*)(lds + PG8_SB(b, h) + boff + n * 2048 + k * 1024); } while (0)
; #define PG8_MMA(ai, bj, At, Bt) do { __builtin_amdgcn_s_setprio(1); _Pragma("unroll") for (int m = 0; m < 4; ++m) _Pragma("unroll") for (int n = 0; n < 2; ++n) _Pragma("unroll") for (int k = 0; k < 2; ++k) \
;         acc[ai][bj][m][n] = __builtin_amdgcn_mfma_f32_16x16x32_bf16(Bt[n][k], At[m][k], acc[ai][bj][m][n], 0, 0, 0); __builtin_amdgcn_s_setprio(0); } while (0)
; #define PG8_WAIT_V(n) asm volatile("s_waitcnt vmcnt(" #n ")" ::: "memory")
; #define PG8_WAIT_L(n) asm volatile("s_waitcnt lgkmcnt(" #n ")" ::: "memory")
; #define PG8_BAR __builtin_amdgcn_s_barrier()
; #define PG8_SCHED __builtin_amdgcn_sched_barrier(0)
; template <class Epi, class Sched>
; __device__ __forceinline__ void gemm_phase(PG8_LAS unsigned char* lds, const Gemm g, const Sched& S, const Epi& E) {
;     ...
;             PG8_BAR; PG8_WAIT_L(0); PG8_MMA(1, 0, At, B0); PG8_BAR; PG8_SCHED;
;             PG8_STAGE(PG8_SB(0, 1), b2 + hstepB, voffB);
;             PG8_WAIT_V(6); PG8_BAR; PG8_MMA(1, 1, At, B1); PG8_BAR;
;             PG8_LDB(B0, 1, 0); PG8_SCHED; PG8_LDA(At, 1, 0); PG8_STAGE(PG8_SA(0, 1), a2 + hstep, voffA);
;             PG8_WAIT_L(8); PG8_BAR; PG8_WAIT_L(0); PG8_MMA(0, 0, At, B0); PG8_BAR; PG8_SCHED;
;             PG8_LDB(B1, 1, 1); PG8_STAGE(PG8_SB(1, 0), b3, voffB);
;             PG8_BAR; PG8_WAIT_L(0); PG8_MMA(0, 1, At, B1); PG8_BAR;
	s_setprio 1
	v_mfma_f32_16x16x32_bf16 v[60:63], v[150:153], v[166:169], v[60:63]
	v_mfma_f32_16x16x32_bf16 v[56:59], v[158:161], v[166:169], v[56:59]
	v_mfma_f32_16x16x32_bf16 v[44:47], v[150:153], v[174:177], v[44:47]
	v_mfma_f32_16x16x32_bf16 v[40:43], v[158:161], v[174:177], v[40:43]
	v_mfma_f32_16x16x32_bf16 v[28:31], v[150:153], v[182:185], v[28:31]
	v_mfma_f32_16x16x32_bf16 v[24:27], v[158:161], v[182:185], v[24:27]
	v_mfma_f32_16x16x32_bf16 v[12:15], v[150:153], v[190:193], v[12:15]
	v_mfma_f32_16x16x32_bf16 v[8:11], v[158:161], v[190:193], v[8:11]
	v_mfma_f32_16x16x32_bf16 v[60:63], v[154:157], v[170:173], v[60:63]
	v_mfma_f32_16x16x32_bf16 v[56:59], v[162:165], v[170:173], v[56:59]
	v_mfma_f32_16x16x32_bf16 v[44:47], v[154:157], v[178:181], v[44:47]
	v_mfma_f32_16x16x32_bf16 v[40:43], v[162:165], v[178:181], v[40:43]
	v_mfma_f32_16x16x32_bf16 v[28:31], v[154:157], v[186:189], v[28:31]
	v_mfma_f32_16x16x32_bf16 v[24:27], v[162:165], v[186:189], v[24:27]
	v_mfma_f32_16x16x32_bf16 v[12:15], v[154:157], v[194:197], v[12:15]
	v_mfma_f32_16x16x32_bf16 v[8:11], v[162:165], v[194:197], v[8:11]
	v_mfma_f32_16x16x32_bf16 v[52:55], v[198:201], v[166:169], v[52:55]
	v_mfma_f32_16x16x32_bf16 v[48:51], v[206:209], v[166:169], v[48:51]
	v_mfma_f32_16x16x32_bf16 v[36:39], v[198:201], v[174:177], v[36:39]
	v_mfma_f32_16x16x32_bf16 v[32:35], v[206:209], v[174:177], v[32:35]
	v_mfma_f32_16x16x32_bf16 v[20:23], v[198:201], v[182:185], v[20:23]
	v_mfma_f32_16x16x32_bf16 v[16:19], v[206:209], v[182:185], v[16:19]
	v_mfma_f32_16x16x32_bf16 v[4:7], v[198:201], v[190:193], v[4:7]
	v_mfma_f32_16x16x32_bf16 v[0:3], v[206:209], v[190:193], v[0:3]
	v_mfma_f32_16x16x32_bf16 v[52:55], v[202:205], v[170:173], v[52:55]
	v_mfma_f32_16x16x32_bf16 v[48:51], v[210:213], v[170:173], v[48:51]
	v_mfma_f32_16x16x32_bf16 v[36:39], v[202:205], v[178:181], v[36:39]
	v_mfma_f32_16x16x32_bf16 v[32:35], v[210:213], v[178:181], v[32:35]
	v_mfma_f32_16x16x32_bf16 v[20:23], v[202:205], v[186:189], v[20:23]
	v_mfma_f32_16x16x32_bf16 v[16:19], v[210:213], v[186:189], v[16:19]
	v_mfma_f32_16x16x32_bf16 v[4:7], v[202:205], v[194:197], v[4:7]
	v_mfma_f32_16x16x32_bf16 v[0:3], v[210:213], v[194:197], v[0:3]
	s_setprio 0
	s_barrier
	s_add_i32 s70, 0, 0x18000
	v_add_u32_e32 v162, s70, v145
	ds_read_b128 v[150:153], v162
	ds_read_b128 v[154:157], v162 offset:1024
	ds_read_b128 v[158:161], v162 offset:2048
	ds_read_b128 v[162:165], v162 offset:3072
	s_add_u32 s50, s50, 0x80000
	s_addc_u32 s51, s51, 0
	s_mov_b32 m0, s56
	v_lshl_add_u64 v[198:199], s[50:51], 0, v[130:131]
	ds_read_b128 v[166:169], v148 offset:32768
	ds_read_b128 v[170:173], v148 offset:33792
	ds_read_b128 v[174:177], v148 offset:34816
	ds_read_b128 v[178:181], v148 offset:35840
	ds_read_b128 v[182:185], v148 offset:36864
	ds_read_b128 v[186:189], v148 offset:37888
	ds_read_b128 v[190:193], v148 offset:38912
	ds_read_b128 v[194:197], v148 offset:39936
	global_load_lds_dwordx4 v[198:199], off
	v_lshl_add_u64 v[198:199], s[50:51], 0, v[134:135]
	s_mov_b32 m0, s57
	s_nop 0
	global_load_lds_dwordx4 v[198:199], off
	s_add_i32 s71, 0, 0x1c000
	s_add_u32 s50, s48, 0x8000
	s_addc_u32 s51, s49, 0
	s_add_i32 s70, s70, s53
	v_add_u32_e32 v210, s71, v145
	v_lshl_add_u64 v[218:219], s[50:51], 0, v[128:129]
	s_mov_b32 m0, s70
	ds_read_b128 v[198:201], v210
	ds_read_b128 v[202:205], v210 offset:1024
	ds_read_b128 v[206:209], v210 offset:2048
	ds_read_b128 v[210:213], v210 offset:3072
	s_waitcnt vmcnt(8)
	s_waitcnt lgkmcnt(0)
	s_barrier
	s_setprio 1
	v_mfma_f32_16x16x32_bf16 v[124:127], v[150:153], v[166:169], v[124:127]
	v_mfma_f32_16x16x32_bf16 v[120:123], v[158:161], v[166:169], v[120:123]
	v_mfma_f32_16x16x32_bf16 v[108:111], v[150:153], v[174:177], v[108:111]
	v_mfma_f32_16x16x32_bf16 v[104:107], v[158:161], v[174:177], v[104:107]
	v_mfma_f32_16x16x32_bf16 v[92:95], v[150:153], v[182:185], v[92:95]
	v_mfma_f32_16x16x32_bf16 v[88:91], v[158:161], v[182:185], v[88:91]
	v_mfma_f32_16x16x32_bf16 v[76:79], v[150:153], v[190:193], v[76:79]
	v_mfma_f32_16x16x32_bf16 v[72:75], v[158:161], v[190:193], v[72:75]
	v_mfma_f32_16x16x32_bf16 v[124:127], v[154:157], v[170:173], v[124:127]
	v_mfma_f32_16x16x32_bf16 v[120:123], v[162:165], v[170:173], v[120:123]
	v_mfma_f32_16x16x32_bf16 v[108:111], v[154:157], v[178:181], v[108:111]
	v_mfma_f32_16x16x32_bf16 v[104:107], v[162:165], v[178:181], v[104:107]
	v_mfma_f32_16x16x32_bf16 v[92:95], v[154:157], v[186:189], v[92:95]
	v_mfma_f32_16x16x32_bf16 v[88:91], v[162:165], v[186:189], v[88:91]
	v_mfma_f32_16x16x32_bf16 v[76:79], v[154:157], v[194:197], v[76:79]
	v_mfma_f32_16x16x32_bf16 v[72:75], v[162:165], v[194:197], v[72:75]
	v_mfma_f32_16x16x32_bf16 v[116:119], v[198:201], v[166:169], v[116:119]
	v_mfma_f32_16x16x32_bf16 v[112:115], v[206:209], v[166:169], v[112:115]
	v_mfma_f32_16x16x32_bf16 v[100:103], v[198:201], v[174:177], v[100:103]
	v_mfma_f32_16x16x32_bf16 v[96:99], v[206:209], v[174:177], v[96:99]
	v_mfma_f32_16x16x32_bf16 v[84:87], v[198:201], v[182:185], v[84:87]
	v_mfma_f32_16x16x32_bf16 v[80:83], v[206:209], v[182:185], v[80:83]
	v_mfma_f32_16x16x32_bf16 v[68:71], v[198:201], v[190:193], v[68:71]
	v_mfma_f32_16x16x32_bf16 v[64:67], v[206:209], v[190:193], v[64:67]
	v_mfma_f32_16x16x32_bf16 v[116:119], v[202:205], v[170:173], v[116:119]
	v_mfma_f32_16x16x32_bf16 v[112:115], v[210:213], v[170:173], v[112:115]
	v_mfma_f32_16x16x32_bf16 v[100:103], v[202:205], v[178:181], v[100:103]
	v_mfma_f32_16x16x32_bf16 v[96:99], v[210:213], v[178:181], v[96:99]
	v_mfma_f32_16x16x32_bf16 v[84:87], v[202:205], v[186:189], v[84:87]
	v_mfma_f32_16x16x32_bf16 v[80:83], v[210:213], v[186:189], v[80:83]
	v_mfma_f32_16x16x32_bf16 v[68:71], v[202:205], v[194:197], v[68:71]
	v_mfma_f32_16x16x32_bf16 v[64:67], v[210:213], v[194:197], v[64:67]
	s_setprio 0
	s_barrier
; #define PG8_STAGE(bufoff, gbase, voff) do { _Pragma("unroll") for (int _i = 0; _i < 2; ++_i) \
;         __builtin_amdgcn_global_load_lds((const unsigned*)((const char*)(gbase) + (voff)[_i]), (PG8_LAS unsigned*)(lds + (bufoff) + ldsw + _i * 8192), 16, 0, 0); } while (0)
; #define PG8_LDA(dst, b, h) do { _Pragma("unroll") for (int m = 0; m < 4; ++m) _Pragma("unroll") for (int k = 0; k < 2; ++k) dst[m][k] = *(const PG8_LAS bf16x8*)(lds + PG8_SA(b, h) + aoff + m * 2048 + k * 1024); } while (0)
; #define PG8_LDB(dst, b, h) do { _Pragma("unroll") for (int n = 0; n < 2; ++n) _Pragma("unroll") for (int k = 0; k < 2; ++k) dst[n][k] = *(const PG8_LAS bf16x8*)(lds + PG8_SB(b, h) + boff + n * 2048 + k * 1024); } while (0)
; #define PG8_MMA(ai, bj, At, Bt) do { __builtin_amdgcn_s_setprio(1); _Pragma("unroll") for (int m = 0; m < 4; ++m) _Pragma("unroll") for (int n = 0; n < 2; ++n) _Pragma("unroll") for (int k = 0; k < 2; ++k) \
;         acc[ai][bj][m][n] = __builtin_amdgcn_mfma_f32_16x16x32_bf16(Bt[n][k], At[m][k], acc[ai][bj][m][n], 0, 0, 0); __builtin_amdgcn_s_setprio(0); } while (0)
; #define PG8_WAIT_V(n) asm volatile("s_waitcnt vmcnt(" #n ")" ::: "memory")
; #define PG8_WAIT_L(n) asm volatile("s_waitcnt lgkmcnt(" #n ")" ::: "memory")
; #define PG8_BAR __builtin_amdgcn_s_barrier()
; #define PG8_SCHED __builtin_amdgcn_sched_barrier(0)
; template <class Epi, class Sched>
; __device__ __forceinline__ void gemm_phase(PG8_LAS unsigned char* lds, const Gemm g, const Sched& S, const Epi& E) {
;     ...
;             PG8_LDB(B1, 1, 1); PG8_STAGE(PG8_SB(1, 0), b3, voffB);
;             PG8_BAR; PG8_WAIT_L(0); PG8_MMA(0, 1, At, B1); PG8_BAR;
;             PG8_LDA(At, 1, 1); PG8_STAGE(PG8_SA(1, 0), a3, voffA);
;             PG8_BAR; PG8_WAIT_L(0); PG8_MMA(1, 0, At, B0); PG8_BAR; PG8_SCHED;
;             PG8_STAGE(PG8_SB(1, 1), b3 + hstepB, voffB);
;             PG8_WAIT_V(6); PG8_BAR; PG8_MMA(1, 1, At, B1); PG8_BAR;
;         }
	global_load_lds_dwordx4 v[218:219], off
	v_lshl_add_u64 v[218:219], s[50:51], 0, v[132:133]
	s_add_i32 m0, s70, 0x2000
	s_nop 0
	global_load_lds_dwordx4 v[218:219], off
	s_mov_b32 m0, s59
	v_lshl_add_u64 v[214:215], v[214:215], 0, s[12:13]
	ds_read_b128 v[166:169], v148 offset:49152
	ds_read_b128 v[170:173], v148 offset:50176
	ds_read_b128 v[174:177], v148 offset:51200
	ds_read_b128 v[178:181], v148 offset:52224
	ds_read_b128 v[182:185], v148 offset:53248
	ds_read_b128 v[186:189], v148 offset:54272
	ds_read_b128 v[190:193], v148 offset:55296
	ds_read_b128 v[194:197], v148 offset:56320
	global_load_lds_dwordx4 v[214:215], off
	v_lshl_add_u64 v[214:215], v[216:217], 0, s[12:13]
	s_mov_b32 m0, s60
	s_nop 0
	global_load_lds_dwordx4 v[214:215], off
	s_add_u32 s48, s48, 0xc000
	s_addc_u32 s49, s49, 0
	s_add_i32 s50, s71, s53
	v_lshl_add_u64 v[252:253], s[48:49], 0, v[128:129]
	s_mov_b32 m0, s50
	s_nop 0
	global_load_lds_dwordx4 v[252:253], off
	v_lshl_add_u64 v[252:253], s[48:49], 0, v[132:133]
	s_add_i32 m0, s50, 0x2000
	s_nop 0
	global_load_lds_dwordx4 v[252:253], off
	s_waitcnt vmcnt(8)
	s_waitcnt lgkmcnt(0)
	s_barrier
	s_setprio 1
	v_mfma_f32_16x16x32_bf16 v[60:63], v[150:153], v[166:169], v[60:63]
	v_mfma_f32_16x16x32_bf16 v[56:59], v[158:161], v[166:169], v[56:59]
	v_mfma_f32_16x16x32_bf16 v[44:47], v[150:153], v[174:177], v[44:47]
	v_mfma_f32_16x16x32_bf16 v[40:43], v[158:161], v[174:177], v[40:43]
	v_mfma_f32_16x16x32_bf16 v[28:31], v[150:153], v[182:185], v[28:31]
	v_mfma_f32_16x16x32_bf16 v[24:27], v[158:161], v[182:185], v[24:27]
	v_mfma_f32_16x16x32_bf16 v[12:15], v[150:153], v[190:193], v[12:15]
	v_mfma_f32_16x16x32_bf16 v[8:11], v[158:161], v[190:193], v[8:11]
	v_mfma_f32_16x16x32_bf16 v[60:63], v[154:157], v[170:173], v[60:63]
	v_mfma_f32_16x16x32_bf16 v[56:59], v[162:165], v[170:173], v[56:59]
	v_mfma_f32_16x16x32_bf16 v[44:47], v[154:157], v[178:181], v[44:47]
	v_mfma_f32_16x16x32_bf16 v[40:43], v[162:165], v[178:181], v[40:43]
	v_mfma_f32_16x16x32_bf16 v[28:31], v[154:157], v[186:189], v[28:31]
	v_mfma_f32_16x16x32_bf16 v[24:27], v[162:165], v[186:189], v[24:27]
	v_mfma_f32_16x16x32_bf16 v[12:15], v[154:157], v[194:197], v[12:15]
	v_mfma_f32_16x16x32_bf16 v[8:11], v[162:165], v[194:197], v[8:11]
	v_mfma_f32_16x16x32_bf16 v[52:55], v[198:201], v[166:169], v[52:55]
	v_mfma_f32_16x16x32_bf16 v[48:51], v[206:209], v[166:169], v[48:51]
	v_mfma_f32_16x16x32_bf16 v[36:39], v[198:201], v[174:177], v[36:39]
	v_mfma_f32_16x16x32_bf16 v[32:35], v[206:209], v[174:177], v[32:35]
	v_mfma_f32_16x16x32_bf16 v[20:23], v[198:201], v[182:185], v[20:23]
	v_mfma_f32_16x16x32_bf16 v[16:19], v[206:209], v[182:185], v[16:19]
	v_mfma_f32_16x16x32_bf16 v[4:7], v[198:201], v[190:193], v[4:7]
	v_mfma_f32_16x16x32_bf16 v[0:3], v[206:209], v[190:193], v[0:3]
	v_mfma_f32_16x16x32_bf16 v[52:55], v[202:205], v[170:173], v[52:55]
	v_mfma_f32_16x16x32_bf16 v[48:51], v[210:213], v[170:173], v[48:51]
	v_mfma_f32_16x16x32_bf16 v[36:39], v[202:205], v[178:181], v[36:39]
	v_mfma_f32_16x16x32_bf16 v[32:35], v[210:213], v[178:181], v[32:35]
	v_mfma_f32_16x16x32_bf16 v[20:23], v[202:205], v[186:189], v[20:23]
	v_mfma_f32_16x16x32_bf16 v[16:19], v[210:213], v[186:189], v[16:19]
	v_mfma_f32_16x16x32_bf16 v[4:7], v[202:205], v[194:197], v[4:7]
	v_mfma_f32_16x16x32_bf16 v[0:3], v[210:213], v[194:197], v[0:3]
	s_setprio 0
	s_add_i32 s69, s69, 2
	s_add_u32 s67, s67, 0x10000
	s_addc_u32 s68, s68, 0
	s_add_u32 s6, s6, 0x100
	s_addc_u32 s7, s7, 0
	s_cmp_gt_u32 s69, 29
	s_barrier
	s_cbranch_scc0 .LBB0_280
	s_cmp_eq_u32 s78, 0
	s_cbranch_scc0 .Lhalf_skip_x_2
	s_barrier

; #define PG8_STAGE(bufoff, gbase, voff) do { _Pragma("unroll") for (int _i = 0; _i < 2; ++_i) \
;         __builtin_amdgcn_global_load_lds((const unsigned*)((const char*)(gbase) + (voff)[_i]), (PG8_LAS unsigned*)(lds + (bufoff) + ldsw + _i * 8192), 16, 0, 0); } while (0)
; #define PG8_LDA(dst, b, h) do { _Pragma("unroll") for (int m = 0; m < 4; ++m) _Pragma("unroll") for (int k = 0; k < 2; ++k) dst[m][k] = *(const PG8_LAS bf16x8*)(lds + PG8_SA(b, h) + aoff + m * 2048 + k * 1024); } while (0)
; #define PG8_LDB(dst, b, h) do { _Pragma("unroll") for (int n = 0; n < 2; ++n) _Pragma("unroll") for (int k = 0; k < 2; ++k) dst[n][k] = *(const PG8_LAS bf16x8*)(lds + PG8_SB(b, h) + boff + n * 2048 + k * 1024); } while (0)
; #define PG8_MMA(ai, bj, At, Bt) do { __builtin_amdgcn_s_setprio(1); _Pragma("unroll") for (int m = 0; m < 4; ++m) _Pragma("unroll") for (int n = 0; n < 2; ++n) _Pragma("unroll") for (int k = 0; k < 2; ++k) \
;         acc[ai][bj][m][n] = __builtin_amdgcn_mfma_f32_16x16x32_bf16(Bt[n][k], At[m][k], acc[ai][bj][m][n], 0, 0, 0); __builtin_amdgcn_s_setprio(0); } while (0)
; #define PG8_WAIT_V(n) asm volatile("s_waitcnt vmcnt(" #n ")" ::: "memory")
; #define PG8_WAIT_L(n) asm volatile("s_waitcnt lgkmcnt(" #n ")" ::: "memory")
; template <class Epi, class Sched>
; __device__ __forceinline__ void gemm_phase(PG8_LAS unsigned char* lds, const Gemm g, const Sched& S, const Epi& E) {
;     ...
;             const bool last = (t == nt - 2);
;             const char* a1 = cA + (size_t)(t + 1) * kstep;
;             const char* a2 = last ? nA : cA + (size_t)(t + 2) * kstep; const char* b2 = last ? nB : cB + (size_t)(t + 2) * kstepB;
;             const char* a3 = a2 + kstep; const char* b3 = b2 + kstepB;
;             if (last && has_next) S.a_ready(nxt);
;             PG8_LDB(B0, 0, 0); PG8_SCHED; PG8_LDA(At, 0, 0); PG8_STAGE(PG8_SA(1, 1), a1 + hstep, voffA);
;             PG8_WAIT_L(8); PG8_BAR; PG8_WAIT_L(0); PG8_MMA(0, 0, At, B0); PG8_BAR; PG8_SCHED;
;             PG8_LDB(B1, 0, 1); PG8_STAGE(PG8_SB(0, 0), b2, voffB);
;             PG8_BAR; PG8_WAIT_L(0); PG8_MMA(0, 1, At, B1); PG8_BAR;
;             PG8_LDA(At, 0, 1); PG8_STAGE(PG8_SA(0, 0), a2, voffA);
;             PG8_BAR; PG8_WAIT_L(0); PG8_MMA(1, 0, At, B0); PG8_BAR; PG8_SCHED;
;             PG8_STAGE(PG8_SB(0, 1), b2 + hstepB, voffB);
;             PG8_WAIT_V(6); PG8_BAR; PG8_MMA(1, 1, At, B1); PG8_BAR;
.Lhalf_skip_y_3:
.LBB0_397:
	ds_read_b128 v[142:145], v150
	ds_read_b128 v[154:157], v150 offset:1024
	ds_read_b128 v[158:161], v150 offset:2048
	ds_read_b128 v[162:165], v150 offset:3072
	s_add_u32 s26, s24, 0xfff80080
	s_addc_u32 s27, s25, -1
	s_cmp_eq_u32 s66, 28
	s_cselect_b32 s29, s5, s27
	s_cselect_b32 s28, s15, s26
	s_cselect_b32 s27, s17, s65
	s_cselect_b32 s26, s23, s64
	v_lshl_add_u64 v[198:199], s[24:25], 0, v[138:139]
	s_add_i32 m0, s48, 0xc000
	ds_read_b128 v[166:169], v151
	ds_read_b128 v[170:173], v151 offset:1024
	ds_read_b128 v[174:177], v151 offset:2048
	ds_read_b128 v[178:181], v151 offset:3072
	ds_read_b128 v[182:185], v151 offset:4096
	ds_read_b128 v[186:189], v151 offset:5120
	ds_read_b128 v[190:193], v151 offset:6144
	ds_read_b128 v[194:197], v151 offset:7168
	global_load_lds_dwordx4 v[198:199], off
	v_lshl_add_u64 v[198:199], s[24:25], 0, v[140:141]
	s_add_i32 m0, s48, 0xe000
	s_nop 0
	global_load_lds_dwordx4 v[198:199], off
	s_add_i32 s67, s59, s39
	v_lshl_add_u64 v[214:215], s[26:27], 0, v[128:129]
	s_mov_b32 m0, s67
	ds_read_b128 v[198:201], v152
	ds_read_b128 v[202:205], v152 offset:1024
	ds_read_b128 v[206:209], v152 offset:2048
	ds_read_b128 v[210:213], v152 offset:3072
	s_waitcnt vmcnt(8)
	s_waitcnt lgkmcnt(0)
	s_barrier
	s_setprio 1
	v_mfma_f32_16x16x32_bf16 v[124:127], v[142:145], v[166:169], v[124:127]
	v_mfma_f32_16x16x32_bf16 v[120:123], v[158:161], v[166:169], v[120:123]
	v_mfma_f32_16x16x32_bf16 v[108:111], v[142:145], v[174:177], v[108:111]
	v_mfma_f32_16x16x32_bf16 v[104:107], v[158:161], v[174:177], v[104:107]
	v_mfma_f32_16x16x32_bf16 v[92:95], v[142:145], v[182:185], v[92:95]
	v_mfma_f32_16x16x32_bf16 v[88:91], v[158:161], v[182:185], v[88:91]
	v_mfma_f32_16x16x32_bf16 v[76:79], v[142:145], v[190:193], v[76:79]
	v_mfma_f32_16x16x32_bf16 v[72:75], v[158:161], v[190:193], v[72:75]
	v_mfma_f32_16x16x32_bf16 v[124:127], v[154:157], v[170:173], v[124:127]
	v_mfma_f32_16x16x32_bf16 v[120:123], v[162:165], v[170:173], v[120:123]
	v_mfma_f32_16x16x32_bf16 v[108:111], v[154:157], v[178:181], v[108:111]
	v_mfma_f32_16x16x32_bf16 v[104:107], v[162:165], v[178:181], v[104:107]
	v_mfma_f32_16x16x32_bf16 v[92:95], v[154:157], v[186:189], v[92:95]
	v_mfma_f32_16x16x32_bf16 v[88:91], v[162:165], v[186:189], v[88:91]
	v_mfma_f32_16x16x32_bf16 v[76:79], v[154:157], v[194:197], v[76:79]
	v_mfma_f32_16x16x32_bf16 v[72:75], v[162:165], v[194:197], v[72:75]
	v_mfma_f32_16x16x32_bf16 v[116:119], v[198:201], v[166:169], v[116:119]
	v_mfma_f32_16x16x32_bf16 v[112:115], v[206:209], v[166:169], v[112:115]
	v_mfma_f32_16x16x32_bf16 v[100:103], v[198:201], v[174:177], v[100:103]
	v_mfma_f32_16x16x32_bf16 v[96:99], v[206:209], v[174:177], v[96:99]
	v_mfma_f32_16x16x32_bf16 v[84:87], v[198:201], v[182:185], v[84:87]
	v_mfma_f32_16x16x32_bf16 v[80:83], v[206:209], v[182:185], v[80:83]
	v_mfma_f32_16x16x32_bf16 v[68:71], v[198:201], v[190:193], v[68:71]
	v_mfma_f32_16x16x32_bf16 v[64:67], v[206:209], v[190:193], v[64:67]
	v_mfma_f32_16x16x32_bf16 v[116:119], v[202:205], v[170:173], v[116:119]
	v_mfma_f32_16x16x32_bf16 v[112:115], v[210:213], v[170:173], v[112:115]
	v_mfma_f32_16x16x32_bf16 v[100:103], v[202:205], v[178:181], v[100:103]
	v_mfma_f32_16x16x32_bf16 v[96:99], v[210:213], v[178:181], v[96:99]
	v_mfma_f32_16x16x32_bf16 v[84:87], v[202:205], v[186:189], v[84:87]
	v_mfma_f32_16x16x32_bf16 v[80:83], v[210:213], v[186:189], v[80:83]
	v_mfma_f32_16x16x32_bf16 v[68:71], v[202:205], v[194:197], v[68:71]
	v_mfma_f32_16x16x32_bf16 v[64:67], v[210:213], v[194:197], v[64:67]
	s_setprio 0
	s_barrier
	global_load_lds_dwordx4 v[214:215], off
	v_lshl_add_u64 v[214:215], s[26:27], 0, v[132:133]
	s_add_i32 m0, s67, 0x2000
	s_nop 0
	global_load_lds_dwordx4 v[214:215], off
	s_mov_b32 m0, s48
	v_lshl_add_u64 v[214:215], s[28:29], 0, v[130:131]
	ds_read_b128 v[166:169], v151 offset:16384
	ds_read_b128 v[170:173], v151 offset:17408
	ds_read_b128 v[174:177], v151 offset:18432
	ds_read_b128 v[178:181], v151 offset:19456
	ds_read_b128 v[182:185], v151 offset:20480
	ds_read_b128 v[186:189], v151 offset:21504
	ds_read_b128 v[190:193], v151 offset:22528
	ds_read_b128 v[194:197], v151 offset:23552
	global_load_lds_dwordx4 v[214:215], off
	v_lshl_add_u64 v[216:217], s[28:29], 0, v[134:135]
	s_mov_b32 m0, s49
	s_nop 0
	global_load_lds_dwordx4 v[216:217], off
	s_add_u32 s68, s26, 0x4000
	s_addc_u32 s69, s27, 0
	s_add_i32 s67, s60, s39
	v_lshl_add_u64 v[250:251], s[68:69], 0, v[128:129]
	s_mov_b32 m0, s67
	s_nop 0
	global_load_lds_dwordx4 v[250:251], off
	v_lshl_add_u64 v[250:251], s[68:69], 0, v[132:133]
	s_add_i32 m0, s67, 0x2000
	s_nop 0
	global_load_lds_dwordx4 v[250:251], off
	s_waitcnt vmcnt(8)
	s_waitcnt lgkmcnt(0)
	s_barrier
; #define PG8_STAGE(bufoff, gbase, voff) do { _Pragma("unroll") for (int _i = 0; _i < 2; ++_i) \
;         __builtin_amdgcn_global_load_lds((const unsigned*)((const char*)(gbase) + (voff)[_i]), (PG8_LAS unsigned*)(lds + (bufoff) + ldsw + _i * 8192), 16, 0, 0); } while (0)
; #define PG8_LDA(dst, b, h) do { _Pragma("unroll") for (int m = 0; m < 4; ++m) _Pragma("unroll") for (int k = 0; k < 2; ++k) dst[m][k] = *(const PG8_LAS bf16x8*)(lds + PG8_SA(b, h) + aoff + m * 2048 + k * 1024); } while (0)
; #define PG8_LDB(dst, b, h) do { _Pragma("unroll") for (int n = 0; n < 2; ++n) _Pragma("unroll") for (int k = 0; k < 2; ++k) dst[n][k] = *(const PG8_LAS bf16x8*)(lds + PG8_SB(b, h) + boff + n * 2048 + k * 1024); } while (0)
; #define PG8_MMA(ai, bj, At, Bt) do { __builtin_amdgcn_s_setprio(1); _Pragma("unroll") for (int m = 0; m < 4; ++m) _Pragma("unroll") for (int n = 0; n < 2; ++n) _Pragma("unroll") for (int k = 0; k < 2; ++k) \
;         acc[ai][bj][m][n] = __builtin_amdgcn_mfma_f32_16x16x32_bf16(Bt[n][k], At[m][k], acc[ai][bj][m][n], 0, 0, 0); __builtin_amdgcn_s_setprio(0); } while (0)
; #define PG8_WAIT_V(n) asm volatile("s_waitcnt vmcnt(" #n ")" ::: "memory")
; #define PG8_WAIT_L(n) asm volatile("s_waitcnt lgkmcnt(" #n ")" ::: "memory")
; #define PG8_BAR __builtin_amdgcn_s_barrier()
; #define PG8_SCHED __builtin_amdgcn_sched_barrier(0)
; template <class Epi, class Sched>
; __device__ __forceinline__ void gemm_phase(PG8_LAS unsigned char* lds, const Gemm g, const Sched& S, const Epi& E) {
;     ...
;             PG8_BAR; PG8_WAIT_L(0); PG8_MMA(1, 0, At, B0); PG8_BAR; PG8_SCHED;
;             PG8_STAGE(PG8_SB(0, 1), b2 + hstepB, voffB);
;             PG8_WAIT_V(6); PG8_BAR; PG8_MMA(1, 1, At, B1); PG8_BAR;
;             PG8_LDB(B0, 1, 0); PG8_SCHED; PG8_LDA(At, 1, 0); PG8_STAGE(PG8_SA(0, 1), a2 + hstep, voffA);
;             PG8_WAIT_L(8); PG8_BAR; PG8_WAIT_L(0); PG8_MMA(0, 0, At, B0); PG8_BAR; PG8_SCHED;
;             PG8_LDB(B1, 1, 1); PG8_STAGE(PG8_SB(1, 0), b3, voffB);
;             PG8_BAR; PG8_WAIT_L(0); PG8_MMA(0, 1, At, B1); PG8_BAR;
	s_setprio 1
	v_mfma_f32_16x16x32_bf16 v[60:63], v[142:145], v[166:169], v[60:63]
	v_mfma_f32_16x16x32_bf16 v[56:59], v[158:161], v[166:169], v[56:59]
	v_mfma_f32_16x16x32_bf16 v[44:47], v[142:145], v[174:177], v[44:47]
	v_mfma_f32_16x16x32_bf16 v[40:43], v[158:161], v[174:177], v[40:43]
	v_mfma_f32_16x16x32_bf16 v[28:31], v[142:145], v[182:185], v[28:31]
	v_mfma_f32_16x16x32_bf16 v[24:27], v[158:161], v[182:185], v[24:27]
	v_mfma_f32_16x16x32_bf16 v[12:15], v[142:145], v[190:193], v[12:15]
	v_mfma_f32_16x16x32_bf16 v[8:11], v[158:161], v[190:193], v[8:11]
	v_mfma_f32_16x16x32_bf16 v[60:63], v[154:157], v[170:173], v[60:63]
	v_mfma_f32_16x16x32_bf16 v[56:59], v[162:165], v[170:173], v[56:59]
	v_mfma_f32_16x16x32_bf16 v[44:47], v[154:157], v[178:181], v[44:47]
	v_mfma_f32_16x16x32_bf16 v[40:43], v[162:165], v[178:181], v[40:43]
	v_mfma_f32_16x16x32_bf16 v[28:31], v[154:157], v[186:189], v[28:31]
	v_mfma_f32_16x16x32_bf16 v[24:27], v[162:165], v[186:189], v[24:27]
	v_mfma_f32_16x16x32_bf16 v[12:15], v[154:157], v[194:197], v[12:15]
	v_mfma_f32_16x16x32_bf16 v[8:11], v[162:165], v[194:197], v[8:11]
	v_mfma_f32_16x16x32_bf16 v[52:55], v[198:201], v[166:169], v[52:55]
	v_mfma_f32_16x16x32_bf16 v[48:51], v[206:209], v[166:169], v[48:51]
	v_mfma_f32_16x16x32_bf16 v[36:39], v[198:201], v[174:177], v[36:39]
	v_mfma_f32_16x16x32_bf16 v[32:35], v[206:209], v[174:177], v[32:35]
	v_mfma_f32_16x16x32_bf16 v[20:23], v[198:201], v[182:185], v[20:23]
	v_mfma_f32_16x16x32_bf16 v[16:19], v[206:209], v[182:185], v[16:19]
	v_mfma_f32_16x16x32_bf16 v[4:7], v[198:201], v[190:193], v[4:7]
	v_mfma_f32_16x16x32_bf16 v[0:3], v[206:209], v[190:193], v[0:3]
	v_mfma_f32_16x16x32_bf16 v[52:55], v[202:205], v[170:173], v[52:55]
	v_mfma_f32_16x16x32_bf16 v[48:51], v[210:213], v[170:173], v[48:51]
	v_mfma_f32_16x16x32_bf16 v[36:39], v[202:205], v[178:181], v[36:39]
	v_mfma_f32_16x16x32_bf16 v[32:35], v[210:213], v[178:181], v[32:35]
	v_mfma_f32_16x16x32_bf16 v[20:23], v[202:205], v[186:189], v[20:23]
	v_mfma_f32_16x16x32_bf16 v[16:19], v[210:213], v[186:189], v[16:19]
	v_mfma_f32_16x16x32_bf16 v[4:7], v[202:205], v[194:197], v[4:7]
	v_mfma_f32_16x16x32_bf16 v[0:3], v[210:213], v[194:197], v[0:3]
	s_setprio 0
	s_barrier
	s_add_i32 s67, 0, 0x18000
	v_add_u32_e32 v136, s67, v148
	ds_read_b128 v[142:145], v136
	ds_read_b128 v[154:157], v136 offset:1024
	ds_read_b128 v[158:161], v136 offset:2048
	ds_read_b128 v[162:165], v136 offset:3072
	s_add_u32 s28, s28, 0x80000
	s_addc_u32 s29, s29, 0
	s_mov_b32 m0, s50
	v_lshl_add_u64 v[198:199], s[28:29], 0, v[130:131]
	ds_read_b128 v[166:169], v151 offset:32768
	ds_read_b128 v[170:173], v151 offset:33792
	ds_read_b128 v[174:177], v151 offset:34816
	ds_read_b128 v[178:181], v151 offset:35840
	ds_read_b128 v[182:185], v151 offset:36864
	ds_read_b128 v[186:189], v151 offset:37888
	ds_read_b128 v[190:193], v151 offset:38912
	ds_read_b128 v[194:197], v151 offset:39936
	global_load_lds_dwordx4 v[198:199], off
	v_lshl_add_u64 v[198:199], s[28:29], 0, v[134:135]
	s_mov_b32 m0, s51
	s_nop 0
	global_load_lds_dwordx4 v[198:199], off
	s_add_i32 s68, 0, 0x1c000
	s_add_u32 s28, s26, 0x8000
	s_addc_u32 s29, s27, 0
	s_add_i32 s67, s67, s39
	v_add_u32_e32 v136, s68, v148
	v_lshl_add_u64 v[218:219], s[28:29], 0, v[128:129]
	s_mov_b32 m0, s67
	ds_read_b128 v[198:201], v136
	ds_read_b128 v[202:205], v136 offset:1024
	ds_read_b128 v[206:209], v136 offset:2048
	ds_read_b128 v[210:213], v136 offset:3072
	s_waitcnt vmcnt(8)
	s_waitcnt lgkmcnt(0)
	s_barrier
	s_setprio 1
	v_mfma_f32_16x16x32_bf16 v[124:127], v[142:145], v[166:169], v[124:127]
	v_mfma_f32_16x16x32_bf16 v[120:123], v[158:161], v[166:169], v[120:123]
	v_mfma_f32_16x16x32_bf16 v[108:111], v[142:145], v[174:177], v[108:111]
	v_mfma_f32_16x16x32_bf16 v[104:107], v[158:161], v[174:177], v[104:107]
	v_mfma_f32_16x16x32_bf16 v[92:95], v[142:145], v[182:185], v[92:95]
	v_mfma_f32_16x16x32_bf16 v[88:91], v[158:161], v[182:185], v[88:91]
	v_mfma_f32_16x16x32_bf16 v[76:79], v[142:145], v[190:193], v[76:79]
	v_mfma_f32_16x16x32_bf16 v[72:75], v[158:161], v[190:193], v[72:75]
	v_mfma_f32_16x16x32_bf16 v[124:127], v[154:157], v[170:173], v[124:127]
	v_mfma_f32_16x16x32_bf16 v[120:123], v[162:165], v[170:173], v[120:123]
	v_mfma_f32_16x16x32_bf16 v[108:111], v[154:157], v[178:181], v[108:111]
	v_mfma_f32_16x16x32_bf16 v[104:107], v[162:165], v[178:181], v[104:107]
	v_mfma_f32_16x16x32_bf16 v[92:95], v[154:157], v[186:189], v[92:95]
	v_mfma_f32_16x16x32_bf16 v[88:91], v[162:165], v[186:189], v[88:91]
	v_mfma_f32_16x16x32_bf16 v[76:79], v[154:157], v[194:197], v[76:79]
	v_mfma_f32_16x16x32_bf16 v[72:75], v[162:165], v[194:197], v[72:75]
	v_mfma_f32_16x16x32_bf16 v[116:119], v[198:201], v[166:169], v[116:119]
	v_mfma_f32_16x16x32_bf16 v[112:115], v[206:209], v[166:169], v[112:115]
	v_mfma_f32_16x16x32_bf16 v[100:103], v[198:201], v[174:177], v[100:103]
	v_mfma_f32_16x16x32_bf16 v[96:99], v[206:209], v[174:177], v[96:99]
	v_mfma_f32_16x16x32_bf16 v[84:87], v[198:201], v[182:185], v[84:87]
	v_mfma_f32_16x16x32_bf16 v[80:83], v[206:209], v[182:185], v[80:83]
	v_mfma_f32_16x16x32_bf16 v[68:71], v[198:201], v[190:193], v[68:71]
	v_mfma_f32_16x16x32_bf16 v[64:67], v[206:209], v[190:193], v[64:67]
	v_mfma_f32_16x16x32_bf16 v[116:119], v[202:205], v[170:173], v[116:119]
	v_mfma_f32_16x16x32_bf16 v[112:115], v[210:213], v[170:173], v[112:115]
	v_mfma_f32_16x16x32_bf16 v[100:103], v[202:205], v[178:181], v[100:103]
	v_mfma_f32_16x16x32_bf16 v[96:99], v[210:213], v[178:181], v[96:99]
	v_mfma_f32_16x16x32_bf16 v[84:87], v[202:205], v[186:189], v[84:87]
	v_mfma_f32_16x16x32_bf16 v[80:83], v[210:213], v[186:189], v[80:83]
	v_mfma_f32_16x16x32_bf16 v[68:71], v[202:205], v[194:197], v[68:71]
	v_mfma_f32_16x16x32_bf16 v[64:67], v[210:213], v[194:197], v[64:67]
	s_setprio 0
	s_barrier
; #define PG8_STAGE(bufoff, gbase, voff) do { _Pragma("unroll") for (int _i = 0; _i < 2; ++_i) \
;         __builtin_amdgcn_global_load_lds((const unsigned*)((const char*)(gbase) + (voff)[_i]), (PG8_LAS unsigned*)(lds + (bufoff) + ldsw + _i * 8192), 16, 0, 0); } while (0)
; #define PG8_LDA(dst, b, h) do { _Pragma("unroll") for (int m = 0; m < 4; ++m) _Pragma("unroll") for (int k = 0; k < 2; ++k) dst[m][k] = *(const PG8_LAS bf16x8*)(lds + PG8_SA(b, h) + aoff + m * 2048 + k * 1024); } while (0)
; #define PG8_LDB(dst, b, h) do { _Pragma("unroll") for (int n = 0; n < 2; ++n) _Pragma("unroll") for (int k = 0; k < 2; ++k) dst[n][k] = *(const PG8_LAS bf16x8*)(lds + PG8_SB(b, h) + boff + n * 2048 + k * 1024); } while (0)
; #define PG8_MMA(ai, bj, At, Bt) do { __builtin_amdgcn_s_setprio(1); _Pragma("unroll") for (int m = 0; m < 4; ++m) _Pragma("unroll") for (int n = 0; n < 2; ++n) _Pragma("unroll") for (int k = 0; k < 2; ++k) \
;         acc[ai][bj][m][n] = __builtin_amdgcn_mfma_f32_16x16x32_bf16(Bt[n][k], At[m][k], acc[ai][bj][m][n], 0, 0, 0); __builtin_amdgcn_s_setprio(0); } while (0)
; #define PG8_WAIT_V(n) asm volatile("s_waitcnt vmcnt(" #n ")" ::: "memory")
; #define PG8_WAIT_L(n) asm volatile("s_waitcnt lgkmcnt(" #n ")" ::: "memory")
; #define PG8_BAR __builtin_amdgcn_s_barrier()
; #define PG8_SCHED __builtin_amdgcn_sched_barrier(0)
; template <class Epi, class Sched>
; __device__ __forceinline__ void gemm_phase(PG8_LAS unsigned char* lds, const Gemm g, const Sched& S, const Epi& E) {
;     ...
;             PG8_LDB(B1, 1, 1); PG8_STAGE(PG8_SB(1, 0), b3, voffB);
;             PG8_BAR; PG8_WAIT_L(0); PG8_MMA(0, 1, At, B1); PG8_BAR;
;             PG8_LDA(At, 1, 1); PG8_STAGE(PG8_SA(1, 0), a3, voffA);
;             PG8_BAR; PG8_WAIT_L(0); PG8_MMA(1, 0, At, B0); PG8_BAR; PG8_SCHED;
;             PG8_STAGE(PG8_SB(1, 1), b3 + hstepB, voffB);
;             PG8_WAIT_V(6); PG8_BAR; PG8_MMA(1, 1, At, B1); PG8_BAR;
;         }
	global_load_lds_dwordx4 v[218:219], off
	v_lshl_add_u64 v[218:219], s[28:29], 0, v[132:133]
	s_add_i32 m0, s67, 0x2000
	s_nop 0
	global_load_lds_dwordx4 v[218:219], off
	s_mov_b32 m0, s55
	v_lshl_add_u64 v[214:215], v[214:215], 0, s[10:11]
	ds_read_b128 v[166:169], v151 offset:49152
	ds_read_b128 v[170:173], v151 offset:50176
	ds_read_b128 v[174:177], v151 offset:51200
	ds_read_b128 v[178:181], v151 offset:52224
	ds_read_b128 v[182:185], v151 offset:53248
	ds_read_b128 v[186:189], v151 offset:54272
	ds_read_b128 v[190:193], v151 offset:55296
	ds_read_b128 v[194:197], v151 offset:56320
	global_load_lds_dwordx4 v[214:215], off
	v_lshl_add_u64 v[214:215], v[216:217], 0, s[10:11]
	s_mov_b32 m0, s56
	s_nop 0
	global_load_lds_dwordx4 v[214:215], off
	s_add_u32 s26, s26, 0xc000
	s_addc_u32 s27, s27, 0
	s_add_i32 s28, s68, s39
	v_lshl_add_u64 v[252:253], s[26:27], 0, v[128:129]
	s_mov_b32 m0, s28
	s_nop 0
	global_load_lds_dwordx4 v[252:253], off
	v_lshl_add_u64 v[252:253], s[26:27], 0, v[132:133]
	s_add_i32 m0, s28, 0x2000
	s_nop 0
	global_load_lds_dwordx4 v[252:253], off
	s_waitcnt vmcnt(8)
	s_waitcnt lgkmcnt(0)
	s_barrier
	s_setprio 1
	v_mfma_f32_16x16x32_bf16 v[60:63], v[142:145], v[166:169], v[60:63]
	v_mfma_f32_16x16x32_bf16 v[56:59], v[158:161], v[166:169], v[56:59]
	v_mfma_f32_16x16x32_bf16 v[44:47], v[142:145], v[174:177], v[44:47]
	v_mfma_f32_16x16x32_bf16 v[40:43], v[158:161], v[174:177], v[40:43]
	v_mfma_f32_16x16x32_bf16 v[28:31], v[142:145], v[182:185], v[28:31]
	v_mfma_f32_16x16x32_bf16 v[24:27], v[158:161], v[182:185], v[24:27]
	v_mfma_f32_16x16x32_bf16 v[12:15], v[142:145], v[190:193], v[12:15]
	v_mfma_f32_16x16x32_bf16 v[8:11], v[158:161], v[190:193], v[8:11]
	v_mfma_f32_16x16x32_bf16 v[60:63], v[154:157], v[170:173], v[60:63]
	v_mfma_f32_16x16x32_bf16 v[56:59], v[162:165], v[170:173], v[56:59]
	v_mfma_f32_16x16x32_bf16 v[44:47], v[154:157], v[178:181], v[44:47]
	v_mfma_f32_16x16x32_bf16 v[40:43], v[162:165], v[178:181], v[40:43]
	v_mfma_f32_16x16x32_bf16 v[28:31], v[154:157], v[186:189], v[28:31]
	v_mfma_f32_16x16x32_bf16 v[24:27], v[162:165], v[186:189], v[24:27]
	v_mfma_f32_16x16x32_bf16 v[12:15], v[154:157], v[194:197], v[12:15]
	v_mfma_f32_16x16x32_bf16 v[8:11], v[162:165], v[194:197], v[8:11]
	v_mfma_f32_16x16x32_bf16 v[52:55], v[198:201], v[166:169], v[52:55]
	v_mfma_f32_16x16x32_bf16 v[48:51], v[206:209], v[166:169], v[48:51]
	v_mfma_f32_16x16x32_bf16 v[36:39], v[198:201], v[174:177], v[36:39]
	v_mfma_f32_16x16x32_bf16 v[32:35], v[206:209], v[174:177], v[32:35]
	v_mfma_f32_16x16x32_bf16 v[20:23], v[198:201], v[182:185], v[20:23]
	v_mfma_f32_16x16x32_bf16 v[16:19], v[206:209], v[182:185], v[16:19]
	v_mfma_f32_16x16x32_bf16 v[4:7], v[198:201], v[190:193], v[4:7]
	v_mfma_f32_16x16x32_bf16 v[0:3], v[206:209], v[190:193], v[0:3]
	v_mfma_f32_16x16x32_bf16 v[52:55], v[202:205], v[170:173], v[52:55]
	v_mfma_f32_16x16x32_bf16 v[48:51], v[210:213], v[170:173], v[48:51]
	v_mfma_f32_16x16x32_bf16 v[36:39], v[202:205], v[178:181], v[36:39]
	v_mfma_f32_16x16x32_bf16 v[32:35], v[210:213], v[178:181], v[32:35]
	v_mfma_f32_16x16x32_bf16 v[20:23], v[202:205], v[186:189], v[20:23]
	v_mfma_f32_16x16x32_bf16 v[16:19], v[210:213], v[186:189], v[16:19]
	v_mfma_f32_16x16x32_bf16 v[4:7], v[202:205], v[194:197], v[4:7]
	v_mfma_f32_16x16x32_bf16 v[0:3], v[210:213], v[194:197], v[0:3]
	s_setprio 0
	s_add_i32 s66, s66, 2
	s_add_u32 s64, s64, 0x10000
	s_addc_u32 s65, s65, 0
	s_add_u32 s24, s24, 0x100
	s_addc_u32 s25, s25, 0
	s_cmp_gt_u32 s66, 29
	s_barrier
	s_cbranch_scc0 .LBB0_397
	s_cmp_eq_u32 s78, 0
	s_cbranch_scc0 .Lhalf_skip_x_3
	s_barrier

; #define PG8_STAGE(bufoff, gbase, voff) do { _Pragma("unroll") for (int _i = 0; _i < 2; ++_i) \
;         __builtin_amdgcn_global_load_lds((const unsigned*)((const char*)(gbase) + (voff)[_i]), (PG8_LAS unsigned*)(lds + (bufoff) + ldsw + _i * 8192), 16, 0, 0); } while (0)
; #define PG8_LDA(dst, b, h) do { _Pragma("unroll") for (int m = 0; m < 4; ++m) _Pragma("unroll") for (int k = 0; k < 2; ++k) dst[m][k] = *(const PG8_LAS bf16x8*)(lds + PG8_SA(b, h) + aoff + m * 2048 + k * 1024); } while (0)
; #define PG8_LDB(dst, b, h) do { _Pragma("unroll") for (int n = 0; n < 2; ++n) _Pragma("unroll") for (int k = 0; k < 2; ++k) dst[n][k] = *(const PG8_LAS bf16x8*)(lds + PG8_SB(b, h) + boff + n * 2048 + k * 1024); } while (0)
; #define PG8_MMA(ai, bj, At, Bt) do { __builtin_amdgcn_s_setprio(1); _Pragma("unroll") for (int m = 0; m < 4; ++m) _Pragma("unroll") for (int n = 0; n < 2; ++n) _Pragma("unroll") for (int k = 0; k < 2; ++k) \
;         acc[ai][bj][m][n] = __builtin_amdgcn_mfma_f32_16x16x32_bf16(Bt[n][k], At[m][k], acc[ai][bj][m][n], 0, 0, 0); __builtin_amdgcn_s_setprio(0); } while (0)
; #define PG8_WAIT_V(n) asm volatile("s_waitcnt vmcnt(" #n ")" ::: "memory")
; #define PG8_WAIT_L(n) asm volatile("s_waitcnt lgkmcnt(" #n ")" ::: "memory")
; template <class Epi, class Sched>
; __device__ __forceinline__ void gemm_phase(PG8_LAS unsigned char* lds, const Gemm g, const Sched& S, const Epi& E) {
;     ...
;             const bool last = (t == nt - 2);
;             const char* a1 = cA + (size_t)(t + 1) * kstep;
;             const char* a2 = last ? nA : cA + (size_t)(t + 2) * kstep; const char* b2 = last ? nB : cB + (size_t)(t + 2) * kstepB;
;             const char* a3 = a2 + kstep; const char* b3 = b2 + kstepB;
;             if (last && has_next) S.a_ready(nxt);
;             PG8_LDB(B0, 0, 0); PG8_SCHED; PG8_LDA(At, 0, 0); PG8_STAGE(PG8_SA(1, 1), a1 + hstep, voffA);
;             PG8_WAIT_L(8); PG8_BAR; PG8_WAIT_L(0); PG8_MMA(0, 0, At, B0); PG8_BAR; PG8_SCHED;
;             PG8_LDB(B1, 0, 1); PG8_STAGE(PG8_SB(0, 0), b2, voffB);
;             PG8_BAR; PG8_WAIT_L(0); PG8_MMA(0, 1, At, B1); PG8_BAR;
;             PG8_LDA(At, 0, 1); PG8_STAGE(PG8_SA(0, 0), a2, voffA);
;             PG8_BAR; PG8_WAIT_L(0); PG8_MMA(1, 0, At, B0); PG8_BAR; PG8_SCHED;
;             PG8_STAGE(PG8_SB(0, 1), b2 + hstepB, voffB);
;             PG8_WAIT_V(6); PG8_BAR; PG8_MMA(1, 1, At, B1); PG8_BAR;
.Lhalf_skip_y_4:
.LBB0_613:
	v_add_u32_e32 v1, s57, v231
	ds_read_b128 v[132:135], v1
	ds_read_b128 v[136:139], v1 offset:1024
	ds_read_b128 v[140:143], v1 offset:2048
	ds_read_b128 v[144:147], v1 offset:3072
	s_add_u32 s26, s24, 0xfffc0080
	s_addc_u32 s27, s25, -1
	s_cmp_eq_u32 s63, 12
	s_cselect_b32 s29, s7, s27
	s_cselect_b32 s28, s15, s26
	s_cselect_b32 s27, s17, s62
	s_cselect_b32 s26, s19, s61
	v_lshl_add_u64 v[2:3], s[24:25], 0, v[204:205]
	s_add_i32 m0, s49, 0xc000
	ds_read_b128 v[148:151], v233
	ds_read_b128 v[152:155], v233 offset:1024
	ds_read_b128 v[156:159], v233 offset:2048
	ds_read_b128 v[160:163], v233 offset:3072
	ds_read_b128 v[164:167], v233 offset:4096
	ds_read_b128 v[168:171], v233 offset:5120
	ds_read_b128 v[172:175], v233 offset:6144
	ds_read_b128 v[176:179], v233 offset:7168
	global_load_lds_dwordx4 v[2:3], off
	v_lshl_add_u64 v[2:3], s[24:25], 0, v[206:207]
	s_add_i32 m0, s49, 0xe000
	s_nop 0
	global_load_lds_dwordx4 v[2:3], off
	s_add_i32 s64, s57, s48
	v_add_u32_e32 v1, s58, v231
	v_lshl_add_u64 v[250:251], s[26:27], 0, v[196:197]
	s_mov_b32 m0, s64
	ds_read_b128 v[180:183], v1
	ds_read_b128 v[184:187], v1 offset:1024
	ds_read_b128 v[188:191], v1 offset:2048
	ds_read_b128 v[192:195], v1 offset:3072
	s_waitcnt vmcnt(8)
	s_waitcnt lgkmcnt(0)
	s_barrier
	s_setprio 1
	v_mfma_f32_16x16x32_bf16 v[2:5], v[132:135], v[148:151], v[4:7]
	v_mfma_f32_16x16x32_bf16 v[6:9], v[140:143], v[148:151], v[8:11]
	v_mfma_f32_16x16x32_bf16 v[32:35], v[132:135], v[156:159], v[32:35]
	v_mfma_f32_16x16x32_bf16 v[28:31], v[140:143], v[156:159], v[28:31]
	v_mfma_f32_16x16x32_bf16 v[24:27], v[132:135], v[164:167], v[24:27]
	v_mfma_f32_16x16x32_bf16 v[20:23], v[140:143], v[164:167], v[20:23]
	v_mfma_f32_16x16x32_bf16 v[16:19], v[132:135], v[172:175], v[16:19]
	v_mfma_f32_16x16x32_bf16 v[12:15], v[140:143], v[172:175], v[12:15]
	v_mfma_f32_16x16x32_bf16 v[2:5], v[136:139], v[152:155], v[2:5]
	v_mfma_f32_16x16x32_bf16 v[8:11], v[144:147], v[152:155], v[6:9]
	v_mfma_f32_16x16x32_bf16 v[32:35], v[136:139], v[160:163], v[32:35]
	v_mfma_f32_16x16x32_bf16 v[28:31], v[144:147], v[160:163], v[28:31]
	v_mfma_f32_16x16x32_bf16 v[24:27], v[136:139], v[168:171], v[24:27]
	v_mfma_f32_16x16x32_bf16 v[20:23], v[144:147], v[168:171], v[20:23]
	v_mfma_f32_16x16x32_bf16 v[16:19], v[136:139], v[176:179], v[16:19]
	v_mfma_f32_16x16x32_bf16 v[12:15], v[144:147], v[176:179], v[12:15]
	v_mfma_f32_16x16x32_bf16 v[128:131], v[180:183], v[148:151], v[128:131]
	v_mfma_f32_16x16x32_bf16 v[124:127], v[188:191], v[148:151], v[124:127]
	v_mfma_f32_16x16x32_bf16 v[120:123], v[180:183], v[156:159], v[120:123]
	v_mfma_f32_16x16x32_bf16 v[116:119], v[188:191], v[156:159], v[116:119]
	v_mfma_f32_16x16x32_bf16 v[112:115], v[180:183], v[164:167], v[112:115]
	v_mfma_f32_16x16x32_bf16 v[108:111], v[188:191], v[164:167], v[108:111]
	v_mfma_f32_16x16x32_bf16 v[104:107], v[180:183], v[172:175], v[104:107]
	v_mfma_f32_16x16x32_bf16 v[100:103], v[188:191], v[172:175], v[100:103]
	v_mfma_f32_16x16x32_bf16 v[128:131], v[184:187], v[152:155], v[128:131]
	v_mfma_f32_16x16x32_bf16 v[124:127], v[192:195], v[152:155], v[124:127]
	v_mfma_f32_16x16x32_bf16 v[120:123], v[184:187], v[160:163], v[120:123]
	v_mfma_f32_16x16x32_bf16 v[116:119], v[192:195], v[160:163], v[116:119]
	v_mfma_f32_16x16x32_bf16 v[112:115], v[184:187], v[168:171], v[112:115]
	v_mfma_f32_16x16x32_bf16 v[108:111], v[192:195], v[168:171], v[108:111]
	v_mfma_f32_16x16x32_bf16 v[104:107], v[184:187], v[176:179], v[104:107]
	v_mfma_f32_16x16x32_bf16 v[100:103], v[192:195], v[176:179], v[100:103]
	s_setprio 0
	s_barrier
	global_load_lds_dwordx4 v[250:251], off
	v_lshl_add_u64 v[250:251], s[26:27], 0, v[200:201]
	s_add_i32 m0, s64, 0x2000
	s_nop 0
	global_load_lds_dwordx4 v[250:251], off
	s_mov_b32 m0, s49
	v_lshl_add_u64 v[212:213], s[28:29], 0, v[198:199]
	ds_read_b128 v[148:151], v233 offset:16384
	ds_read_b128 v[152:155], v233 offset:17408
	ds_read_b128 v[156:159], v233 offset:18432
	ds_read_b128 v[160:163], v233 offset:19456
	ds_read_b128 v[164:167], v233 offset:20480
	ds_read_b128 v[168:171], v233 offset:21504
	ds_read_b128 v[172:175], v233 offset:22528
	ds_read_b128 v[176:179], v233 offset:23552
	global_load_lds_dwordx4 v[212:213], off
	v_lshl_add_u64 v[214:215], s[28:29], 0, v[202:203]
	s_mov_b32 m0, s50
	s_nop 0
	global_load_lds_dwordx4 v[214:215], off
	s_add_u32 s64, s26, 0x4000
	s_addc_u32 s65, s27, 0
	s_add_i32 s66, s58, s48
	v_lshl_add_u64 v[6:7], s[64:65], 0, v[196:197]
	s_mov_b32 m0, s66
	s_nop 0
	global_load_lds_dwordx4 v[6:7], off
	v_lshl_add_u64 v[6:7], s[64:65], 0, v[200:201]
	s_add_i32 m0, s66, 0x2000
	s_nop 0
	global_load_lds_dwordx4 v[6:7], off
	s_waitcnt vmcnt(8)
	s_waitcnt lgkmcnt(0)
	s_barrier
; #define PG8_STAGE(bufoff, gbase, voff) do { _Pragma("unroll") for (int _i = 0; _i < 2; ++_i) \
;         __builtin_amdgcn_global_load_lds((const unsigned*)((const char*)(gbase) + (voff)[_i]), (PG8_LAS unsigned*)(lds + (bufoff) + ldsw + _i * 8192), 16, 0, 0); } while (0)
; #define PG8_LDA(dst, b, h) do { _Pragma("unroll") for (int m = 0; m < 4; ++m) _Pragma("unroll") for (int k = 0; k < 2; ++k) dst[m][k] = *(const PG8_LAS bf16x8*)(lds + PG8_SA(b, h) + aoff + m * 2048 + k * 1024); } while (0)
; #define PG8_LDB(dst, b, h) do { _Pragma("unroll") for (int n = 0; n < 2; ++n) _Pragma("unroll") for (int k = 0; k < 2; ++k) dst[n][k] = *(const PG8_LAS bf16x8*)(lds + PG8_SB(b, h) + boff + n * 2048 + k * 1024); } while (0)
; #define PG8_MMA(ai, bj, At, Bt) do { __builtin_amdgcn_s_setprio(1); _Pragma("unroll") for (int m = 0; m < 4; ++m) _Pragma("unroll") for (int n = 0; n < 2; ++n) _Pragma("unroll") for (int k = 0; k < 2; ++k) \
;         acc[ai][bj][m][n] = __builtin_amdgcn_mfma_f32_16x16x32_bf16(Bt[n][k], At[m][k], acc[ai][bj][m][n], 0, 0, 0); __builtin_amdgcn_s_setprio(0); } while (0)
; #define PG8_WAIT_V(n) asm volatile("s_waitcnt vmcnt(" #n ")" ::: "memory")
; #define PG8_WAIT_L(n) asm volatile("s_waitcnt lgkmcnt(" #n ")" ::: "memory")
; #define PG8_BAR __builtin_amdgcn_s_barrier()
; #define PG8_SCHED __builtin_amdgcn_sched_barrier(0)
; template <class Epi, class Sched>
; __device__ __forceinline__ void gemm_phase(PG8_LAS unsigned char* lds, const Gemm g, const Sched& S, const Epi& E) {
;     ...
;             PG8_BAR; PG8_WAIT_L(0); PG8_MMA(1, 0, At, B0); PG8_BAR; PG8_SCHED;
;             PG8_STAGE(PG8_SB(0, 1), b2 + hstepB, voffB);
;             PG8_WAIT_V(6); PG8_BAR; PG8_MMA(1, 1, At, B1); PG8_BAR;
;             PG8_LDB(B0, 1, 0); PG8_SCHED; PG8_LDA(At, 1, 0); PG8_STAGE(PG8_SA(0, 1), a2 + hstep, voffA);
;             PG8_WAIT_L(8); PG8_BAR; PG8_WAIT_L(0); PG8_MMA(0, 0, At, B0); PG8_BAR; PG8_SCHED;
;             PG8_LDB(B1, 1, 1); PG8_STAGE(PG8_SB(1, 0), b3, voffB);
;             PG8_BAR; PG8_WAIT_L(0); PG8_MMA(0, 1, At, B1); PG8_BAR;
	s_setprio 1
	v_mfma_f32_16x16x32_bf16 v[96:99], v[132:135], v[148:151], v[96:99]
	v_mfma_f32_16x16x32_bf16 v[92:95], v[140:143], v[148:151], v[92:95]
	v_mfma_f32_16x16x32_bf16 v[88:91], v[132:135], v[156:159], v[88:91]
	v_mfma_f32_16x16x32_bf16 v[84:87], v[140:143], v[156:159], v[84:87]
	v_mfma_f32_16x16x32_bf16 v[80:83], v[132:135], v[164:167], v[80:83]
	v_mfma_f32_16x16x32_bf16 v[76:79], v[140:143], v[164:167], v[76:79]
	v_mfma_f32_16x16x32_bf16 v[72:75], v[132:135], v[172:175], v[72:75]
	v_mfma_f32_16x16x32_bf16 v[68:71], v[140:143], v[172:175], v[68:71]
	v_mfma_f32_16x16x32_bf16 v[96:99], v[136:139], v[152:155], v[96:99]
	v_mfma_f32_16x16x32_bf16 v[92:95], v[144:147], v[152:155], v[92:95]
	v_mfma_f32_16x16x32_bf16 v[88:91], v[136:139], v[160:163], v[88:91]
	v_mfma_f32_16x16x32_bf16 v[84:87], v[144:147], v[160:163], v[84:87]
	v_mfma_f32_16x16x32_bf16 v[80:83], v[136:139], v[168:171], v[80:83]
	v_mfma_f32_16x16x32_bf16 v[76:79], v[144:147], v[168:171], v[76:79]
	v_mfma_f32_16x16x32_bf16 v[72:75], v[136:139], v[176:179], v[72:75]
	v_mfma_f32_16x16x32_bf16 v[68:71], v[144:147], v[176:179], v[68:71]
	v_mfma_f32_16x16x32_bf16 v[64:67], v[180:183], v[148:151], v[64:67]
	v_mfma_f32_16x16x32_bf16 v[60:63], v[188:191], v[148:151], v[60:63]
	v_mfma_f32_16x16x32_bf16 v[56:59], v[180:183], v[156:159], v[56:59]
	v_mfma_f32_16x16x32_bf16 v[52:55], v[188:191], v[156:159], v[52:55]
	v_mfma_f32_16x16x32_bf16 v[48:51], v[180:183], v[164:167], v[48:51]
	v_mfma_f32_16x16x32_bf16 v[44:47], v[188:191], v[164:167], v[44:47]
	v_mfma_f32_16x16x32_bf16 v[40:43], v[180:183], v[172:175], v[40:43]
	v_mfma_f32_16x16x32_bf16 v[36:39], v[188:191], v[172:175], v[36:39]
	v_mfma_f32_16x16x32_bf16 v[64:67], v[184:187], v[152:155], v[64:67]
	v_mfma_f32_16x16x32_bf16 v[60:63], v[192:195], v[152:155], v[60:63]
	v_mfma_f32_16x16x32_bf16 v[56:59], v[184:187], v[160:163], v[56:59]
	v_mfma_f32_16x16x32_bf16 v[52:55], v[192:195], v[160:163], v[52:55]
	v_mfma_f32_16x16x32_bf16 v[48:51], v[184:187], v[168:171], v[48:51]
	v_mfma_f32_16x16x32_bf16 v[44:47], v[192:195], v[168:171], v[44:47]
	v_mfma_f32_16x16x32_bf16 v[40:43], v[184:187], v[176:179], v[40:43]
	v_mfma_f32_16x16x32_bf16 v[36:39], v[192:195], v[176:179], v[36:39]
	s_setprio 0
	s_barrier
	s_add_i32 s64, 0, 0x18000
	v_add_u32_e32 v1, s64, v231
	ds_read_b128 v[132:135], v1
	ds_read_b128 v[136:139], v1 offset:1024
	ds_read_b128 v[140:143], v1 offset:2048
	ds_read_b128 v[144:147], v1 offset:3072
	s_add_u32 s28, s28, 0x40000
	s_addc_u32 s29, s29, 0
	s_mov_b32 m0, s51
	v_lshl_add_u64 v[6:7], s[28:29], 0, v[198:199]
	ds_read_b128 v[148:151], v233 offset:32768
	ds_read_b128 v[152:155], v233 offset:33792
	ds_read_b128 v[156:159], v233 offset:34816
	ds_read_b128 v[160:163], v233 offset:35840
	ds_read_b128 v[164:167], v233 offset:36864
	ds_read_b128 v[168:171], v233 offset:37888
	ds_read_b128 v[172:175], v233 offset:38912
	ds_read_b128 v[176:179], v233 offset:39936
	global_load_lds_dwordx4 v[6:7], off
	v_lshl_add_u64 v[6:7], s[28:29], 0, v[202:203]
	s_mov_b32 m0, s52
	s_nop 0
	global_load_lds_dwordx4 v[6:7], off
	s_add_i32 s65, 0, 0x1c000
	s_add_u32 s28, s26, 0x8000
	s_addc_u32 s29, s27, 0
	s_add_i32 s64, s64, s48
	v_add_u32_e32 v1, s65, v231
	v_lshl_add_u64 v[252:253], s[28:29], 0, v[196:197]
	s_mov_b32 m0, s64
	ds_read_b128 v[180:183], v1
	ds_read_b128 v[184:187], v1 offset:1024
	ds_read_b128 v[188:191], v1 offset:2048
	ds_read_b128 v[192:195], v1 offset:3072
	s_waitcnt vmcnt(8)
	s_waitcnt lgkmcnt(0)
	s_barrier
	s_setprio 1
	v_mfma_f32_16x16x32_bf16 v[2:5], v[132:135], v[148:151], v[2:5]
	v_mfma_f32_16x16x32_bf16 v[8:11], v[140:143], v[148:151], v[8:11]
	v_mfma_f32_16x16x32_bf16 v[32:35], v[132:135], v[156:159], v[32:35]
	v_mfma_f32_16x16x32_bf16 v[28:31], v[140:143], v[156:159], v[28:31]
	v_mfma_f32_16x16x32_bf16 v[24:27], v[132:135], v[164:167], v[24:27]
	v_mfma_f32_16x16x32_bf16 v[20:23], v[140:143], v[164:167], v[20:23]
	v_mfma_f32_16x16x32_bf16 v[16:19], v[132:135], v[172:175], v[16:19]
	v_mfma_f32_16x16x32_bf16 v[12:15], v[140:143], v[172:175], v[12:15]
	v_mfma_f32_16x16x32_bf16 v[4:7], v[136:139], v[152:155], v[2:5]
	v_mfma_f32_16x16x32_bf16 v[8:11], v[144:147], v[152:155], v[8:11]
	v_mfma_f32_16x16x32_bf16 v[32:35], v[136:139], v[160:163], v[32:35]
	v_mfma_f32_16x16x32_bf16 v[28:31], v[144:147], v[160:163], v[28:31]
	v_mfma_f32_16x16x32_bf16 v[24:27], v[136:139], v[168:171], v[24:27]
	v_mfma_f32_16x16x32_bf16 v[20:23], v[144:147], v[168:171], v[20:23]
	v_mfma_f32_16x16x32_bf16 v[16:19], v[136:139], v[176:179], v[16:19]
	v_mfma_f32_16x16x32_bf16 v[12:15], v[144:147], v[176:179], v[12:15]
	v_mfma_f32_16x16x32_bf16 v[128:131], v[180:183], v[148:151], v[128:131]
	v_mfma_f32_16x16x32_bf16 v[124:127], v[188:191], v[148:151], v[124:127]
	v_mfma_f32_16x16x32_bf16 v[120:123], v[180:183], v[156:159], v[120:123]
	v_mfma_f32_16x16x32_bf16 v[116:119], v[188:191], v[156:159], v[116:119]
	v_mfma_f32_16x16x32_bf16 v[112:115], v[180:183], v[164:167], v[112:115]
	v_mfma_f32_16x16x32_bf16 v[108:111], v[188:191], v[164:167], v[108:111]
	v_mfma_f32_16x16x32_bf16 v[104:107], v[180:183], v[172:175], v[104:107]
	v_mfma_f32_16x16x32_bf16 v[100:103], v[188:191], v[172:175], v[100:103]
	v_mfma_f32_16x16x32_bf16 v[128:131], v[184:187], v[152:155], v[128:131]
	v_mfma_f32_16x16x32_bf16 v[124:127], v[192:195], v[152:155], v[124:127]
	v_mfma_f32_16x16x32_bf16 v[120:123], v[184:187], v[160:163], v[120:123]
	v_mfma_f32_16x16x32_bf16 v[116:119], v[192:195], v[160:163], v[116:119]
	v_mfma_f32_16x16x32_bf16 v[112:115], v[184:187], v[168:171], v[112:115]
	v_mfma_f32_16x16x32_bf16 v[108:111], v[192:195], v[168:171], v[108:111]
	v_mfma_f32_16x16x32_bf16 v[104:107], v[184:187], v[176:179], v[104:107]
	v_mfma_f32_16x16x32_bf16 v[100:103], v[192:195], v[176:179], v[100:103]
	s_setprio 0
	s_barrier
; #define PG8_STAGE(bufoff, gbase, voff) do { _Pragma("unroll") for (int _i = 0; _i < 2; ++_i) \
;         __builtin_amdgcn_global_load_lds((const unsigned*)((const char*)(gbase) + (voff)[_i]), (PG8_LAS unsigned*)(lds + (bufoff) + ldsw + _i * 8192), 16, 0, 0); } while (0)
; #define PG8_LDA(dst, b, h) do { _Pragma("unroll") for (int m = 0; m < 4; ++m) _Pragma("unroll") for (int k = 0; k < 2; ++k) dst[m][k] = *(const PG8_LAS bf16x8*)(lds + PG8_SA(b, h) + aoff + m * 2048 + k * 1024); } while (0)
; #define PG8_LDB(dst, b, h) do { _Pragma("unroll") for (int n = 0; n < 2; ++n) _Pragma("unroll") for (int k = 0; k < 2; ++k) dst[n][k] = *(const PG8_LAS bf16x8*)(lds + PG8_SB(b, h) + boff + n * 2048 + k * 1024); } while (0)
; #define PG8_MMA(ai, bj, At, Bt) do { __builtin_amdgcn_s_setprio(1); _Pragma("unroll") for (int m = 0; m < 4; ++m) _Pragma("unroll") for (int n = 0; n < 2; ++n) _Pragma("unroll") for (int k = 0; k < 2; ++k) \
;         acc[ai][bj][m][n] = __builtin_amdgcn_mfma_f32_16x16x32_bf16(Bt[n][k], At[m][k], acc[ai][bj][m][n], 0, 0, 0); __builtin_amdgcn_s_setprio(0); } while (0)
; #define PG8_WAIT_V(n) asm volatile("s_waitcnt vmcnt(" #n ")" ::: "memory")
; #define PG8_WAIT_L(n) asm volatile("s_waitcnt lgkmcnt(" #n ")" ::: "memory")
; #define PG8_BAR __builtin_amdgcn_s_barrier()
; #define PG8_SCHED __builtin_amdgcn_sched_barrier(0)
; template <class Epi, class Sched>
; __device__ __forceinline__ void gemm_phase(PG8_LAS unsigned char* lds, const Gemm g, const Sched& S, const Epi& E) {
;     ...
;             PG8_LDB(B1, 1, 1); PG8_STAGE(PG8_SB(1, 0), b3, voffB);
;             PG8_BAR; PG8_WAIT_L(0); PG8_MMA(0, 1, At, B1); PG8_BAR;
;             PG8_LDA(At, 1, 1); PG8_STAGE(PG8_SA(1, 0), a3, voffA);
;             PG8_BAR; PG8_WAIT_L(0); PG8_MMA(1, 0, At, B0); PG8_BAR; PG8_SCHED;
;             PG8_STAGE(PG8_SB(1, 1), b3 + hstepB, voffB);
;             PG8_WAIT_V(6); PG8_BAR; PG8_MMA(1, 1, At, B1); PG8_BAR;
;         }
	global_load_lds_dwordx4 v[252:253], off
	v_lshl_add_u64 v[252:253], s[28:29], 0, v[200:201]
	s_add_i32 m0, s64, 0x2000
	s_nop 0
	global_load_lds_dwordx4 v[252:253], off
	s_mov_b32 m0, s55
	v_lshl_add_u64 v[2:3], v[212:213], 0, s[12:13]
	ds_read_b128 v[148:151], v233 offset:49152
	ds_read_b128 v[152:155], v233 offset:50176
	ds_read_b128 v[156:159], v233 offset:51200
	ds_read_b128 v[160:163], v233 offset:52224
	ds_read_b128 v[164:167], v233 offset:53248
	ds_read_b128 v[168:171], v233 offset:54272
	ds_read_b128 v[172:175], v233 offset:55296
	ds_read_b128 v[176:179], v233 offset:56320
	global_load_lds_dwordx4 v[2:3], off
	v_lshl_add_u64 v[2:3], v[214:215], 0, s[12:13]
	s_mov_b32 m0, s56
	s_nop 0
	global_load_lds_dwordx4 v[2:3], off
	s_add_u32 s26, s26, 0xc000
	s_addc_u32 s27, s27, 0
	s_add_i32 s28, s65, s48
	v_lshl_add_u64 v[2:3], s[26:27], 0, v[196:197]
	s_mov_b32 m0, s28
	s_nop 0
	global_load_lds_dwordx4 v[2:3], off
	v_lshl_add_u64 v[2:3], s[26:27], 0, v[200:201]
	s_add_i32 m0, s28, 0x2000
	s_nop 0
	global_load_lds_dwordx4 v[2:3], off
	s_waitcnt vmcnt(8)
	s_waitcnt lgkmcnt(0)
	s_barrier
	s_setprio 1
	v_mfma_f32_16x16x32_bf16 v[96:99], v[132:135], v[148:151], v[96:99]
	v_mfma_f32_16x16x32_bf16 v[92:95], v[140:143], v[148:151], v[92:95]
	v_mfma_f32_16x16x32_bf16 v[88:91], v[132:135], v[156:159], v[88:91]
	v_mfma_f32_16x16x32_bf16 v[84:87], v[140:143], v[156:159], v[84:87]
	v_mfma_f32_16x16x32_bf16 v[80:83], v[132:135], v[164:167], v[80:83]
	v_mfma_f32_16x16x32_bf16 v[76:79], v[140:143], v[164:167], v[76:79]
	v_mfma_f32_16x16x32_bf16 v[72:75], v[132:135], v[172:175], v[72:75]
	v_mfma_f32_16x16x32_bf16 v[68:71], v[140:143], v[172:175], v[68:71]
	v_mfma_f32_16x16x32_bf16 v[96:99], v[136:139], v[152:155], v[96:99]
	v_mfma_f32_16x16x32_bf16 v[92:95], v[144:147], v[152:155], v[92:95]
	v_mfma_f32_16x16x32_bf16 v[88:91], v[136:139], v[160:163], v[88:91]
	v_mfma_f32_16x16x32_bf16 v[84:87], v[144:147], v[160:163], v[84:87]
	v_mfma_f32_16x16x32_bf16 v[80:83], v[136:139], v[168:171], v[80:83]
	v_mfma_f32_16x16x32_bf16 v[76:79], v[144:147], v[168:171], v[76:79]
	v_mfma_f32_16x16x32_bf16 v[72:75], v[136:139], v[176:179], v[72:75]
	v_mfma_f32_16x16x32_bf16 v[68:71], v[144:147], v[176:179], v[68:71]
	v_mfma_f32_16x16x32_bf16 v[64:67], v[180:183], v[148:151], v[64:67]
	v_mfma_f32_16x16x32_bf16 v[60:63], v[188:191], v[148:151], v[60:63]
	v_mfma_f32_16x16x32_bf16 v[56:59], v[180:183], v[156:159], v[56:59]
	v_mfma_f32_16x16x32_bf16 v[52:55], v[188:191], v[156:159], v[52:55]
	v_mfma_f32_16x16x32_bf16 v[48:51], v[180:183], v[164:167], v[48:51]
	v_mfma_f32_16x16x32_bf16 v[44:47], v[188:191], v[164:167], v[44:47]
	v_mfma_f32_16x16x32_bf16 v[40:43], v[180:183], v[172:175], v[40:43]
	v_mfma_f32_16x16x32_bf16 v[36:39], v[188:191], v[172:175], v[36:39]
	v_mfma_f32_16x16x32_bf16 v[64:67], v[184:187], v[152:155], v[64:67]
	v_mfma_f32_16x16x32_bf16 v[60:63], v[192:195], v[152:155], v[60:63]
	v_mfma_f32_16x16x32_bf16 v[56:59], v[184:187], v[160:163], v[56:59]
	v_mfma_f32_16x16x32_bf16 v[52:55], v[192:195], v[160:163], v[52:55]
	v_mfma_f32_16x16x32_bf16 v[48:51], v[184:187], v[168:171], v[48:51]
	v_mfma_f32_16x16x32_bf16 v[44:47], v[192:195], v[168:171], v[44:47]
	v_mfma_f32_16x16x32_bf16 v[40:43], v[184:187], v[176:179], v[40:43]
	v_mfma_f32_16x16x32_bf16 v[36:39], v[192:195], v[176:179], v[36:39]
	s_setprio 0
	s_add_i32 s63, s63, 2
	s_add_u32 s61, s61, 0x10000
	s_addc_u32 s62, s62, 0
	s_add_u32 s24, s24, 0x100
	s_addc_u32 s25, s25, 0
	s_cmp_gt_u32 s63, 13
	s_barrier
	s_cbranch_scc0 .LBB0_613
	s_cmp_eq_u32 s78, 0
	s_cbranch_scc0 .Lhalf_skip_x_4
	s_barrier

; #define PG8_STAGE(bufoff, gbase, voff) do { _Pragma("unroll") for (int _i = 0; _i < 2; ++_i) \
;         __builtin_amdgcn_global_load_lds((const unsigned*)((const char*)(gbase) + (voff)[_i]), (PG8_LAS unsigned*)(lds + (bufoff) + ldsw + _i * 8192), 16, 0, 0); } while (0)
; #define PG8_LDA(dst, b, h) do { _Pragma("unroll") for (int m = 0; m < 4; ++m) _Pragma("unroll") for (int k = 0; k < 2; ++k) dst[m][k] = *(const PG8_LAS bf16x8*)(lds + PG8_SA(b, h) + aoff + m * 2048 + k * 1024); } while (0)
; #define PG8_LDB(dst, b, h) do { _Pragma("unroll") for (int n = 0; n < 2; ++n) _Pragma("unroll") for (int k = 0; k < 2; ++k) dst[n][k] = *(const PG8_LAS bf16x8*)(lds + PG8_SB(b, h) + boff + n * 2048 + k * 1024); } while (0)
; #define PG8_MMA(ai, bj, At, Bt) do { __builtin_amdgcn_s_setprio(1); _Pragma("unroll") for (int m = 0; m < 4; ++m) _Pragma("unroll") for (int n = 0; n < 2; ++n) _Pragma("unroll") for (int k = 0; k < 2; ++k) \
;         acc[ai][bj][m][n] = __builtin_amdgcn_mfma_f32_16x16x32_bf16(Bt[n][k], At[m][k], acc[ai][bj][m][n], 0, 0, 0); __builtin_amdgcn_s_setprio(0); } while (0)
; #define PG8_WAIT_V(n) asm volatile("s_waitcnt vmcnt(" #n ")" ::: "memory")
; #define PG8_WAIT_L(n) asm volatile("s_waitcnt lgkmcnt(" #n ")" ::: "memory")
; template <class Epi, class Sched>
; __device__ __forceinline__ void gemm_phase(PG8_LAS unsigned char* lds, const Gemm g, const Sched& S, const Epi& E) {
;     ...
;             const bool last = (t == nt - 2);
;             const char* a1 = cA + (size_t)(t + 1) * kstep;
;             const char* a2 = last ? nA : cA + (size_t)(t + 2) * kstep; const char* b2 = last ? nB : cB + (size_t)(t + 2) * kstepB;
;             const char* a3 = a2 + kstep; const char* b3 = b2 + kstepB;
;             if (last && has_next) S.a_ready(nxt);
;             PG8_LDB(B0, 0, 0); PG8_SCHED; PG8_LDA(At, 0, 0); PG8_STAGE(PG8_SA(1, 1), a1 + hstep, voffA);
;             PG8_WAIT_L(8); PG8_BAR; PG8_WAIT_L(0); PG8_MMA(0, 0, At, B0); PG8_BAR; PG8_SCHED;
;             PG8_LDB(B1, 0, 1); PG8_STAGE(PG8_SB(0, 0), b2, voffB);
;             PG8_BAR; PG8_WAIT_L(0); PG8_MMA(0, 1, At, B1); PG8_BAR;
;             PG8_LDA(At, 0, 1); PG8_STAGE(PG8_SA(0, 0), a2, voffA);
;             PG8_BAR; PG8_WAIT_L(0); PG8_MMA(1, 0, At, B0); PG8_BAR; PG8_SCHED;
;             PG8_STAGE(PG8_SB(0, 1), b2 + hstepB, voffB);
;             PG8_WAIT_V(6); PG8_BAR; PG8_MMA(1, 1, At, B1); PG8_BAR;
.Lhalf_skip_y_5:
.LBB0_783:
	ds_read_b128 v[128:131], v197
	ds_read_b128 v[132:135], v197 offset:1024
	ds_read_b128 v[136:139], v197 offset:2048
	ds_read_b128 v[140:143], v197 offset:3072
	s_add_u32 s30, s28, 0x100
	s_addc_u32 s31, s29, 0
	s_cmp_eq_u32 s69, 28
	s_cselect_b32 s39, s19, s31
	s_cselect_b32 s38, s65, s30
	s_cselect_b32 s37, s21, s68
	s_cselect_b32 s36, s66, s67
	v_lshl_add_u64 v[192:193], s[28:29], 0, v[172:173]
	s_add_i32 m0, s27, 0xc000
	ds_read_b128 v[144:147], v198
	ds_read_b128 v[148:151], v198 offset:1024
	ds_read_b128 v[152:155], v198 offset:2048
	ds_read_b128 v[156:159], v198 offset:3072
	ds_read_b128 v[160:163], v198 offset:4096
	ds_read_b128 v[180:183], v198 offset:5120
	ds_read_b128 v[184:187], v198 offset:6144
	ds_read_b128 v[188:191], v198 offset:7168
	global_load_lds_dwordx4 v[192:193], off
	v_lshl_add_u64 v[192:193], s[28:29], 0, v[174:175]
	s_add_i32 m0, s27, 0xe000
	s_nop 0
	global_load_lds_dwordx4 v[192:193], off
	s_add_i32 s28, s62, s54
	v_lshl_add_u64 v[192:193], s[36:37], 0, v[164:165]
	s_mov_b32 m0, s28
	ds_read_b128 v[200:203], v199
	ds_read_b128 v[204:207], v199 offset:1024
	ds_read_b128 v[208:211], v199 offset:2048
	ds_read_b128 v[212:215], v199 offset:3072
	s_waitcnt vmcnt(8)
	s_waitcnt lgkmcnt(0)
	s_barrier
	s_setprio 1
	v_mfma_f32_16x16x32_bf16 v[124:127], v[128:131], v[144:147], v[124:127]
	v_mfma_f32_16x16x32_bf16 v[120:123], v[136:139], v[144:147], v[120:123]
	v_mfma_f32_16x16x32_bf16 v[116:119], v[128:131], v[152:155], v[116:119]
	v_mfma_f32_16x16x32_bf16 v[104:107], v[136:139], v[152:155], v[104:107]
	v_mfma_f32_16x16x32_bf16 v[92:95], v[128:131], v[160:163], v[92:95]
	v_mfma_f32_16x16x32_bf16 v[88:91], v[136:139], v[160:163], v[88:91]
	v_mfma_f32_16x16x32_bf16 v[76:79], v[128:131], v[184:187], v[76:79]
	v_mfma_f32_16x16x32_bf16 v[72:75], v[136:139], v[184:187], v[72:75]
	v_mfma_f32_16x16x32_bf16 v[124:127], v[132:135], v[148:151], v[124:127]
	v_mfma_f32_16x16x32_bf16 v[120:123], v[140:143], v[148:151], v[120:123]
	v_mfma_f32_16x16x32_bf16 v[116:119], v[132:135], v[156:159], v[116:119]
	v_mfma_f32_16x16x32_bf16 v[104:107], v[140:143], v[156:159], v[104:107]
	v_mfma_f32_16x16x32_bf16 v[92:95], v[132:135], v[180:183], v[92:95]
	v_mfma_f32_16x16x32_bf16 v[88:91], v[140:143], v[180:183], v[88:91]
	v_mfma_f32_16x16x32_bf16 v[76:79], v[132:135], v[188:191], v[76:79]
	v_mfma_f32_16x16x32_bf16 v[72:75], v[140:143], v[188:191], v[72:75]
	v_mfma_f32_16x16x32_bf16 v[112:115], v[200:203], v[144:147], v[112:115]
	v_mfma_f32_16x16x32_bf16 v[108:111], v[208:211], v[144:147], v[108:111]
	v_mfma_f32_16x16x32_bf16 v[100:103], v[200:203], v[152:155], v[100:103]
	v_mfma_f32_16x16x32_bf16 v[96:99], v[208:211], v[152:155], v[96:99]
	v_mfma_f32_16x16x32_bf16 v[84:87], v[200:203], v[160:163], v[84:87]
	v_mfma_f32_16x16x32_bf16 v[80:83], v[208:211], v[160:163], v[80:83]
	v_mfma_f32_16x16x32_bf16 v[68:71], v[200:203], v[184:187], v[68:71]
	v_mfma_f32_16x16x32_bf16 v[64:67], v[208:211], v[184:187], v[64:67]
	v_mfma_f32_16x16x32_bf16 v[112:115], v[204:207], v[148:151], v[112:115]
	v_mfma_f32_16x16x32_bf16 v[108:111], v[212:215], v[148:151], v[108:111]
	v_mfma_f32_16x16x32_bf16 v[100:103], v[204:207], v[156:159], v[100:103]
	v_mfma_f32_16x16x32_bf16 v[96:99], v[212:215], v[156:159], v[96:99]
	v_mfma_f32_16x16x32_bf16 v[84:87], v[204:207], v[180:183], v[84:87]
	v_mfma_f32_16x16x32_bf16 v[80:83], v[212:215], v[180:183], v[80:83]
	v_mfma_f32_16x16x32_bf16 v[68:71], v[204:207], v[188:191], v[68:71]
	v_mfma_f32_16x16x32_bf16 v[64:67], v[212:215], v[188:191], v[64:67]
	s_setprio 0
	s_barrier
	global_load_lds_dwordx4 v[192:193], off
	v_lshl_add_u64 v[192:193], s[36:37], 0, v[168:169]
	s_add_i32 m0, s28, 0x2000
	s_nop 0
	global_load_lds_dwordx4 v[192:193], off
	s_mov_b32 m0, s27
	v_lshl_add_u64 v[192:193], s[38:39], 0, v[166:167]
	ds_read_b128 v[144:147], v198 offset:16384
	ds_read_b128 v[148:151], v198 offset:17408
	ds_read_b128 v[152:155], v198 offset:18432
	ds_read_b128 v[156:159], v198 offset:19456
	ds_read_b128 v[160:163], v198 offset:20480
	ds_read_b128 v[180:183], v198 offset:21504
	ds_read_b128 v[184:187], v198 offset:22528
	ds_read_b128 v[188:191], v198 offset:23552
	global_load_lds_dwordx4 v[192:193], off
	v_lshl_add_u64 v[216:217], s[38:39], 0, v[170:171]
	s_mov_b32 m0, s55
	s_nop 0
	global_load_lds_dwordx4 v[216:217], off
	s_add_u32 s28, s36, 0x4000
	s_addc_u32 s29, s37, 0
	s_add_i32 s70, s63, s54
	v_lshl_add_u64 v[250:251], s[28:29], 0, v[164:165]
	s_mov_b32 m0, s70
	s_nop 0
	global_load_lds_dwordx4 v[250:251], off
	v_lshl_add_u64 v[250:251], s[28:29], 0, v[168:169]
	s_add_i32 m0, s70, 0x2000
	s_nop 0
	global_load_lds_dwordx4 v[250:251], off
	s_waitcnt vmcnt(8)
	s_waitcnt lgkmcnt(0)
	s_barrier
; #define PG8_STAGE(bufoff, gbase, voff) do { _Pragma("unroll") for (int _i = 0; _i < 2; ++_i) \
;         __builtin_amdgcn_global_load_lds((const unsigned*)((const char*)(gbase) + (voff)[_i]), (PG8_LAS unsigned*)(lds + (bufoff) + ldsw + _i * 8192), 16, 0, 0); } while (0)
; #define PG8_LDA(dst, b, h) do { _Pragma("unroll") for (int m = 0; m < 4; ++m) _Pragma("unroll") for (int k = 0; k < 2; ++k) dst[m][k] = *(const PG8_LAS bf16x8*)(lds + PG8_SA(b, h) + aoff + m * 2048 + k * 1024); } while (0)
; #define PG8_LDB(dst, b, h) do { _Pragma("unroll") for (int n = 0; n < 2; ++n) _Pragma("unroll") for (int k = 0; k < 2; ++k) dst[n][k] = *(const PG8_LAS bf16x8*)(lds + PG8_SB(b, h) + boff + n * 2048 + k * 1024); } while (0)
; #define PG8_MMA(ai, bj, At, Bt) do { __builtin_amdgcn_s_setprio(1); _Pragma("unroll") for (int m = 0; m < 4; ++m) _Pragma("unroll") for (int n = 0; n < 2; ++n) _Pragma("unroll") for (int k = 0; k < 2; ++k) \
;         acc[ai][bj][m][n] = __builtin_amdgcn_mfma_f32_16x16x32_bf16(Bt[n][k], At[m][k], acc[ai][bj][m][n], 0, 0, 0); __builtin_amdgcn_s_setprio(0); } while (0)
; #define PG8_WAIT_V(n) asm volatile("s_waitcnt vmcnt(" #n ")" ::: "memory")
; #define PG8_WAIT_L(n) asm volatile("s_waitcnt lgkmcnt(" #n ")" ::: "memory")
; #define PG8_BAR __builtin_amdgcn_s_barrier()
; #define PG8_SCHED __builtin_amdgcn_sched_barrier(0)
; template <class Epi, class Sched>
; __device__ __forceinline__ void gemm_phase(PG8_LAS unsigned char* lds, const Gemm g, const Sched& S, const Epi& E) {
;     ...
;             PG8_BAR; PG8_WAIT_L(0); PG8_MMA(1, 0, At, B0); PG8_BAR; PG8_SCHED;
;             PG8_STAGE(PG8_SB(0, 1), b2 + hstepB, voffB);
;             PG8_WAIT_V(6); PG8_BAR; PG8_MMA(1, 1, At, B1); PG8_BAR;
;             PG8_LDB(B0, 1, 0); PG8_SCHED; PG8_LDA(At, 1, 0); PG8_STAGE(PG8_SA(0, 1), a2 + hstep, voffA);
;             PG8_WAIT_L(8); PG8_BAR; PG8_WAIT_L(0); PG8_MMA(0, 0, At, B0); PG8_BAR; PG8_SCHED;
;             PG8_LDB(B1, 1, 1); PG8_STAGE(PG8_SB(1, 0), b3, voffB);
;             PG8_BAR; PG8_WAIT_L(0); PG8_MMA(0, 1, At, B1); PG8_BAR;
	s_setprio 1
	v_mfma_f32_16x16x32_bf16 v[60:63], v[128:131], v[144:147], v[60:63]
	v_mfma_f32_16x16x32_bf16 v[56:59], v[136:139], v[144:147], v[56:59]
	v_mfma_f32_16x16x32_bf16 v[44:47], v[128:131], v[152:155], v[44:47]
	v_mfma_f32_16x16x32_bf16 v[40:43], v[136:139], v[152:155], v[40:43]
	v_mfma_f32_16x16x32_bf16 v[28:31], v[128:131], v[160:163], v[28:31]
	v_mfma_f32_16x16x32_bf16 v[24:27], v[136:139], v[160:163], v[24:27]
	v_mfma_f32_16x16x32_bf16 v[12:15], v[128:131], v[184:187], v[12:15]
	v_mfma_f32_16x16x32_bf16 v[8:11], v[136:139], v[184:187], v[8:11]
	v_mfma_f32_16x16x32_bf16 v[60:63], v[132:135], v[148:151], v[60:63]
	v_mfma_f32_16x16x32_bf16 v[56:59], v[140:143], v[148:151], v[56:59]
	v_mfma_f32_16x16x32_bf16 v[44:47], v[132:135], v[156:159], v[44:47]
	v_mfma_f32_16x16x32_bf16 v[40:43], v[140:143], v[156:159], v[40:43]
	v_mfma_f32_16x16x32_bf16 v[28:31], v[132:135], v[180:183], v[28:31]
	v_mfma_f32_16x16x32_bf16 v[24:27], v[140:143], v[180:183], v[24:27]
	v_mfma_f32_16x16x32_bf16 v[12:15], v[132:135], v[188:191], v[12:15]
	v_mfma_f32_16x16x32_bf16 v[8:11], v[140:143], v[188:191], v[8:11]
	v_mfma_f32_16x16x32_bf16 v[52:55], v[200:203], v[144:147], v[52:55]
	v_mfma_f32_16x16x32_bf16 v[48:51], v[208:211], v[144:147], v[48:51]
	v_mfma_f32_16x16x32_bf16 v[36:39], v[200:203], v[152:155], v[36:39]
	v_mfma_f32_16x16x32_bf16 v[32:35], v[208:211], v[152:155], v[32:35]
	v_mfma_f32_16x16x32_bf16 v[20:23], v[200:203], v[160:163], v[20:23]
	v_mfma_f32_16x16x32_bf16 v[16:19], v[208:211], v[160:163], v[16:19]
	v_mfma_f32_16x16x32_bf16 v[4:7], v[200:203], v[184:187], v[4:7]
	v_mfma_f32_16x16x32_bf16 v[0:3], v[208:211], v[184:187], v[0:3]
	v_mfma_f32_16x16x32_bf16 v[52:55], v[204:207], v[148:151], v[52:55]
	v_mfma_f32_16x16x32_bf16 v[48:51], v[212:215], v[148:151], v[48:51]
	v_mfma_f32_16x16x32_bf16 v[36:39], v[204:207], v[156:159], v[36:39]
	v_mfma_f32_16x16x32_bf16 v[32:35], v[212:215], v[156:159], v[32:35]
	v_mfma_f32_16x16x32_bf16 v[20:23], v[204:207], v[180:183], v[20:23]
	v_mfma_f32_16x16x32_bf16 v[16:19], v[212:215], v[180:183], v[16:19]
	v_mfma_f32_16x16x32_bf16 v[4:7], v[204:207], v[188:191], v[4:7]
	v_mfma_f32_16x16x32_bf16 v[0:3], v[212:215], v[188:191], v[0:3]
	s_setprio 0
	s_barrier
	s_add_i32 s70, 0, 0x18000
	v_add_u32_e32 v140, s70, v195
	ds_read_b128 v[128:131], v140
	ds_read_b128 v[132:135], v140 offset:1024
	ds_read_b128 v[136:139], v140 offset:2048
	ds_read_b128 v[140:143], v140 offset:3072
	s_add_u32 s28, s38, 0x80000
	s_addc_u32 s29, s39, 0
	s_mov_b32 m0, s56
	v_lshl_add_u64 v[200:201], s[28:29], 0, v[166:167]
	ds_read_b128 v[144:147], v198 offset:32768
	ds_read_b128 v[148:151], v198 offset:33792
	ds_read_b128 v[152:155], v198 offset:34816
	ds_read_b128 v[156:159], v198 offset:35840
	ds_read_b128 v[160:163], v198 offset:36864
	ds_read_b128 v[180:183], v198 offset:37888
	ds_read_b128 v[184:187], v198 offset:38912
	ds_read_b128 v[188:191], v198 offset:39936
	global_load_lds_dwordx4 v[200:201], off
	v_lshl_add_u64 v[200:201], s[28:29], 0, v[170:171]
	s_mov_b32 m0, s57
	s_nop 0
	global_load_lds_dwordx4 v[200:201], off
	s_add_i32 s38, 0, 0x1c000
	s_add_u32 s28, s36, 0x8000
	s_addc_u32 s29, s37, 0
	s_add_i32 s39, s70, s54
	v_add_u32_e32 v212, s38, v195
	v_lshl_add_u64 v[218:219], s[28:29], 0, v[164:165]
	s_mov_b32 m0, s39
	ds_read_b128 v[200:203], v212
	ds_read_b128 v[204:207], v212 offset:1024
	ds_read_b128 v[208:211], v212 offset:2048
	ds_read_b128 v[212:215], v212 offset:3072
	s_waitcnt vmcnt(8)
	s_waitcnt lgkmcnt(0)
	s_barrier
	s_setprio 1
	v_mfma_f32_16x16x32_bf16 v[124:127], v[128:131], v[144:147], v[124:127]
	v_mfma_f32_16x16x32_bf16 v[120:123], v[136:139], v[144:147], v[120:123]
	v_mfma_f32_16x16x32_bf16 v[116:119], v[128:131], v[152:155], v[116:119]
	v_mfma_f32_16x16x32_bf16 v[104:107], v[136:139], v[152:155], v[104:107]
	v_mfma_f32_16x16x32_bf16 v[92:95], v[128:131], v[160:163], v[92:95]
	v_mfma_f32_16x16x32_bf16 v[88:91], v[136:139], v[160:163], v[88:91]
	v_mfma_f32_16x16x32_bf16 v[76:79], v[128:131], v[184:187], v[76:79]
	v_mfma_f32_16x16x32_bf16 v[72:75], v[136:139], v[184:187], v[72:75]
	v_mfma_f32_16x16x32_bf16 v[124:127], v[132:135], v[148:151], v[124:127]
	v_mfma_f32_16x16x32_bf16 v[120:123], v[140:143], v[148:151], v[120:123]
	v_mfma_f32_16x16x32_bf16 v[116:119], v[132:135], v[156:159], v[116:119]
	v_mfma_f32_16x16x32_bf16 v[104:107], v[140:143], v[156:159], v[104:107]
	v_mfma_f32_16x16x32_bf16 v[92:95], v[132:135], v[180:183], v[92:95]
	v_mfma_f32_16x16x32_bf16 v[88:91], v[140:143], v[180:183], v[88:91]
	v_mfma_f32_16x16x32_bf16 v[76:79], v[132:135], v[188:191], v[76:79]
	v_mfma_f32_16x16x32_bf16 v[72:75], v[140:143], v[188:191], v[72:75]
	v_mfma_f32_16x16x32_bf16 v[112:115], v[200:203], v[144:147], v[112:115]
	v_mfma_f32_16x16x32_bf16 v[108:111], v[208:211], v[144:147], v[108:111]
	v_mfma_f32_16x16x32_bf16 v[100:103], v[200:203], v[152:155], v[100:103]
	v_mfma_f32_16x16x32_bf16 v[96:99], v[208:211], v[152:155], v[96:99]
	v_mfma_f32_16x16x32_bf16 v[84:87], v[200:203], v[160:163], v[84:87]
	v_mfma_f32_16x16x32_bf16 v[80:83], v[208:211], v[160:163], v[80:83]
	v_mfma_f32_16x16x32_bf16 v[68:71], v[200:203], v[184:187], v[68:71]
	v_mfma_f32_16x16x32_bf16 v[64:67], v[208:211], v[184:187], v[64:67]
	v_mfma_f32_16x16x32_bf16 v[112:115], v[204:207], v[148:151], v[112:115]
	v_mfma_f32_16x16x32_bf16 v[108:111], v[212:215], v[148:151], v[108:111]
	v_mfma_f32_16x16x32_bf16 v[100:103], v[204:207], v[156:159], v[100:103]
	v_mfma_f32_16x16x32_bf16 v[96:99], v[212:215], v[156:159], v[96:99]
	v_mfma_f32_16x16x32_bf16 v[84:87], v[204:207], v[180:183], v[84:87]
	v_mfma_f32_16x16x32_bf16 v[80:83], v[212:215], v[180:183], v[80:83]
	v_mfma_f32_16x16x32_bf16 v[68:71], v[204:207], v[188:191], v[68:71]
	v_mfma_f32_16x16x32_bf16 v[64:67], v[212:215], v[188:191], v[64:67]
	s_setprio 0
	s_barrier
; #define PG8_STAGE(bufoff, gbase, voff) do { _Pragma("unroll") for (int _i = 0; _i < 2; ++_i) \
;         __builtin_amdgcn_global_load_lds((const unsigned*)((const char*)(gbase) + (voff)[_i]), (PG8_LAS unsigned*)(lds + (bufoff) + ldsw + _i * 8192), 16, 0, 0); } while (0)
; #define PG8_LDA(dst, b, h) do { _Pragma("unroll") for (int m = 0; m < 4; ++m) _Pragma("unroll") for (int k = 0; k < 2; ++k) dst[m][k] = *(const PG8_LAS bf16x8*)(lds + PG8_SA(b, h) + aoff + m * 2048 + k * 1024); } while (0)
; #define PG8_LDB(dst, b, h) do { _Pragma("unroll") for (int n = 0; n < 2; ++n) _Pragma("unroll") for (int k = 0; k < 2; ++k) dst[n][k] = *(const PG8_LAS bf16x8*)(lds + PG8_SB(b, h) + boff + n * 2048 + k * 1024); } while (0)
; #define PG8_MMA(ai, bj, At, Bt) do { __builtin_amdgcn_s_setprio(1); _Pragma("unroll") for (int m = 0; m < 4; ++m) _Pragma("unroll") for (int n = 0; n < 2; ++n) _Pragma("unroll") for (int k = 0; k < 2; ++k) \
;         acc[ai][bj][m][n] = __builtin_amdgcn_mfma_f32_16x16x32_bf16(Bt[n][k], At[m][k], acc[ai][bj][m][n], 0, 0, 0); __builtin_amdgcn_s_setprio(0); } while (0)
; #define PG8_WAIT_V(n) asm volatile("s_waitcnt vmcnt(" #n ")" ::: "memory")
; #define PG8_WAIT_L(n) asm volatile("s_waitcnt lgkmcnt(" #n ")" ::: "memory")
; #define PG8_BAR __builtin_amdgcn_s_barrier()
; #define PG8_SCHED __builtin_amdgcn_sched_barrier(0)
; template <class Epi, class Sched>
; __device__ __forceinline__ void gemm_phase(PG8_LAS unsigned char* lds, const Gemm g, const Sched& S, const Epi& E) {
;     ...
;             PG8_LDB(B1, 1, 1); PG8_STAGE(PG8_SB(1, 0), b3, voffB);
;             PG8_BAR; PG8_WAIT_L(0); PG8_MMA(0, 1, At, B1); PG8_BAR;
;             PG8_LDA(At, 1, 1); PG8_STAGE(PG8_SA(1, 0), a3, voffA);
;             PG8_BAR; PG8_WAIT_L(0); PG8_MMA(1, 0, At, B0); PG8_BAR; PG8_SCHED;
;             PG8_STAGE(PG8_SB(1, 1), b3 + hstepB, voffB);
;             PG8_WAIT_V(6); PG8_BAR; PG8_MMA(1, 1, At, B1); PG8_BAR;
;         }
	global_load_lds_dwordx4 v[218:219], off
	v_lshl_add_u64 v[218:219], s[28:29], 0, v[168:169]
	s_add_i32 m0, s39, 0x2000
	s_nop 0
	global_load_lds_dwordx4 v[218:219], off
	s_mov_b32 m0, s59
	v_lshl_add_u64 v[192:193], v[192:193], 0, s[10:11]
	ds_read_b128 v[144:147], v198 offset:49152
	ds_read_b128 v[148:151], v198 offset:50176
	ds_read_b128 v[152:155], v198 offset:51200
	ds_read_b128 v[156:159], v198 offset:52224
	ds_read_b128 v[160:163], v198 offset:53248
	ds_read_b128 v[180:183], v198 offset:54272
	ds_read_b128 v[184:187], v198 offset:55296
	ds_read_b128 v[188:191], v198 offset:56320
	global_load_lds_dwordx4 v[192:193], off
	v_lshl_add_u64 v[192:193], v[216:217], 0, s[10:11]
	s_mov_b32 m0, s60
	s_nop 0
	global_load_lds_dwordx4 v[192:193], off
	s_add_u32 s28, s36, 0xc000
	s_addc_u32 s29, s37, 0
	s_add_i32 s36, s38, s54
	v_lshl_add_u64 v[252:253], s[28:29], 0, v[164:165]
	s_mov_b32 m0, s36
	s_nop 0
	global_load_lds_dwordx4 v[252:253], off
	v_lshl_add_u64 v[252:253], s[28:29], 0, v[168:169]
	s_add_i32 m0, s36, 0x2000
	s_nop 0
	global_load_lds_dwordx4 v[252:253], off
	s_waitcnt vmcnt(8)
	s_waitcnt lgkmcnt(0)
	s_barrier
	s_setprio 1
	v_mfma_f32_16x16x32_bf16 v[60:63], v[128:131], v[144:147], v[60:63]
	v_mfma_f32_16x16x32_bf16 v[56:59], v[136:139], v[144:147], v[56:59]
	v_mfma_f32_16x16x32_bf16 v[44:47], v[128:131], v[152:155], v[44:47]
	v_mfma_f32_16x16x32_bf16 v[40:43], v[136:139], v[152:155], v[40:43]
	v_mfma_f32_16x16x32_bf16 v[28:31], v[128:131], v[160:163], v[28:31]
	v_mfma_f32_16x16x32_bf16 v[24:27], v[136:139], v[160:163], v[24:27]
	v_mfma_f32_16x16x32_bf16 v[12:15], v[128:131], v[184:187], v[12:15]
	v_mfma_f32_16x16x32_bf16 v[8:11], v[136:139], v[184:187], v[8:11]
	v_mfma_f32_16x16x32_bf16 v[60:63], v[132:135], v[148:151], v[60:63]
	v_mfma_f32_16x16x32_bf16 v[56:59], v[140:143], v[148:151], v[56:59]
	v_mfma_f32_16x16x32_bf16 v[44:47], v[132:135], v[156:159], v[44:47]
	v_mfma_f32_16x16x32_bf16 v[40:43], v[140:143], v[156:159], v[40:43]
	v_mfma_f32_16x16x32_bf16 v[28:31], v[132:135], v[180:183], v[28:31]
	v_mfma_f32_16x16x32_bf16 v[24:27], v[140:143], v[180:183], v[24:27]
	v_mfma_f32_16x16x32_bf16 v[12:15], v[132:135], v[188:191], v[12:15]
	v_mfma_f32_16x16x32_bf16 v[8:11], v[140:143], v[188:191], v[8:11]
	v_mfma_f32_16x16x32_bf16 v[52:55], v[200:203], v[144:147], v[52:55]
	v_mfma_f32_16x16x32_bf16 v[48:51], v[208:211], v[144:147], v[48:51]
	v_mfma_f32_16x16x32_bf16 v[36:39], v[200:203], v[152:155], v[36:39]
	v_mfma_f32_16x16x32_bf16 v[32:35], v[208:211], v[152:155], v[32:35]
	v_mfma_f32_16x16x32_bf16 v[20:23], v[200:203], v[160:163], v[20:23]
	v_mfma_f32_16x16x32_bf16 v[16:19], v[208:211], v[160:163], v[16:19]
	v_mfma_f32_16x16x32_bf16 v[4:7], v[200:203], v[184:187], v[4:7]
	v_mfma_f32_16x16x32_bf16 v[0:3], v[208:211], v[184:187], v[0:3]
	v_mfma_f32_16x16x32_bf16 v[52:55], v[204:207], v[148:151], v[52:55]
	v_mfma_f32_16x16x32_bf16 v[48:51], v[212:215], v[148:151], v[48:51]
	v_mfma_f32_16x16x32_bf16 v[36:39], v[204:207], v[156:159], v[36:39]
	v_mfma_f32_16x16x32_bf16 v[32:35], v[212:215], v[156:159], v[32:35]
	v_mfma_f32_16x16x32_bf16 v[20:23], v[204:207], v[180:183], v[20:23]
	v_mfma_f32_16x16x32_bf16 v[16:19], v[212:215], v[180:183], v[16:19]
	v_mfma_f32_16x16x32_bf16 v[4:7], v[204:207], v[188:191], v[4:7]
	v_mfma_f32_16x16x32_bf16 v[0:3], v[212:215], v[188:191], v[0:3]
	s_setprio 0
	s_add_i32 s69, s69, 2
	s_add_u32 s67, s67, 0x10000
	s_addc_u32 s68, s68, 0
	s_cmp_gt_u32 s69, 29
	s_mov_b64 s[28:29], s[30:31]
	s_barrier
	s_cbranch_scc0 .LBB0_783
	s_cmp_eq_u32 s78, 0
	s_cbranch_scc0 .Lhalf_skip_x_5
	s_barrier

; #define PG8_STAGE(bufoff, gbase, voff) do { _Pragma("unroll") for (int _i = 0; _i < 2; ++_i) \
;         __builtin_amdgcn_global_load_lds((const unsigned*)((const char*)(gbase) + (voff)[_i]), (PG8_LAS unsigned*)(lds + (bufoff) + ldsw + _i * 8192), 16, 0, 0); } while (0)
; #define PG8_LDA(dst, b, h) do { _Pragma("unroll") for (int m = 0; m < 4; ++m) _Pragma("unroll") for (int k = 0; k < 2; ++k) dst[m][k] = *(const PG8_LAS bf16x8*)(lds + PG8_SA(b, h) + aoff + m * 2048 + k * 1024); } while (0)
; #define PG8_LDB(dst, b, h) do { _Pragma("unroll") for (int n = 0; n < 2; ++n) _Pragma("unroll") for (int k = 0; k < 2; ++k) dst[n][k] = *(const PG8_LAS bf16x8*)(lds + PG8_SB(b, h) + boff + n * 2048 + k * 1024); } while (0)
; #define PG8_MMA(ai, bj, At, Bt) do { __builtin_amdgcn_s_setprio(1); _Pragma("unroll") for (int m = 0; m < 4; ++m) _Pragma("unroll") for (int n = 0; n < 2; ++n) _Pragma("unroll") for (int k = 0; k < 2; ++k) \
;         acc[ai][bj][m][n] = __builtin_amdgcn_mfma_f32_16x16x32_bf16(Bt[n][k], At[m][k], acc[ai][bj][m][n], 0, 0, 0); __builtin_amdgcn_s_setprio(0); } while (0)
; #define PG8_WAIT_V(n) asm volatile("s_waitcnt vmcnt(" #n ")" ::: "memory")
; #define PG8_WAIT_L(n) asm volatile("s_waitcnt lgkmcnt(" #n ")" ::: "memory")
; template <class Epi, class Sched>
; __device__ __forceinline__ void gemm_phase(PG8_LAS unsigned char* lds, const Gemm g, const Sched& S, const Epi& E) {
;     ...
;             const bool last = (t == nt - 2);
;             const char* a1 = cA + (size_t)(t + 1) * kstep;
;             const char* a2 = last ? nA : cA + (size_t)(t + 2) * kstep; const char* b2 = last ? nB : cB + (size_t)(t + 2) * kstepB;
;             const char* a3 = a2 + kstep; const char* b3 = b2 + kstepB;
;             if (last && has_next) S.a_ready(nxt);
;             PG8_LDB(B0, 0, 0); PG8_SCHED; PG8_LDA(At, 0, 0); PG8_STAGE(PG8_SA(1, 1), a1 + hstep, voffA);
;             PG8_WAIT_L(8); PG8_BAR; PG8_WAIT_L(0); PG8_MMA(0, 0, At, B0); PG8_BAR; PG8_SCHED;
;             PG8_LDB(B1, 0, 1); PG8_STAGE(PG8_SB(0, 0), b2, voffB);
;             PG8_BAR; PG8_WAIT_L(0); PG8_MMA(0, 1, At, B1); PG8_BAR;
;             PG8_LDA(At, 0, 1); PG8_STAGE(PG8_SA(0, 0), a2, voffA);
;             PG8_BAR; PG8_WAIT_L(0); PG8_MMA(1, 0, At, B0); PG8_BAR; PG8_SCHED;
;             PG8_STAGE(PG8_SB(0, 1), b2 + hstepB, voffB);
;             PG8_WAIT_V(6); PG8_BAR; PG8_MMA(1, 1, At, B1); PG8_BAR;
.Lhalf_skip_y_6:
.LBB0_904:
	ds_read_b128 v[152:155], v149
	ds_read_b128 v[156:159], v149 offset:1024
	ds_read_b128 v[160:163], v149 offset:2048
	ds_read_b128 v[164:167], v149 offset:3072
	s_add_u32 s22, s20, 0xfff80080
	s_addc_u32 s23, s21, -1
	s_cmp_eq_u32 s61, 28
	s_cselect_b32 s25, s11, s23
	s_cselect_b32 s24, s57, s22
	s_cselect_b32 s23, s13, s60
	s_cselect_b32 s22, s58, s59
	v_lshl_add_u64 v[144:145], s[20:21], 0, v[136:137]
	s_add_i32 m0, s19, 0xc000
	ds_read_b128 v[168:171], v150
	ds_read_b128 v[172:175], v150 offset:1024
	ds_read_b128 v[176:179], v150 offset:2048
	ds_read_b128 v[180:183], v150 offset:3072
	ds_read_b128 v[184:187], v150 offset:4096
	ds_read_b128 v[188:191], v150 offset:5120
	ds_read_b128 v[192:195], v150 offset:6144
	ds_read_b128 v[196:199], v150 offset:7168
	global_load_lds_dwordx4 v[144:145], off
	v_lshl_add_u64 v[144:145], s[20:21], 0, v[138:139]
	s_add_i32 m0, s19, 0xe000
	s_nop 0
	global_load_lds_dwordx4 v[144:145], off
	s_add_i32 s62, s53, s38
	v_lshl_add_u64 v[144:145], s[22:23], 0, v[128:129]
	s_mov_b32 m0, s62
	ds_read_b128 v[200:203], v151
	ds_read_b128 v[204:207], v151 offset:1024
	ds_read_b128 v[208:211], v151 offset:2048
	ds_read_b128 v[212:215], v151 offset:3072
	s_waitcnt vmcnt(8)
	s_waitcnt lgkmcnt(0)
	s_barrier
	s_setprio 1
	v_mfma_f32_16x16x32_bf16 v[124:127], v[152:155], v[168:171], v[124:127]
	v_mfma_f32_16x16x32_bf16 v[120:123], v[160:163], v[168:171], v[120:123]
	v_mfma_f32_16x16x32_bf16 v[108:111], v[152:155], v[176:179], v[108:111]
	v_mfma_f32_16x16x32_bf16 v[104:107], v[160:163], v[176:179], v[104:107]
	v_mfma_f32_16x16x32_bf16 v[92:95], v[152:155], v[184:187], v[92:95]
	v_mfma_f32_16x16x32_bf16 v[88:91], v[160:163], v[184:187], v[88:91]
	v_mfma_f32_16x16x32_bf16 v[76:79], v[152:155], v[192:195], v[76:79]
	v_mfma_f32_16x16x32_bf16 v[72:75], v[160:163], v[192:195], v[72:75]
	v_mfma_f32_16x16x32_bf16 v[124:127], v[156:159], v[172:175], v[124:127]
	v_mfma_f32_16x16x32_bf16 v[120:123], v[164:167], v[172:175], v[120:123]
	v_mfma_f32_16x16x32_bf16 v[108:111], v[156:159], v[180:183], v[108:111]
	v_mfma_f32_16x16x32_bf16 v[104:107], v[164:167], v[180:183], v[104:107]
	v_mfma_f32_16x16x32_bf16 v[92:95], v[156:159], v[188:191], v[92:95]
	v_mfma_f32_16x16x32_bf16 v[88:91], v[164:167], v[188:191], v[88:91]
	v_mfma_f32_16x16x32_bf16 v[76:79], v[156:159], v[196:199], v[76:79]
	v_mfma_f32_16x16x32_bf16 v[72:75], v[164:167], v[196:199], v[72:75]
	v_mfma_f32_16x16x32_bf16 v[116:119], v[200:203], v[168:171], v[116:119]
	v_mfma_f32_16x16x32_bf16 v[112:115], v[208:211], v[168:171], v[112:115]
	v_mfma_f32_16x16x32_bf16 v[100:103], v[200:203], v[176:179], v[100:103]
	v_mfma_f32_16x16x32_bf16 v[96:99], v[208:211], v[176:179], v[96:99]
	v_mfma_f32_16x16x32_bf16 v[84:87], v[200:203], v[184:187], v[84:87]
	v_mfma_f32_16x16x32_bf16 v[80:83], v[208:211], v[184:187], v[80:83]
	v_mfma_f32_16x16x32_bf16 v[68:71], v[200:203], v[192:195], v[68:71]
	v_mfma_f32_16x16x32_bf16 v[64:67], v[208:211], v[192:195], v[64:67]
	v_mfma_f32_16x16x32_bf16 v[116:119], v[204:207], v[172:175], v[116:119]
	v_mfma_f32_16x16x32_bf16 v[112:115], v[212:215], v[172:175], v[112:115]
	v_mfma_f32_16x16x32_bf16 v[100:103], v[204:207], v[180:183], v[100:103]
	v_mfma_f32_16x16x32_bf16 v[96:99], v[212:215], v[180:183], v[96:99]
	v_mfma_f32_16x16x32_bf16 v[84:87], v[204:207], v[188:191], v[84:87]
	v_mfma_f32_16x16x32_bf16 v[80:83], v[212:215], v[188:191], v[80:83]
	v_mfma_f32_16x16x32_bf16 v[68:71], v[204:207], v[196:199], v[68:71]
	v_mfma_f32_16x16x32_bf16 v[64:67], v[212:215], v[196:199], v[64:67]
	s_setprio 0
	s_barrier
	global_load_lds_dwordx4 v[144:145], off
	v_lshl_add_u64 v[144:145], s[22:23], 0, v[130:131]
	s_add_i32 m0, s62, 0x2000
	s_nop 0
	global_load_lds_dwordx4 v[144:145], off
	s_mov_b32 m0, s19
	v_lshl_add_u64 v[144:145], s[24:25], 0, v[134:135]
	ds_read_b128 v[168:171], v150 offset:16384
	ds_read_b128 v[172:175], v150 offset:17408
	ds_read_b128 v[176:179], v150 offset:18432
	ds_read_b128 v[180:183], v150 offset:19456
	ds_read_b128 v[184:187], v150 offset:20480
	ds_read_b128 v[188:191], v150 offset:21504
	ds_read_b128 v[192:195], v150 offset:22528
	ds_read_b128 v[196:199], v150 offset:23552
	global_load_lds_dwordx4 v[144:145], off
	v_lshl_add_u64 v[216:217], s[24:25], 0, v[132:133]
	s_mov_b32 m0, s46
	s_nop 0
	global_load_lds_dwordx4 v[216:217], off
	s_add_u32 s62, s22, 0x4000
	s_addc_u32 s63, s23, 0
	s_add_i32 s64, s54, s38
	v_lshl_add_u64 v[250:251], s[62:63], 0, v[128:129]
	s_mov_b32 m0, s64
	s_nop 0
	global_load_lds_dwordx4 v[250:251], off
	v_lshl_add_u64 v[250:251], s[62:63], 0, v[130:131]
	s_add_i32 m0, s64, 0x2000
	s_nop 0
	global_load_lds_dwordx4 v[250:251], off
	s_waitcnt vmcnt(8)
	s_waitcnt lgkmcnt(0)
	s_barrier
; #define PG8_STAGE(bufoff, gbase, voff) do { _Pragma("unroll") for (int _i = 0; _i < 2; ++_i) \
;         __builtin_amdgcn_global_load_lds((const unsigned*)((const char*)(gbase) + (voff)[_i]), (PG8_LAS unsigned*)(lds + (bufoff) + ldsw + _i * 8192), 16, 0, 0); } while (0)
; #define PG8_LDA(dst, b, h) do { _Pragma("unroll") for (int m = 0; m < 4; ++m) _Pragma("unroll") for (int k = 0; k < 2; ++k) dst[m][k] = *(const PG8_LAS bf16x8*)(lds + PG8_SA(b, h) + aoff + m * 2048 + k * 1024); } while (0)
; #define PG8_LDB(dst, b, h) do { _Pragma("unroll") for (int n = 0; n < 2; ++n) _Pragma("unroll") for (int k = 0; k < 2; ++k) dst[n][k] = *(const PG8_LAS bf16x8*)(lds + PG8_SB(b, h) + boff + n * 2048 + k * 1024); } while (0)
; #define PG8_MMA(ai, bj, At, Bt) do { __builtin_amdgcn_s_setprio(1); _Pragma("unroll") for (int m = 0; m < 4; ++m) _Pragma("unroll") for (int n = 0; n < 2; ++n) _Pragma("unroll") for (int k = 0; k < 2; ++k) \
;         acc[ai][bj][m][n] = __builtin_amdgcn_mfma_f32_16x16x32_bf16(Bt[n][k], At[m][k], acc[ai][bj][m][n], 0, 0, 0); __builtin_amdgcn_s_setprio(0); } while (0)
; #define PG8_WAIT_V(n) asm volatile("s_waitcnt vmcnt(" #n ")" ::: "memory")
; #define PG8_WAIT_L(n) asm volatile("s_waitcnt lgkmcnt(" #n ")" ::: "memory")
; #define PG8_BAR __builtin_amdgcn_s_barrier()
; #define PG8_SCHED __builtin_amdgcn_sched_barrier(0)
; template <class Epi, class Sched>
; __device__ __forceinline__ void gemm_phase(PG8_LAS unsigned char* lds, const Gemm g, const Sched& S, const Epi& E) {
;     ...
;             PG8_BAR; PG8_WAIT_L(0); PG8_MMA(1, 0, At, B0); PG8_BAR; PG8_SCHED;
;             PG8_STAGE(PG8_SB(0, 1), b2 + hstepB, voffB);
;             PG8_WAIT_V(6); PG8_BAR; PG8_MMA(1, 1, At, B1); PG8_BAR;
;             PG8_LDB(B0, 1, 0); PG8_SCHED; PG8_LDA(At, 1, 0); PG8_STAGE(PG8_SA(0, 1), a2 + hstep, voffA);
;             PG8_WAIT_L(8); PG8_BAR; PG8_WAIT_L(0); PG8_MMA(0, 0, At, B0); PG8_BAR; PG8_SCHED;
;             PG8_LDB(B1, 1, 1); PG8_STAGE(PG8_SB(1, 0), b3, voffB);
;             PG8_BAR; PG8_WAIT_L(0); PG8_MMA(0, 1, At, B1); PG8_BAR;
	s_setprio 1
	v_mfma_f32_16x16x32_bf16 v[60:63], v[152:155], v[168:171], v[60:63]
	v_mfma_f32_16x16x32_bf16 v[56:59], v[160:163], v[168:171], v[56:59]
	v_mfma_f32_16x16x32_bf16 v[44:47], v[152:155], v[176:179], v[44:47]
	v_mfma_f32_16x16x32_bf16 v[40:43], v[160:163], v[176:179], v[40:43]
	v_mfma_f32_16x16x32_bf16 v[28:31], v[152:155], v[184:187], v[28:31]
	v_mfma_f32_16x16x32_bf16 v[24:27], v[160:163], v[184:187], v[24:27]
	v_mfma_f32_16x16x32_bf16 v[12:15], v[152:155], v[192:195], v[12:15]
	v_mfma_f32_16x16x32_bf16 v[8:11], v[160:163], v[192:195], v[8:11]
	v_mfma_f32_16x16x32_bf16 v[60:63], v[156:159], v[172:175], v[60:63]
	v_mfma_f32_16x16x32_bf16 v[56:59], v[164:167], v[172:175], v[56:59]
	v_mfma_f32_16x16x32_bf16 v[44:47], v[156:159], v[180:183], v[44:47]
	v_mfma_f32_16x16x32_bf16 v[40:43], v[164:167], v[180:183], v[40:43]
	v_mfma_f32_16x16x32_bf16 v[28:31], v[156:159], v[188:191], v[28:31]
	v_mfma_f32_16x16x32_bf16 v[24:27], v[164:167], v[188:191], v[24:27]
	v_mfma_f32_16x16x32_bf16 v[12:15], v[156:159], v[196:199], v[12:15]
	v_mfma_f32_16x16x32_bf16 v[8:11], v[164:167], v[196:199], v[8:11]
	v_mfma_f32_16x16x32_bf16 v[52:55], v[200:203], v[168:171], v[52:55]
	v_mfma_f32_16x16x32_bf16 v[48:51], v[208:211], v[168:171], v[48:51]
	v_mfma_f32_16x16x32_bf16 v[36:39], v[200:203], v[176:179], v[36:39]
	v_mfma_f32_16x16x32_bf16 v[32:35], v[208:211], v[176:179], v[32:35]
	v_mfma_f32_16x16x32_bf16 v[20:23], v[200:203], v[184:187], v[20:23]
	v_mfma_f32_16x16x32_bf16 v[16:19], v[208:211], v[184:187], v[16:19]
	v_mfma_f32_16x16x32_bf16 v[4:7], v[200:203], v[192:195], v[4:7]
	v_mfma_f32_16x16x32_bf16 v[0:3], v[208:211], v[192:195], v[0:3]
	v_mfma_f32_16x16x32_bf16 v[52:55], v[204:207], v[172:175], v[52:55]
	v_mfma_f32_16x16x32_bf16 v[48:51], v[212:215], v[172:175], v[48:51]
	v_mfma_f32_16x16x32_bf16 v[36:39], v[204:207], v[180:183], v[36:39]
	v_mfma_f32_16x16x32_bf16 v[32:35], v[212:215], v[180:183], v[32:35]
	v_mfma_f32_16x16x32_bf16 v[20:23], v[204:207], v[188:191], v[20:23]
	v_mfma_f32_16x16x32_bf16 v[16:19], v[212:215], v[188:191], v[16:19]
	v_mfma_f32_16x16x32_bf16 v[4:7], v[204:207], v[196:199], v[4:7]
	v_mfma_f32_16x16x32_bf16 v[0:3], v[212:215], v[196:199], v[0:3]
	s_setprio 0
	s_barrier
	s_add_i32 s62, 0, 0x18000
	v_add_u32_e32 v164, s62, v147
	ds_read_b128 v[152:155], v164
	ds_read_b128 v[156:159], v164 offset:1024
	ds_read_b128 v[160:163], v164 offset:2048
	ds_read_b128 v[164:167], v164 offset:3072
	s_add_u32 s24, s24, 0x80000
	s_addc_u32 s25, s25, 0
	s_mov_b32 m0, s47
	v_lshl_add_u64 v[200:201], s[24:25], 0, v[134:135]
	ds_read_b128 v[168:171], v150 offset:32768
	ds_read_b128 v[172:175], v150 offset:33792
	ds_read_b128 v[176:179], v150 offset:34816
	ds_read_b128 v[180:183], v150 offset:35840
	ds_read_b128 v[184:187], v150 offset:36864
	ds_read_b128 v[188:191], v150 offset:37888
	ds_read_b128 v[192:195], v150 offset:38912
	ds_read_b128 v[196:199], v150 offset:39936
	global_load_lds_dwordx4 v[200:201], off
	v_lshl_add_u64 v[200:201], s[24:25], 0, v[132:133]
	s_mov_b32 m0, s48
	s_nop 0
	global_load_lds_dwordx4 v[200:201], off
	s_add_i32 s63, 0, 0x1c000
	s_add_u32 s24, s22, 0x8000
	s_addc_u32 s25, s23, 0
	s_add_i32 s62, s62, s38
	v_add_u32_e32 v212, s63, v147
	v_lshl_add_u64 v[218:219], s[24:25], 0, v[128:129]
	s_mov_b32 m0, s62
	ds_read_b128 v[200:203], v212
	ds_read_b128 v[204:207], v212 offset:1024
	ds_read_b128 v[208:211], v212 offset:2048
	ds_read_b128 v[212:215], v212 offset:3072
	s_waitcnt vmcnt(8)
	s_waitcnt lgkmcnt(0)
	s_barrier
	s_setprio 1
	v_mfma_f32_16x16x32_bf16 v[124:127], v[152:155], v[168:171], v[124:127]
	v_mfma_f32_16x16x32_bf16 v[120:123], v[160:163], v[168:171], v[120:123]
	v_mfma_f32_16x16x32_bf16 v[108:111], v[152:155], v[176:179], v[108:111]
	v_mfma_f32_16x16x32_bf16 v[104:107], v[160:163], v[176:179], v[104:107]
	v_mfma_f32_16x16x32_bf16 v[92:95], v[152:155], v[184:187], v[92:95]
	v_mfma_f32_16x16x32_bf16 v[88:91], v[160:163], v[184:187], v[88:91]
	v_mfma_f32_16x16x32_bf16 v[76:79], v[152:155], v[192:195], v[76:79]
	v_mfma_f32_16x16x32_bf16 v[72:75], v[160:163], v[192:195], v[72:75]
	v_mfma_f32_16x16x32_bf16 v[124:127], v[156:159], v[172:175], v[124:127]
	v_mfma_f32_16x16x32_bf16 v[120:123], v[164:167], v[172:175], v[120:123]
	v_mfma_f32_16x16x32_bf16 v[108:111], v[156:159], v[180:183], v[108:111]
	v_mfma_f32_16x16x32_bf16 v[104:107], v[164:167], v[180:183], v[104:107]
	v_mfma_f32_16x16x32_bf16 v[92:95], v[156:159], v[188:191], v[92:95]
	v_mfma_f32_16x16x32_bf16 v[88:91], v[164:167], v[188:191], v[88:91]
	v_mfma_f32_16x16x32_bf16 v[76:79], v[156:159], v[196:199], v[76:79]
	v_mfma_f32_16x16x32_bf16 v[72:75], v[164:167], v[196:199], v[72:75]
	v_mfma_f32_16x16x32_bf16 v[116:119], v[200:203], v[168:171], v[116:119]
	v_mfma_f32_16x16x32_bf16 v[112:115], v[208:211], v[168:171], v[112:115]
	v_mfma_f32_16x16x32_bf16 v[100:103], v[200:203], v[176:179], v[100:103]
	v_mfma_f32_16x16x32_bf16 v[96:99], v[208:211], v[176:179], v[96:99]
	v_mfma_f32_16x16x32_bf16 v[84:87], v[200:203], v[184:187], v[84:87]
	v_mfma_f32_16x16x32_bf16 v[80:83], v[208:211], v[184:187], v[80:83]
	v_mfma_f32_16x16x32_bf16 v[68:71], v[200:203], v[192:195], v[68:71]
	v_mfma_f32_16x16x32_bf16 v[64:67], v[208:211], v[192:195], v[64:67]
	v_mfma_f32_16x16x32_bf16 v[116:119], v[204:207], v[172:175], v[116:119]
	v_mfma_f32_16x16x32_bf16 v[112:115], v[212:215], v[172:175], v[112:115]
	v_mfma_f32_16x16x32_bf16 v[100:103], v[204:207], v[180:183], v[100:103]
	v_mfma_f32_16x16x32_bf16 v[96:99], v[212:215], v[180:183], v[96:99]
	v_mfma_f32_16x16x32_bf16 v[84:87], v[204:207], v[188:191], v[84:87]
	v_mfma_f32_16x16x32_bf16 v[80:83], v[212:215], v[188:191], v[80:83]
	v_mfma_f32_16x16x32_bf16 v[68:71], v[204:207], v[196:199], v[68:71]
	v_mfma_f32_16x16x32_bf16 v[64:67], v[212:215], v[196:199], v[64:67]
	s_setprio 0
	s_barrier
; #define PG8_STAGE(bufoff, gbase, voff) do { _Pragma("unroll") for (int _i = 0; _i < 2; ++_i) \
;         __builtin_amdgcn_global_load_lds((const unsigned*)((const char*)(gbase) + (voff)[_i]), (PG8_LAS unsigned*)(lds + (bufoff) + ldsw + _i * 8192), 16, 0, 0); } while (0)
; #define PG8_LDA(dst, b, h) do { _Pragma("unroll") for (int m = 0; m < 4; ++m) _Pragma("unroll") for (int k = 0; k < 2; ++k) dst[m][k] = *(const PG8_LAS bf16x8*)(lds + PG8_SA(b, h) + aoff + m * 2048 + k * 1024); } while (0)
; #define PG8_LDB(dst, b, h) do { _Pragma("unroll") for (int n = 0; n < 2; ++n) _Pragma("unroll") for (int k = 0; k < 2; ++k) dst[n][k] = *(const PG8_LAS bf16x8*)(lds + PG8_SB(b, h) + boff + n * 2048 + k * 1024); } while (0)
; #define PG8_MMA(ai, bj, At, Bt) do { __builtin_amdgcn_s_setprio(1); _Pragma("unroll") for (int m = 0; m < 4; ++m) _Pragma("unroll") for (int n = 0; n < 2; ++n) _Pragma("unroll") for (int k = 0; k < 2; ++k) \
;         acc[ai][bj][m][n] = __builtin_amdgcn_mfma_f32_16x16x32_bf16(Bt[n][k], At[m][k], acc[ai][bj][m][n], 0, 0, 0); __builtin_amdgcn_s_setprio(0); } while (0)
; #define PG8_WAIT_V(n) asm volatile("s_waitcnt vmcnt(" #n ")" ::: "memory")
; #define PG8_WAIT_L(n) asm volatile("s_waitcnt lgkmcnt(" #n ")" ::: "memory")
; #define PG8_BAR __builtin_amdgcn_s_barrier()
; #define PG8_SCHED __builtin_amdgcn_sched_barrier(0)
; template <class Epi, class Sched>
; __device__ __forceinline__ void gemm_phase(PG8_LAS unsigned char* lds, const Gemm g, const Sched& S, const Epi& E) {
;     ...
;             PG8_LDB(B1, 1, 1); PG8_STAGE(PG8_SB(1, 0), b3, voffB);
;             PG8_BAR; PG8_WAIT_L(0); PG8_MMA(0, 1, At, B1); PG8_BAR;
;             PG8_LDA(At, 1, 1); PG8_STAGE(PG8_SA(1, 0), a3, voffA);
;             PG8_BAR; PG8_WAIT_L(0); PG8_MMA(1, 0, At, B0); PG8_BAR; PG8_SCHED;
;             PG8_STAGE(PG8_SB(1, 1), b3 + hstepB, voffB);
;             PG8_WAIT_V(6); PG8_BAR; PG8_MMA(1, 1, At, B1); PG8_BAR;
;         }
	global_load_lds_dwordx4 v[218:219], off
	v_lshl_add_u64 v[218:219], s[24:25], 0, v[130:131]
	s_add_i32 m0, s62, 0x2000
	s_nop 0
	global_load_lds_dwordx4 v[218:219], off
	s_mov_b32 m0, s50
	v_lshl_add_u64 v[144:145], v[144:145], 0, s[8:9]
	ds_read_b128 v[168:171], v150 offset:49152
	ds_read_b128 v[172:175], v150 offset:50176
	ds_read_b128 v[176:179], v150 offset:51200
	ds_read_b128 v[180:183], v150 offset:52224
	ds_read_b128 v[184:187], v150 offset:53248
	ds_read_b128 v[188:191], v150 offset:54272
	ds_read_b128 v[192:195], v150 offset:55296
	ds_read_b128 v[196:199], v150 offset:56320
	global_load_lds_dwordx4 v[144:145], off
	v_lshl_add_u64 v[144:145], v[216:217], 0, s[8:9]
	s_mov_b32 m0, s51
	s_nop 0
	global_load_lds_dwordx4 v[144:145], off
	s_add_u32 s22, s22, 0xc000
	s_addc_u32 s23, s23, 0
	s_add_i32 s24, s63, s38
	v_lshl_add_u64 v[144:145], s[22:23], 0, v[128:129]
	s_mov_b32 m0, s24
	s_nop 0
	global_load_lds_dwordx4 v[144:145], off
	v_lshl_add_u64 v[144:145], s[22:23], 0, v[130:131]
	s_add_i32 m0, s24, 0x2000
	s_nop 0
	global_load_lds_dwordx4 v[144:145], off
	s_waitcnt vmcnt(8)
	s_waitcnt lgkmcnt(0)
	s_barrier
	s_setprio 1
	v_mfma_f32_16x16x32_bf16 v[60:63], v[152:155], v[168:171], v[60:63]
	v_mfma_f32_16x16x32_bf16 v[56:59], v[160:163], v[168:171], v[56:59]
	v_mfma_f32_16x16x32_bf16 v[44:47], v[152:155], v[176:179], v[44:47]
	v_mfma_f32_16x16x32_bf16 v[40:43], v[160:163], v[176:179], v[40:43]
	v_mfma_f32_16x16x32_bf16 v[28:31], v[152:155], v[184:187], v[28:31]
	v_mfma_f32_16x16x32_bf16 v[24:27], v[160:163], v[184:187], v[24:27]
	v_mfma_f32_16x16x32_bf16 v[12:15], v[152:155], v[192:195], v[12:15]
	v_mfma_f32_16x16x32_bf16 v[8:11], v[160:163], v[192:195], v[8:11]
	v_mfma_f32_16x16x32_bf16 v[60:63], v[156:159], v[172:175], v[60:63]
	v_mfma_f32_16x16x32_bf16 v[56:59], v[164:167], v[172:175], v[56:59]
	v_mfma_f32_16x16x32_bf16 v[44:47], v[156:159], v[180:183], v[44:47]
	v_mfma_f32_16x16x32_bf16 v[40:43], v[164:167], v[180:183], v[40:43]
	v_mfma_f32_16x16x32_bf16 v[28:31], v[156:159], v[188:191], v[28:31]
	v_mfma_f32_16x16x32_bf16 v[24:27], v[164:167], v[188:191], v[24:27]
	v_mfma_f32_16x16x32_bf16 v[12:15], v[156:159], v[196:199], v[12:15]
	v_mfma_f32_16x16x32_bf16 v[8:11], v[164:167], v[196:199], v[8:11]
	v_mfma_f32_16x16x32_bf16 v[52:55], v[200:203], v[168:171], v[52:55]
	v_mfma_f32_16x16x32_bf16 v[48:51], v[208:211], v[168:171], v[48:51]
	v_mfma_f32_16x16x32_bf16 v[36:39], v[200:203], v[176:179], v[36:39]
	v_mfma_f32_16x16x32_bf16 v[32:35], v[208:211], v[176:179], v[32:35]
	v_mfma_f32_16x16x32_bf16 v[20:23], v[200:203], v[184:187], v[20:23]
	v_mfma_f32_16x16x32_bf16 v[16:19], v[208:211], v[184:187], v[16:19]
	v_mfma_f32_16x16x32_bf16 v[4:7], v[200:203], v[192:195], v[4:7]
	v_mfma_f32_16x16x32_bf16 v[0:3], v[208:211], v[192:195], v[0:3]
	v_mfma_f32_16x16x32_bf16 v[52:55], v[204:207], v[172:175], v[52:55]
	v_mfma_f32_16x16x32_bf16 v[48:51], v[212:215], v[172:175], v[48:51]
	v_mfma_f32_16x16x32_bf16 v[36:39], v[204:207], v[180:183], v[36:39]
	v_mfma_f32_16x16x32_bf16 v[32:35], v[212:215], v[180:183], v[32:35]
	v_mfma_f32_16x16x32_bf16 v[20:23], v[204:207], v[188:191], v[20:23]
	v_mfma_f32_16x16x32_bf16 v[16:19], v[212:215], v[188:191], v[16:19]
	v_mfma_f32_16x16x32_bf16 v[4:7], v[204:207], v[196:199], v[4:7]
	v_mfma_f32_16x16x32_bf16 v[0:3], v[212:215], v[196:199], v[0:3]
	s_setprio 0
	s_add_i32 s61, s61, 2
	s_add_u32 s59, s59, 0x10000
	s_addc_u32 s60, s60, 0
	s_add_u32 s20, s20, 0x100
	s_addc_u32 s21, s21, 0
	s_cmp_gt_u32 s61, 29
	s_barrier
	s_cbranch_scc0 .LBB0_904
	s_cmp_eq_u32 s78, 0
	s_cbranch_scc0 .Lhalf_skip_x_6
	s_barrier

; #define PG8_STAGE(bufoff, gbase, voff) do { _Pragma("unroll") for (int _i = 0; _i < 2; ++_i) \
;         __builtin_amdgcn_global_load_lds((const unsigned*)((const char*)(gbase) + (voff)[_i]), (PG8_LAS unsigned*)(lds + (bufoff) + ldsw + _i * 8192), 16, 0, 0); } while (0)
; #define PG8_LDA(dst, b, h) do { _Pragma("unroll") for (int m = 0; m < 4; ++m) _Pragma("unroll") for (int k = 0; k < 2; ++k) dst[m][k] = *(const PG8_LAS bf16x8*)(lds + PG8_SA(b, h) + aoff + m * 2048 + k * 1024); } while (0)
; #define PG8_LDB(dst, b, h) do { _Pragma("unroll") for (int n = 0; n < 2; ++n) _Pragma("unroll") for (int k = 0; k < 2; ++k) dst[n][k] = *(const PG8_LAS bf16x8*)(lds + PG8_SB(b, h) + boff + n * 2048 + k * 1024); } while (0)
; #define PG8_MMA(ai, bj, At, Bt) do { __builtin_amdgcn_s_setprio(1); _Pragma("unroll") for (int m = 0; m < 4; ++m) _Pragma("unroll") for (int n = 0; n < 2; ++n) _Pragma("unroll") for (int k = 0; k < 2; ++k) \
;         acc[ai][bj][m][n] = __builtin_amdgcn_mfma_f32_16x16x32_bf16(Bt[n][k], At[m][k], acc[ai][bj][m][n], 0, 0, 0); __builtin_amdgcn_s_setprio(0); } while (0)
; #define PG8_WAIT_V(n) asm volatile("s_waitcnt vmcnt(" #n ")" ::: "memory")
; #define PG8_WAIT_L(n) asm volatile("s_waitcnt lgkmcnt(" #n ")" ::: "memory")
; template <class Epi, class Sched>
; __device__ __forceinline__ void gemm_phase(PG8_LAS unsigned char* lds, const Gemm g, const Sched& S, const Epi& E) {
;     ...
;             const bool last = (t == nt - 2);
;             const char* a1 = cA + (size_t)(t + 1) * kstep;
;             const char* a2 = last ? nA : cA + (size_t)(t + 2) * kstep; const char* b2 = last ? nB : cB + (size_t)(t + 2) * kstepB;
;             const char* a3 = a2 + kstep; const char* b3 = b2 + kstepB;
;             if (last && has_next) S.a_ready(nxt);
;             PG8_LDB(B0, 0, 0); PG8_SCHED; PG8_LDA(At, 0, 0); PG8_STAGE(PG8_SA(1, 1), a1 + hstep, voffA);
;             PG8_WAIT_L(8); PG8_BAR; PG8_WAIT_L(0); PG8_MMA(0, 0, At, B0); PG8_BAR; PG8_SCHED;
;             PG8_LDB(B1, 0, 1); PG8_STAGE(PG8_SB(0, 0), b2, voffB);
;             PG8_BAR; PG8_WAIT_L(0); PG8_MMA(0, 1, At, B1); PG8_BAR;
;             PG8_LDA(At, 0, 1); PG8_STAGE(PG8_SA(0, 0), a2, voffA);
;             PG8_BAR; PG8_WAIT_L(0); PG8_MMA(1, 0, At, B0); PG8_BAR; PG8_SCHED;
;             PG8_STAGE(PG8_SB(0, 1), b2 + hstepB, voffB);
;             PG8_WAIT_V(6); PG8_BAR; PG8_MMA(1, 1, At, B1); PG8_BAR;
.Lhalf_skip_y_7:
.LBB0_980:
	ds_read_b128 v[128:131], v197
	ds_read_b128 v[132:135], v197 offset:1024
	ds_read_b128 v[136:139], v197 offset:2048
	ds_read_b128 v[140:143], v197 offset:3072
	s_add_u32 s24, s22, 0x100
	s_addc_u32 s25, s23, 0
	s_cmpk_eq_i32 s65, 0x52
	s_cselect_b32 s29, s7, s25
	s_cselect_b32 s28, s6, s24
	s_cselect_b32 s27, s9, s64
	s_cselect_b32 s26, s8, s63
	v_lshl_add_u64 v[192:193], s[22:23], 0, v[172:173]
	s_add_i32 m0, s49, 0xc000
	ds_read_b128 v[144:147], v198
	ds_read_b128 v[148:151], v198 offset:1024
	ds_read_b128 v[152:155], v198 offset:2048
	ds_read_b128 v[156:159], v198 offset:3072
	ds_read_b128 v[160:163], v198 offset:4096
	ds_read_b128 v[180:183], v198 offset:5120
	ds_read_b128 v[184:187], v198 offset:6144
	ds_read_b128 v[188:191], v198 offset:7168
	global_load_lds_dwordx4 v[192:193], off
	v_lshl_add_u64 v[192:193], s[22:23], 0, v[174:175]
	s_add_i32 m0, s49, 0xe000
	s_nop 0
	global_load_lds_dwordx4 v[192:193], off
	s_add_i32 s22, s57, s48
	v_lshl_add_u64 v[192:193], s[26:27], 0, v[164:165]
	s_mov_b32 m0, s22
	ds_read_b128 v[200:203], v199
	ds_read_b128 v[204:207], v199 offset:1024
	ds_read_b128 v[208:211], v199 offset:2048
	ds_read_b128 v[212:215], v199 offset:3072
	s_waitcnt vmcnt(8)
	s_waitcnt lgkmcnt(0)
	s_barrier
	s_setprio 1
	v_mfma_f32_16x16x32_bf16 v[124:127], v[128:131], v[144:147], v[124:127]
	v_mfma_f32_16x16x32_bf16 v[120:123], v[136:139], v[144:147], v[120:123]
	v_mfma_f32_16x16x32_bf16 v[116:119], v[128:131], v[152:155], v[116:119]
	v_mfma_f32_16x16x32_bf16 v[104:107], v[136:139], v[152:155], v[104:107]
	v_mfma_f32_16x16x32_bf16 v[92:95], v[128:131], v[160:163], v[92:95]
	v_mfma_f32_16x16x32_bf16 v[88:91], v[136:139], v[160:163], v[88:91]
	v_mfma_f32_16x16x32_bf16 v[76:79], v[128:131], v[184:187], v[76:79]
	v_mfma_f32_16x16x32_bf16 v[72:75], v[136:139], v[184:187], v[72:75]
	v_mfma_f32_16x16x32_bf16 v[124:127], v[132:135], v[148:151], v[124:127]
	v_mfma_f32_16x16x32_bf16 v[120:123], v[140:143], v[148:151], v[120:123]
	v_mfma_f32_16x16x32_bf16 v[116:119], v[132:135], v[156:159], v[116:119]
	v_mfma_f32_16x16x32_bf16 v[104:107], v[140:143], v[156:159], v[104:107]
	v_mfma_f32_16x16x32_bf16 v[92:95], v[132:135], v[180:183], v[92:95]
	v_mfma_f32_16x16x32_bf16 v[88:91], v[140:143], v[180:183], v[88:91]
	v_mfma_f32_16x16x32_bf16 v[76:79], v[132:135], v[188:191], v[76:79]
	v_mfma_f32_16x16x32_bf16 v[72:75], v[140:143], v[188:191], v[72:75]
	v_mfma_f32_16x16x32_bf16 v[112:115], v[200:203], v[144:147], v[112:115]
	v_mfma_f32_16x16x32_bf16 v[108:111], v[208:211], v[144:147], v[108:111]
	v_mfma_f32_16x16x32_bf16 v[100:103], v[200:203], v[152:155], v[100:103]
	v_mfma_f32_16x16x32_bf16 v[96:99], v[208:211], v[152:155], v[96:99]
	v_mfma_f32_16x16x32_bf16 v[84:87], v[200:203], v[160:163], v[84:87]
	v_mfma_f32_16x16x32_bf16 v[80:83], v[208:211], v[160:163], v[80:83]
	v_mfma_f32_16x16x32_bf16 v[68:71], v[200:203], v[184:187], v[68:71]
	v_mfma_f32_16x16x32_bf16 v[64:67], v[208:211], v[184:187], v[64:67]
	v_mfma_f32_16x16x32_bf16 v[112:115], v[204:207], v[148:151], v[112:115]
	v_mfma_f32_16x16x32_bf16 v[108:111], v[212:215], v[148:151], v[108:111]
	v_mfma_f32_16x16x32_bf16 v[100:103], v[204:207], v[156:159], v[100:103]
	v_mfma_f32_16x16x32_bf16 v[96:99], v[212:215], v[156:159], v[96:99]
	v_mfma_f32_16x16x32_bf16 v[84:87], v[204:207], v[180:183], v[84:87]
	v_mfma_f32_16x16x32_bf16 v[80:83], v[212:215], v[180:183], v[80:83]
	v_mfma_f32_16x16x32_bf16 v[68:71], v[204:207], v[188:191], v[68:71]
	v_mfma_f32_16x16x32_bf16 v[64:67], v[212:215], v[188:191], v[64:67]
	s_setprio 0
	s_barrier
	global_load_lds_dwordx4 v[192:193], off
	v_lshl_add_u64 v[192:193], s[26:27], 0, v[168:169]
	s_add_i32 m0, s22, 0x2000
	s_nop 0
	global_load_lds_dwordx4 v[192:193], off
	s_mov_b32 m0, s49
	v_lshl_add_u64 v[192:193], s[28:29], 0, v[166:167]
	ds_read_b128 v[144:147], v198 offset:16384
	ds_read_b128 v[148:151], v198 offset:17408
	ds_read_b128 v[152:155], v198 offset:18432
	ds_read_b128 v[156:159], v198 offset:19456
	ds_read_b128 v[160:163], v198 offset:20480
	ds_read_b128 v[180:183], v198 offset:21504
	ds_read_b128 v[184:187], v198 offset:22528
	ds_read_b128 v[188:191], v198 offset:23552
	global_load_lds_dwordx4 v[192:193], off
	v_lshl_add_u64 v[216:217], s[28:29], 0, v[170:171]
	s_mov_b32 m0, s50
	s_nop 0
	global_load_lds_dwordx4 v[216:217], off
	s_add_u32 s22, s26, 0x4000
	s_addc_u32 s23, s27, 0
	s_add_i32 s66, s58, s48
	v_lshl_add_u64 v[250:251], s[22:23], 0, v[164:165]
	s_mov_b32 m0, s66
	s_nop 0
	global_load_lds_dwordx4 v[250:251], off
	v_lshl_add_u64 v[250:251], s[22:23], 0, v[168:169]
	s_add_i32 m0, s66, 0x2000
	s_nop 0
	global_load_lds_dwordx4 v[250:251], off
	s_waitcnt vmcnt(8)
	s_waitcnt lgkmcnt(0)
	s_barrier
; #define PG8_STAGE(bufoff, gbase, voff) do { _Pragma("unroll") for (int _i = 0; _i < 2; ++_i) \
;         __builtin_amdgcn_global_load_lds((const unsigned*)((const char*)(gbase) + (voff)[_i]), (PG8_LAS unsigned*)(lds + (bufoff) + ldsw + _i * 8192), 16, 0, 0); } while (0)
; #define PG8_LDA(dst, b, h) do { _Pragma("unroll") for (int m = 0; m < 4; ++m) _Pragma("unroll") for (int k = 0; k < 2; ++k) dst[m][k] = *(const PG8_LAS bf16x8*)(lds + PG8_SA(b, h) + aoff + m * 2048 + k * 1024); } while (0)
; #define PG8_LDB(dst, b, h) do { _Pragma("unroll") for (int n = 0; n < 2; ++n) _Pragma("unroll") for (int k = 0; k < 2; ++k) dst[n][k] = *(const PG8_LAS bf16x8*)(lds + PG8_SB(b, h) + boff + n * 2048 + k * 1024); } while (0)
; #define PG8_MMA(ai, bj, At, Bt) do { __builtin_amdgcn_s_setprio(1); _Pragma("unroll") for (int m = 0; m < 4; ++m) _Pragma("unroll") for (int n = 0; n < 2; ++n) _Pragma("unroll") for (int k = 0; k < 2; ++k) \
;         acc[ai][bj][m][n] = __builtin_amdgcn_mfma_f32_16x16x32_bf16(Bt[n][k], At[m][k], acc[ai][bj][m][n], 0, 0, 0); __builtin_amdgcn_s_setprio(0); } while (0)
; #define PG8_WAIT_V(n) asm volatile("s_waitcnt vmcnt(" #n ")" ::: "memory")
; #define PG8_WAIT_L(n) asm volatile("s_waitcnt lgkmcnt(" #n ")" ::: "memory")
; #define PG8_BAR __builtin_amdgcn_s_barrier()
; #define PG8_SCHED __builtin_amdgcn_sched_barrier(0)
; template <class Epi, class Sched>
; __device__ __forceinline__ void gemm_phase(PG8_LAS unsigned char* lds, const Gemm g, const Sched& S, const Epi& E) {
;     ...
;             PG8_BAR; PG8_WAIT_L(0); PG8_MMA(1, 0, At, B0); PG8_BAR; PG8_SCHED;
;             PG8_STAGE(PG8_SB(0, 1), b2 + hstepB, voffB);
;             PG8_WAIT_V(6); PG8_BAR; PG8_MMA(1, 1, At, B1); PG8_BAR;
;             PG8_LDB(B0, 1, 0); PG8_SCHED; PG8_LDA(At, 1, 0); PG8_STAGE(PG8_SA(0, 1), a2 + hstep, voffA);
;             PG8_WAIT_L(8); PG8_BAR; PG8_WAIT_L(0); PG8_MMA(0, 0, At, B0); PG8_BAR; PG8_SCHED;
;             PG8_LDB(B1, 1, 1); PG8_STAGE(PG8_SB(1, 0), b3, voffB);
;             PG8_BAR; PG8_WAIT_L(0); PG8_MMA(0, 1, At, B1); PG8_BAR;
	s_setprio 1
	v_mfma_f32_16x16x32_bf16 v[60:63], v[128:131], v[144:147], v[60:63]
	v_mfma_f32_16x16x32_bf16 v[56:59], v[136:139], v[144:147], v[56:59]
	v_mfma_f32_16x16x32_bf16 v[44:47], v[128:131], v[152:155], v[44:47]
	v_mfma_f32_16x16x32_bf16 v[40:43], v[136:139], v[152:155], v[40:43]
	v_mfma_f32_16x16x32_bf16 v[28:31], v[128:131], v[160:163], v[28:31]
	v_mfma_f32_16x16x32_bf16 v[24:27], v[136:139], v[160:163], v[24:27]
	v_mfma_f32_16x16x32_bf16 v[12:15], v[128:131], v[184:187], v[12:15]
	v_mfma_f32_16x16x32_bf16 v[8:11], v[136:139], v[184:187], v[8:11]
	v_mfma_f32_16x16x32_bf16 v[60:63], v[132:135], v[148:151], v[60:63]
	v_mfma_f32_16x16x32_bf16 v[56:59], v[140:143], v[148:151], v[56:59]
	v_mfma_f32_16x16x32_bf16 v[44:47], v[132:135], v[156:159], v[44:47]
	v_mfma_f32_16x16x32_bf16 v[40:43], v[140:143], v[156:159], v[40:43]
	v_mfma_f32_16x16x32_bf16 v[28:31], v[132:135], v[180:183], v[28:31]
	v_mfma_f32_16x16x32_bf16 v[24:27], v[140:143], v[180:183], v[24:27]
	v_mfma_f32_16x16x32_bf16 v[12:15], v[132:135], v[188:191], v[12:15]
	v_mfma_f32_16x16x32_bf16 v[8:11], v[140:143], v[188:191], v[8:11]
	v_mfma_f32_16x16x32_bf16 v[52:55], v[200:203], v[144:147], v[52:55]
	v_mfma_f32_16x16x32_bf16 v[48:51], v[208:211], v[144:147], v[48:51]
	v_mfma_f32_16x16x32_bf16 v[36:39], v[200:203], v[152:155], v[36:39]
	v_mfma_f32_16x16x32_bf16 v[32:35], v[208:211], v[152:155], v[32:35]
	v_mfma_f32_16x16x32_bf16 v[20:23], v[200:203], v[160:163], v[20:23]
	v_mfma_f32_16x16x32_bf16 v[16:19], v[208:211], v[160:163], v[16:19]
	v_mfma_f32_16x16x32_bf16 v[4:7], v[200:203], v[184:187], v[4:7]
	v_mfma_f32_16x16x32_bf16 v[0:3], v[208:211], v[184:187], v[0:3]
	v_mfma_f32_16x16x32_bf16 v[52:55], v[204:207], v[148:151], v[52:55]
	v_mfma_f32_16x16x32_bf16 v[48:51], v[212:215], v[148:151], v[48:51]
	v_mfma_f32_16x16x32_bf16 v[36:39], v[204:207], v[156:159], v[36:39]
	v_mfma_f32_16x16x32_bf16 v[32:35], v[212:215], v[156:159], v[32:35]
	v_mfma_f32_16x16x32_bf16 v[20:23], v[204:207], v[180:183], v[20:23]
	v_mfma_f32_16x16x32_bf16 v[16:19], v[212:215], v[180:183], v[16:19]
	v_mfma_f32_16x16x32_bf16 v[4:7], v[204:207], v[188:191], v[4:7]
	v_mfma_f32_16x16x32_bf16 v[0:3], v[212:215], v[188:191], v[0:3]
	s_setprio 0
	s_barrier
	s_add_i32 s66, 0, 0x18000
	v_add_u32_e32 v140, s66, v195
	ds_read_b128 v[128:131], v140
	ds_read_b128 v[132:135], v140 offset:1024
	ds_read_b128 v[136:139], v140 offset:2048
	ds_read_b128 v[140:143], v140 offset:3072
	s_add_u32 s22, s28, 0x158000
	s_addc_u32 s23, s29, 0
	s_mov_b32 m0, s51
	v_lshl_add_u64 v[200:201], s[22:23], 0, v[166:167]
	ds_read_b128 v[144:147], v198 offset:32768
	ds_read_b128 v[148:151], v198 offset:33792
	ds_read_b128 v[152:155], v198 offset:34816
	ds_read_b128 v[156:159], v198 offset:35840
	ds_read_b128 v[160:163], v198 offset:36864
	ds_read_b128 v[180:183], v198 offset:37888
	ds_read_b128 v[184:187], v198 offset:38912
	ds_read_b128 v[188:191], v198 offset:39936
	global_load_lds_dwordx4 v[200:201], off
	v_lshl_add_u64 v[200:201], s[22:23], 0, v[170:171]
	s_mov_b32 m0, s52
	s_nop 0
	global_load_lds_dwordx4 v[200:201], off
	s_add_i32 s28, 0, 0x1c000
	s_add_u32 s22, s26, 0x8000
	s_addc_u32 s23, s27, 0
	s_add_i32 s29, s66, s48
	v_add_u32_e32 v212, s28, v195
	v_lshl_add_u64 v[218:219], s[22:23], 0, v[164:165]
	s_mov_b32 m0, s29
	ds_read_b128 v[200:203], v212
	ds_read_b128 v[204:207], v212 offset:1024
	ds_read_b128 v[208:211], v212 offset:2048
	ds_read_b128 v[212:215], v212 offset:3072
	s_waitcnt vmcnt(8)
	s_waitcnt lgkmcnt(0)
	s_barrier
	s_setprio 1
	v_mfma_f32_16x16x32_bf16 v[124:127], v[128:131], v[144:147], v[124:127]
	v_mfma_f32_16x16x32_bf16 v[120:123], v[136:139], v[144:147], v[120:123]
	v_mfma_f32_16x16x32_bf16 v[116:119], v[128:131], v[152:155], v[116:119]
	v_mfma_f32_16x16x32_bf16 v[104:107], v[136:139], v[152:155], v[104:107]
	v_mfma_f32_16x16x32_bf16 v[92:95], v[128:131], v[160:163], v[92:95]
	v_mfma_f32_16x16x32_bf16 v[88:91], v[136:139], v[160:163], v[88:91]
	v_mfma_f32_16x16x32_bf16 v[76:79], v[128:131], v[184:187], v[76:79]
	v_mfma_f32_16x16x32_bf16 v[72:75], v[136:139], v[184:187], v[72:75]
	v_mfma_f32_16x16x32_bf16 v[124:127], v[132:135], v[148:151], v[124:127]
	v_mfma_f32_16x16x32_bf16 v[120:123], v[140:143], v[148:151], v[120:123]
	v_mfma_f32_16x16x32_bf16 v[116:119], v[132:135], v[156:159], v[116:119]
	v_mfma_f32_16x16x32_bf16 v[104:107], v[140:143], v[156:159], v[104:107]
	v_mfma_f32_16x16x32_bf16 v[92:95], v[132:135], v[180:183], v[92:95]
	v_mfma_f32_16x16x32_bf16 v[88:91], v[140:143], v[180:183], v[88:91]
	v_mfma_f32_16x16x32_bf16 v[76:79], v[132:135], v[188:191], v[76:79]
	v_mfma_f32_16x16x32_bf16 v[72:75], v[140:143], v[188:191], v[72:75]
	v_mfma_f32_16x16x32_bf16 v[112:115], v[200:203], v[144:147], v[112:115]
	v_mfma_f32_16x16x32_bf16 v[108:111], v[208:211], v[144:147], v[108:111]
	v_mfma_f32_16x16x32_bf16 v[100:103], v[200:203], v[152:155], v[100:103]
	v_mfma_f32_16x16x32_bf16 v[96:99], v[208:211], v[152:155], v[96:99]
	v_mfma_f32_16x16x32_bf16 v[84:87], v[200:203], v[160:163], v[84:87]
	v_mfma_f32_16x16x32_bf16 v[80:83], v[208:211], v[160:163], v[80:83]
	v_mfma_f32_16x16x32_bf16 v[68:71], v[200:203], v[184:187], v[68:71]
	v_mfma_f32_16x16x32_bf16 v[64:67], v[208:211], v[184:187], v[64:67]
	v_mfma_f32_16x16x32_bf16 v[112:115], v[204:207], v[148:151], v[112:115]
	v_mfma_f32_16x16x32_bf16 v[108:111], v[212:215], v[148:151], v[108:111]
	v_mfma_f32_16x16x32_bf16 v[100:103], v[204:207], v[156:159], v[100:103]
	v_mfma_f32_16x16x32_bf16 v[96:99], v[212:215], v[156:159], v[96:99]
	v_mfma_f32_16x16x32_bf16 v[84:87], v[204:207], v[180:183], v[84:87]
	v_mfma_f32_16x16x32_bf16 v[80:83], v[212:215], v[180:183], v[80:83]
	v_mfma_f32_16x16x32_bf16 v[68:71], v[204:207], v[188:191], v[68:71]
	v_mfma_f32_16x16x32_bf16 v[64:67], v[212:215], v[188:191], v[64:67]
	s_setprio 0
	s_barrier
; #define PG8_STAGE(bufoff, gbase, voff) do { _Pragma("unroll") for (int _i = 0; _i < 2; ++_i) \
;         __builtin_amdgcn_global_load_lds((const unsigned*)((const char*)(gbase) + (voff)[_i]), (PG8_LAS unsigned*)(lds + (bufoff) + ldsw + _i * 8192), 16, 0, 0); } while (0)
; #define PG8_LDA(dst, b, h) do { _Pragma("unroll") for (int m = 0; m < 4; ++m) _Pragma("unroll") for (int k = 0; k < 2; ++k) dst[m][k] = *(const PG8_LAS bf16x8*)(lds + PG8_SA(b, h) + aoff + m * 2048 + k * 1024); } while (0)
; #define PG8_LDB(dst, b, h) do { _Pragma("unroll") for (int n = 0; n < 2; ++n) _Pragma("unroll") for (int k = 0; k < 2; ++k) dst[n][k] = *(const PG8_LAS bf16x8*)(lds + PG8_SB(b, h) + boff + n * 2048 + k * 1024); } while (0)
; #define PG8_MMA(ai, bj, At, Bt) do { __builtin_amdgcn_s_setprio(1); _Pragma("unroll") for (int m = 0; m < 4; ++m) _Pragma("unroll") for (int n = 0; n < 2; ++n) _Pragma("unroll") for (int k = 0; k < 2; ++k) \
;         acc[ai][bj][m][n] = __builtin_amdgcn_mfma_f32_16x16x32_bf16(Bt[n][k], At[m][k], acc[ai][bj][m][n], 0, 0, 0); __builtin_amdgcn_s_setprio(0); } while (0)
; #define PG8_WAIT_V(n) asm volatile("s_waitcnt vmcnt(" #n ")" ::: "memory")
; #define PG8_WAIT_L(n) asm volatile("s_waitcnt lgkmcnt(" #n ")" ::: "memory")
; #define PG8_BAR __builtin_amdgcn_s_barrier()
; #define PG8_SCHED __builtin_amdgcn_sched_barrier(0)
; template <class Epi, class Sched>
; __device__ __forceinline__ void gemm_phase(PG8_LAS unsigned char* lds, const Gemm g, const Sched& S, const Epi& E) {
;     ...
;             PG8_LDB(B1, 1, 1); PG8_STAGE(PG8_SB(1, 0), b3, voffB);
;             PG8_BAR; PG8_WAIT_L(0); PG8_MMA(0, 1, At, B1); PG8_BAR;
;             PG8_LDA(At, 1, 1); PG8_STAGE(PG8_SA(1, 0), a3, voffA);
;             PG8_BAR; PG8_WAIT_L(0); PG8_MMA(1, 0, At, B0); PG8_BAR; PG8_SCHED;
;             PG8_STAGE(PG8_SB(1, 1), b3 + hstepB, voffB);
;             PG8_WAIT_V(6); PG8_BAR; PG8_MMA(1, 1, At, B1); PG8_BAR;
;         }
	global_load_lds_dwordx4 v[218:219], off
	v_lshl_add_u64 v[218:219], s[22:23], 0, v[168:169]
	s_add_i32 m0, s29, 0x2000
	s_nop 0
	global_load_lds_dwordx4 v[218:219], off
	s_mov_b32 m0, s54
	v_lshl_add_u64 v[192:193], v[192:193], 0, s[12:13]
	ds_read_b128 v[144:147], v198 offset:49152
	ds_read_b128 v[148:151], v198 offset:50176
	ds_read_b128 v[152:155], v198 offset:51200
	ds_read_b128 v[156:159], v198 offset:52224
	ds_read_b128 v[160:163], v198 offset:53248
	ds_read_b128 v[180:183], v198 offset:54272
	ds_read_b128 v[184:187], v198 offset:55296
	ds_read_b128 v[188:191], v198 offset:56320
	global_load_lds_dwordx4 v[192:193], off
	v_lshl_add_u64 v[192:193], v[216:217], 0, s[12:13]
	s_mov_b32 m0, s55
	s_nop 0
	global_load_lds_dwordx4 v[192:193], off
	s_add_u32 s22, s26, 0xc000
	s_addc_u32 s23, s27, 0
	s_add_i32 s26, s28, s48
	v_lshl_add_u64 v[252:253], s[22:23], 0, v[164:165]
	s_mov_b32 m0, s26
	s_nop 0
	global_load_lds_dwordx4 v[252:253], off
	v_lshl_add_u64 v[252:253], s[22:23], 0, v[168:169]
	s_add_i32 m0, s26, 0x2000
	s_nop 0
	global_load_lds_dwordx4 v[252:253], off
	s_waitcnt vmcnt(8)
	s_waitcnt lgkmcnt(0)
	s_barrier
	s_setprio 1
	v_mfma_f32_16x16x32_bf16 v[60:63], v[128:131], v[144:147], v[60:63]
	v_mfma_f32_16x16x32_bf16 v[56:59], v[136:139], v[144:147], v[56:59]
	v_mfma_f32_16x16x32_bf16 v[44:47], v[128:131], v[152:155], v[44:47]
	v_mfma_f32_16x16x32_bf16 v[40:43], v[136:139], v[152:155], v[40:43]
	v_mfma_f32_16x16x32_bf16 v[28:31], v[128:131], v[160:163], v[28:31]
	v_mfma_f32_16x16x32_bf16 v[24:27], v[136:139], v[160:163], v[24:27]
	v_mfma_f32_16x16x32_bf16 v[12:15], v[128:131], v[184:187], v[12:15]
	v_mfma_f32_16x16x32_bf16 v[8:11], v[136:139], v[184:187], v[8:11]
	v_mfma_f32_16x16x32_bf16 v[60:63], v[132:135], v[148:151], v[60:63]
	v_mfma_f32_16x16x32_bf16 v[56:59], v[140:143], v[148:151], v[56:59]
	v_mfma_f32_16x16x32_bf16 v[44:47], v[132:135], v[156:159], v[44:47]
	v_mfma_f32_16x16x32_bf16 v[40:43], v[140:143], v[156:159], v[40:43]
	v_mfma_f32_16x16x32_bf16 v[28:31], v[132:135], v[180:183], v[28:31]
	v_mfma_f32_16x16x32_bf16 v[24:27], v[140:143], v[180:183], v[24:27]
	v_mfma_f32_16x16x32_bf16 v[12:15], v[132:135], v[188:191], v[12:15]
	v_mfma_f32_16x16x32_bf16 v[8:11], v[140:143], v[188:191], v[8:11]
	v_mfma_f32_16x16x32_bf16 v[52:55], v[200:203], v[144:147], v[52:55]
	v_mfma_f32_16x16x32_bf16 v[48:51], v[208:211], v[144:147], v[48:51]
	v_mfma_f32_16x16x32_bf16 v[36:39], v[200:203], v[152:155], v[36:39]
	v_mfma_f32_16x16x32_bf16 v[32:35], v[208:211], v[152:155], v[32:35]
	v_mfma_f32_16x16x32_bf16 v[20:23], v[200:203], v[160:163], v[20:23]
	v_mfma_f32_16x16x32_bf16 v[16:19], v[208:211], v[160:163], v[16:19]
	v_mfma_f32_16x16x32_bf16 v[4:7], v[200:203], v[184:187], v[4:7]
	v_mfma_f32_16x16x32_bf16 v[0:3], v[208:211], v[184:187], v[0:3]
	v_mfma_f32_16x16x32_bf16 v[52:55], v[204:207], v[148:151], v[52:55]
	v_mfma_f32_16x16x32_bf16 v[48:51], v[212:215], v[148:151], v[48:51]
	v_mfma_f32_16x16x32_bf16 v[36:39], v[204:207], v[156:159], v[36:39]
	v_mfma_f32_16x16x32_bf16 v[32:35], v[212:215], v[156:159], v[32:35]
	v_mfma_f32_16x16x32_bf16 v[20:23], v[204:207], v[180:183], v[20:23]
	v_mfma_f32_16x16x32_bf16 v[16:19], v[212:215], v[180:183], v[16:19]
	v_mfma_f32_16x16x32_bf16 v[4:7], v[204:207], v[188:191], v[4:7]
	v_mfma_f32_16x16x32_bf16 v[0:3], v[212:215], v[188:191], v[0:3]
	s_setprio 0
	s_add_i32 s65, s65, 2
	s_add_u32 s63, s63, 0x10000
	s_addc_u32 s64, s64, 0
	s_cmpk_gt_u32 s65, 0x53
	s_mov_b64 s[22:23], s[24:25]
	s_barrier
	s_cbranch_scc0 .LBB0_980
	s_cmp_eq_u32 s78, 0
	s_cbranch_scc0 .Lhalf_skip_x_7
	s_barrier

; __global__ void __launch_bounds__(512, 2) mega_fwd(Params p, int ph_lo, int ph_hi) {
	.amdhsa_kernel _Z8mega_fwd6Paramsii
		.amdhsa_group_segment_fixed_size 0
		.amdhsa_private_segment_fixed_size 0
		.amdhsa_kernarg_size 440
		.amdhsa_user_sgpr_count 2
		.amdhsa_user_sgpr_dispatch_ptr 0
		.amdhsa_user_sgpr_queue_ptr 0
		.amdhsa_user_sgpr_kernarg_segment_ptr 1
		.amdhsa_user_sgpr_dispatch_id 0
		.amdhsa_user_sgpr_kernarg_preload_length 0
		.amdhsa_user_sgpr_kernarg_preload_offset 0
		.amdhsa_user_sgpr_private_segment_size 0
		.amdhsa_uses_dynamic_stack 0
		.amdhsa_enable_private_segment 0
		.amdhsa_system_sgpr_workgroup_id_x 1
		.amdhsa_system_sgpr_workgroup_id_y 0
		.amdhsa_system_sgpr_workgroup_id_z 0
		.amdhsa_system_sgpr_workgroup_info 0
		.amdhsa_system_vgpr_workitem_id 2
		.amdhsa_next_free_vgpr 256
		.amdhsa_next_free_sgpr 79
		.amdhsa_accum_offset 256
		.amdhsa_reserve_vcc 1
		.amdhsa_float_round_mode_32 0
		.amdhsa_float_round_mode_16_64 0
		.amdhsa_float_denorm_mode_32 3
		.amdhsa_float_denorm_mode_16_64 3
		.amdhsa_dx10_clamp 1
		.amdhsa_ieee_mode 1
		.amdhsa_fp16_overflow 0
		.amdhsa_tg_split 0
		.amdhsa_exception_fp_ieee_invalid_op 0
		.amdhsa_exception_fp_denorm_src 0
		.amdhsa_exception_fp_ieee_div_zero 0
		.amdhsa_exception_fp_ieee_overflow 0
		.amdhsa_exception_fp_ieee_underflow 0
		.amdhsa_exception_fp_ieee_inexact 0
		.amdhsa_exception_int_div_zero 0
	.end_amdhsa_kernel

; __global__ void __launch_bounds__(512, 2) mega_fwd(Params p, int ph_lo, int ph_hi) {
amdhsa.kernels:
  - .agpr_count:     0
    .args:
      - .offset:         0
        .size:           176
        .value_kind:     by_value
      - .offset:         176
        .size:           4
        .value_kind:     by_value
      - .offset:         180
        .size:           4
        .value_kind:     by_value
      - .offset:         184
        .size:           4
        .value_kind:     hidden_block_count_x
      - .offset:         188
        .size:           4
        .value_kind:     hidden_block_count_y
      - .offset:         192
        .size:           4
        .value_kind:     hidden_block_count_z
      - .offset:         196
        .size:           2
        .value_kind:     hidden_group_size_x
      - .offset:         198
        .size:           2
        .value_kind:     hidden_group_size_y
      - .offset:         200
        .size:           2
        .value_kind:     hidden_group_size_z
      - .offset:         202
        .size:           2
        .value_kind:     hidden_remainder_x
      - .offset:         204
        .size:           2
        .value_kind:     hidden_remainder_y
      - .offset:         206
        .size:           2
        .value_kind:     hidden_remainder_z
      - .offset:         224
        .size:           8
        .value_kind:     hidden_global_offset_x
      - .offset:         232
        .size:           8
        .value_kind:     hidden_global_offset_y
      - .offset:         240
        .size:           8
        .value_kind:     hidden_global_offset_z
      - .offset:         248
        .size:           2
        .value_kind:     hidden_grid_dims
      - .offset:         272
        .size:           8
        .value_kind:     hidden_multigrid_sync_arg
      - .offset:         304
        .size:           4
        .value_kind:     hidden_dynamic_lds_size
    .group_segment_fixed_size: 0
    .kernarg_segment_align: 8
    .kernarg_segment_size: 440
    .language:       OpenCL C
    .language_version:
      - 2
      - 0
    .max_flat_workgroup_size: 512
    .name:           _Z8mega_fwd6Paramsii
    .private_segment_fixed_size: 0
    .sgpr_count:     85
    .sgpr_spill_count: 0
    .symbol:         _Z8mega_fwd6Paramsii.kd
    .uniform_work_group_size: 1
    .uses_dynamic_stack: false
    .vgpr_count:     256
    .vgpr_spill_count: 0
    .wavefront_size: 64
